# v025 + weight conversion of later layers moved into idle GEMM tail rounds (branch-in/branch-out), conversion stores nontemporal
# speedup vs baseline: 1.0044x; 1.0044x over previous
.LBB0_31:
	v_mov_b32_e32 v1, v0
	s_barrier
	s_mov_b32 s8, s87
	s_mov_b32 s14, s88
	s_mov_b32 s99, 0
	s_movk_i32 s100, 0x4a3f
	s_mov_b32 s101, 0
.Lconv0_entry:
	v_readfirstlane_b32 s0, v1
	s_nop 0
	s_ashr_i32 s19, s0, 6
	s_lshl_b32 s0, s14, 3
	s_add_i32 s15, s0, s19
	s_add_i32 s15, s15, s99
	s_add_i32 s0, s9, 0x202b8
	v_mov_b32_e32 v2, s0
	s_add_i32 s0, s9, 0x202bc
	ds_read_b32 v2, v2
	v_mov_b32_e32 v3, s0
	s_add_i32 s0, s9, 0x20230
	ds_read_b32 v3, v3
	v_mov_b32_e32 v4, s0
	s_add_i32 s0, s9, 0x20234
	ds_read_b32 v4, v4
	v_mov_b32_e32 v5, s0
	ds_read_b32 v5, v5
	s_add_i32 s0, s9, 0x20240
	s_add_i32 s5, s9, 0x20244
	v_mov_b32_e32 v6, s0
	s_waitcnt lgkmcnt(3)
	v_readfirstlane_b32 s0, v2
	v_mov_b32_e32 v2, s5
	s_add_i32 s5, s9, 0x20260
	ds_read_b32 v6, v6
	s_waitcnt lgkmcnt(3)
	v_readfirstlane_b32 s1, v3
	ds_read_b32 v2, v2
	v_mov_b32_e32 v3, s5
	s_add_i32 s5, s9, 0x20264
	s_waitcnt lgkmcnt(3)
	v_readfirstlane_b32 s2, v4
	ds_read_b32 v3, v3
	v_mov_b32_e32 v4, s5
	s_add_i32 s5, s9, 0x20268
	s_waitcnt lgkmcnt(3)
	v_readfirstlane_b32 s3, v5
	ds_read_b32 v4, v4
	v_mov_b32_e32 v5, s5
	ds_read_b32 v5, v5
	s_add_i32 s5, s9, 0x2026c
	s_add_i32 s10, s9, 0x20280
	s_waitcnt lgkmcnt(4)
	v_readfirstlane_b32 s4, v6
	v_mov_b32_e32 v6, s5
	s_waitcnt lgkmcnt(3)
	v_readfirstlane_b32 s5, v2
	v_mov_b32_e32 v2, s10
	s_add_i32 s10, s9, 0x20284
	s_waitcnt lgkmcnt(2)
	v_readfirstlane_b32 s16, v3
	v_mov_b32_e32 v3, s10
	s_add_i32 s10, s9, 0x20298
	s_waitcnt lgkmcnt(1)
	v_readfirstlane_b32 s17, v4
	v_mov_b32_e32 v4, s10
	s_add_i32 s10, s9, 0x2029c
	s_waitcnt lgkmcnt(0)
	v_readfirstlane_b32 s6, v5
	v_mov_b32_e32 v5, s10
	ds_read_b32 v6, v6
	ds_read_b32 v2, v2
	ds_read_b32 v3, v3
	ds_read_b32 v4, v4
	ds_read_b32 v5, v5
	s_waitcnt lgkmcnt(4)
	v_readfirstlane_b32 s7, v6
	s_waitcnt lgkmcnt(3)
	v_readfirstlane_b32 s10, v2
	s_waitcnt lgkmcnt(2)
	v_readfirstlane_b32 s11, v3
	s_waitcnt lgkmcnt(1)
	v_readfirstlane_b32 s12, v4
	s_cmp_gt_i32 s15, s100
	s_waitcnt lgkmcnt(0)
	v_readfirstlane_b32 s13, v5
	s_cbranch_scc1 .LBB0_54
	s_lshl_b32 s19, s19, 14
	v_bfe_u32 v28, v1, 5, 1
	v_and_b32_e32 v26, 31, v1
	s_add_i32 s9, s9, s19
	v_lshlrev_b32_e32 v2, 2, v26
	v_mul_u32_u24_e32 v6, 0x84, v28
	v_add3_u32 v29, s9, v2, v6
	v_lshlrev_b32_e32 v6, 3, v1
	v_mov_b32_e32 v3, 0
	v_bfe_u32 v30, v1, 3, 3
	v_and_b32_e32 v6, 56, v6
	s_lshl_b32 s18, s8, 3
	v_mul_u32_u24_e32 v10, 0x84, v6
	v_mov_b32_e32 v7, v3
	v_lshlrev_b32_e32 v8, 1, v6
	v_mov_b32_e32 v9, v3
	v_lshlrev_b32_e32 v11, 2, v30
	v_lshl_add_u64 v[4:5], s[12:13], 0, v[2:3]
	v_lshl_add_u64 v[12:13], s[0:1], 0, v[8:9]
	s_mov_b64 s[12:13], 0xd000000
	v_add3_u32 v31, s9, v10, v11
	v_lshl_add_u64 v[10:11], s[10:11], 0, v[2:3]
	s_mov_b64 s[10:11], 0xa400000
	v_lshl_add_u64 v[14:15], s[6:7], 0, v[2:3]
	v_lshl_add_u64 v[24:25], s[0:1], 0, v[6:7]
	s_mov_b64 s[6:7], 0x9c00000
	s_add_u32 s9, s0, 0x8400000
	v_lshl_add_u64 v[18:19], s[4:5], 0, v[2:3]
	s_mov_b64 s[4:5], 0x8000000
	v_lshl_add_u64 v[22:23], s[2:3], 0, v[2:3]
	s_mov_b64 s[2:3], 0x3500000
	v_lshl_add_u64 v[8:9], v[12:13], 0, s[12:13]
	v_or_b32_e32 v32, 8, v30
	v_or_b32_e32 v33, 16, v30
	v_or_b32_e32 v34, 24, v30
	v_lshl_add_u64 v[12:13], v[12:13], 0, s[10:11]
	v_lshl_add_u64 v[16:17], v[24:25], 0, s[6:7]
	s_addc_u32 s10, s1, 0
	v_lshl_add_u64 v[20:21], v[24:25], 0, s[4:5]
	v_lshl_add_u64 v[24:25], v[24:25], 0, s[2:3]
	s_lshl_b32 s11, s15, 5
	s_lshl_b32 s12, s8, 8
	s_lshl_b32 s13, s15, 2
	s_lshl_b32 s19, s8, 5
	s_mov_b32 s3, 0
	s_movk_i32 s20, 0x4000
	s_mov_b32 s21, 0x8000
	s_mov_b32 s22, 0xc000
	s_mov_b32 s23, 0x10000
	s_mov_b32 s24, 0x14000
	s_mov_b32 s25, 0x18000
	s_mov_b32 s26, 0x1c000
	s_mov_b32 s27, 0x20000
	s_mov_b32 s28, 0x24000
	s_mov_b32 s29, 0x28000
	s_mov_b32 s30, 0x2c000
	s_mov_b32 s31, 0x30000
	s_mov_b32 s33, 0x34000
	s_mov_b32 s34, 0x38000
	s_mov_b32 s35, 0x3c000
	s_mov_b32 s36, 0x40000
	s_mov_b32 s37, 0x44000
	s_mov_b32 s38, 0x48000
	s_mov_b32 s39, 0x4c000
	s_mov_b32 s40, 0x50000
	s_mov_b32 s41, 0x54000
	s_mov_b32 s42, 0x58000
	s_mov_b32 s43, 0x5c000
	s_mov_b32 s44, 0x60000
	s_mov_b32 s45, 0x64000
	s_mov_b32 s46, 0x68000
	s_mov_b32 s47, 0x6c000
	s_mov_b32 s48, 0x70000
	s_mov_b32 s49, 0x74000
	s_mov_b32 s50, 0x78000
	s_mov_b32 s51, 0x7c000
	s_movk_i32 s52, 0x7fff
	s_mov_b32 s53, 0xffff0000
	s_mov_b32 s54, 0x16000
	s_mov_b32 s55, 0x42000
	s_mov_b32 s56, 0x6e000
	s_mov_b32 s57, 0x84000
	s_mov_b32 s58, 0x9a000
	s_mov_b32 s59, 0xb0000
	s_mov_b32 s60, 0xc6000
	s_mov_b32 s61, 0xdc000
	s_mov_b32 s62, 0xf2000
	s_mov_b32 s63, 0x108000
	s_mov_b32 s64, 0x11e000
	s_mov_b32 s65, 0x134000
	s_mov_b32 s66, 0x14a000
	s_mov_b32 s67, 0x160000
	s_mov_b32 s68, 0x176000
	s_mov_b32 s69, 0x18c000
	s_mov_b32 s70, 0x1a2000
	s_mov_b32 s71, 0x1b8000
	s_mov_b32 s72, 0x1ce000
	s_mov_b32 s73, 0x1e4000
	s_mov_b32 s74, 0x1fa000
	s_mov_b32 s75, 0x210000
	s_mov_b32 s76, 0x226000
	s_mov_b32 s77, 0x23c000
	s_mov_b32 s78, 0x252000
	s_mov_b32 s79, 0x268000
	s_mov_b32 s80, 0x27e000
	s_mov_b32 s81, 0x294000
	s_mov_b32 s82, 0x2aa000
	v_lshlrev_b32_e32 v26, 2, v26
	s_mov_b32 s83, 0x12900
	v_add_u32_e32 v35, 0x400, v29
	v_add_u32_e32 v36, 0x800, v29
	v_add_u32_e32 v37, 0xc00, v29
	v_add_u32_e32 v38, 0x1000, v29
	v_add_u32_e32 v39, 0x1400, v29
	v_add_u32_e32 v40, 0x1800, v29
	v_add_u32_e32 v41, 0x1c00, v29
	s_branch .LBB0_34
.LBB0_33:
	s_add_i32 s15, s15, s18
	s_add_i32 s11, s11, s12
	s_add_i32 s13, s13, s19
	s_cmp_gt_i32 s15, s100
	s_cbranch_scc1 .LBB0_54
.LBB0_34:
	s_cmpk_gt_i32 s15, 0x4a3f
	s_mov_b64 s[4:5], -1
	s_cbranch_scc0 .LBB0_52
	s_cmpk_gt_u32 s15, 0x4e3f
	s_cbranch_scc0 .LBB0_49
	s_cmpk_gt_u32 s15, 0x663f
	s_cbranch_scc0 .LBB0_46
	s_cmpk_gt_u32 s15, 0x6e3f
	s_cbranch_scc0 .LBB0_43
	s_cmpk_gt_u32 s15, 0x9a3f
	s_cbranch_scc0 .LBB0_40
	s_add_i32 s2, s15, 0xffff65c0
	s_and_b32 s5, s2, 0x1fc0
	s_add_i32 s2, s11, 0xffecb800
	s_and_b32 s4, s2, 0x7e0
	v_or_b32_e32 v2, s5, v28
	s_lshl_b32 s2, s4, 2
	v_lshl_add_u64 v[42:43], v[4:5], 0, s[2:3]
	v_lshlrev_b32_e32 v2, 13, v2
	v_lshl_add_u64 v[42:43], v[42:43], 0, v[2:3]
	v_add_co_u32_e32 v44, vcc, 0x4000, v42
	s_lshl_b32 s2, s5, 1
	s_nop 0
	v_addc_co_u32_e32 v45, vcc, 0, v43, vcc
	v_add_co_u32_e32 v46, vcc, 0x8000, v42
	s_nop 1
	v_addc_co_u32_e32 v47, vcc, 0, v43, vcc
	v_add_co_u32_e32 v48, vcc, 0xc000, v42
	s_nop 1
	v_addc_co_u32_e32 v49, vcc, 0, v43, vcc
	v_add_co_u32_e32 v50, vcc, 0x10000, v42
	s_nop 1
	v_addc_co_u32_e32 v51, vcc, 0, v43, vcc
	v_add_co_u32_e32 v52, vcc, 0x14000, v42
	s_nop 1
	v_addc_co_u32_e32 v53, vcc, 0, v43, vcc
	v_add_co_u32_e32 v54, vcc, 0x18000, v42
	s_nop 1
	v_addc_co_u32_e32 v55, vcc, 0, v43, vcc
	v_add_co_u32_e32 v56, vcc, 0x1c000, v42
	s_nop 1
	v_addc_co_u32_e32 v57, vcc, 0, v43, vcc
	global_load_dword v2, v[42:43], off nt
	global_load_dword v27, v[44:45], off nt
	global_load_dword v60, v[46:47], off nt
	global_load_dword v61, v[48:49], off nt
	global_load_dword v62, v[50:51], off nt
	global_load_dword v63, v[52:53], off nt
	global_load_dword v64, v[54:55], off nt
	global_load_dword v65, v[56:57], off nt
	v_add_co_u32_e32 v44, vcc, 0x20000, v42
	s_nop 1
	v_addc_co_u32_e32 v45, vcc, 0, v43, vcc
	v_add_co_u32_e32 v46, vcc, 0x24000, v42
	s_nop 1
	v_addc_co_u32_e32 v47, vcc, 0, v43, vcc
	v_add_co_u32_e32 v48, vcc, 0x28000, v42
	s_nop 1
	v_addc_co_u32_e32 v49, vcc, 0, v43, vcc
	v_add_co_u32_e32 v50, vcc, 0x2c000, v42
	s_nop 1
	v_addc_co_u32_e32 v51, vcc, 0, v43, vcc
	v_add_co_u32_e32 v52, vcc, 0x30000, v42
	s_nop 1
	v_addc_co_u32_e32 v53, vcc, 0, v43, vcc
	v_add_co_u32_e32 v54, vcc, 0x34000, v42
	s_nop 1
	v_addc_co_u32_e32 v55, vcc, 0, v43, vcc
	v_add_co_u32_e32 v56, vcc, 0x38000, v42
	s_nop 1
	v_addc_co_u32_e32 v57, vcc, 0, v43, vcc
	v_add_co_u32_e32 v58, vcc, 0x3c000, v42
	s_nop 1
	v_addc_co_u32_e32 v59, vcc, 0, v43, vcc
	global_load_dword v66, v[44:45], off nt
	global_load_dword v67, v[46:47], off nt
	global_load_dword v68, v[48:49], off nt
	global_load_dword v69, v[50:51], off nt
	global_load_dword v70, v[52:53], off nt
	global_load_dword v71, v[54:55], off nt
	global_load_dword v72, v[56:57], off nt
	global_load_dword v73, v[58:59], off nt
	v_add_co_u32_e32 v44, vcc, 0x40000, v42
	s_nop 1
	v_addc_co_u32_e32 v45, vcc, 0, v43, vcc
	v_add_co_u32_e32 v46, vcc, 0x44000, v42
	s_nop 1
	v_addc_co_u32_e32 v47, vcc, 0, v43, vcc
	v_add_co_u32_e32 v48, vcc, 0x48000, v42
	s_nop 1
	v_addc_co_u32_e32 v49, vcc, 0, v43, vcc
	v_add_co_u32_e32 v50, vcc, 0x4c000, v42
	s_nop 1
	v_addc_co_u32_e32 v51, vcc, 0, v43, vcc
	v_add_co_u32_e32 v52, vcc, 0x50000, v42
	s_nop 1
	v_addc_co_u32_e32 v53, vcc, 0, v43, vcc
	v_add_co_u32_e32 v54, vcc, 0x54000, v42
	s_nop 1
	v_addc_co_u32_e32 v55, vcc, 0, v43, vcc
	v_add_co_u32_e32 v56, vcc, 0x58000, v42
	s_nop 1
	v_addc_co_u32_e32 v57, vcc, 0, v43, vcc
	v_add_co_u32_e32 v58, vcc, 0x5c000, v42
	s_nop 1
	v_addc_co_u32_e32 v59, vcc, 0, v43, vcc
	global_load_dword v74, v[44:45], off nt
	global_load_dword v75, v[46:47], off nt
	global_load_dword v76, v[48:49], off nt
	global_load_dword v77, v[50:51], off nt
	global_load_dword v78, v[52:53], off nt
	global_load_dword v79, v[54:55], off nt
	global_load_dword v80, v[56:57], off nt
	s_nop 0
	global_load_dword v58, v[58:59], off nt
	v_add_co_u32_e32 v44, vcc, 0x60000, v42
	s_nop 1
	v_addc_co_u32_e32 v45, vcc, 0, v43, vcc
	v_add_co_u32_e32 v46, vcc, 0x64000, v42
	s_nop 1
	v_addc_co_u32_e32 v47, vcc, 0, v43, vcc
	v_add_co_u32_e32 v48, vcc, 0x68000, v42
	s_nop 1
	v_addc_co_u32_e32 v49, vcc, 0, v43, vcc
	v_add_co_u32_e32 v50, vcc, 0x6c000, v42
	s_nop 1
	v_addc_co_u32_e32 v51, vcc, 0, v43, vcc
	v_add_co_u32_e32 v52, vcc, 0x70000, v42
	s_nop 1
	v_addc_co_u32_e32 v53, vcc, 0, v43, vcc
	v_add_co_u32_e32 v54, vcc, 0x74000, v42
	s_nop 1
	v_addc_co_u32_e32 v55, vcc, 0, v43, vcc
	v_add_co_u32_e32 v56, vcc, 0x78000, v42
	s_nop 1
	v_addc_co_u32_e32 v57, vcc, 0, v43, vcc
	v_add_co_u32_e32 v42, vcc, 0x7c000, v42
	s_nop 1
	v_addc_co_u32_e32 v43, vcc, 0, v43, vcc
	global_load_dword v44, v[44:45], off nt
	s_nop 0
	global_load_dword v45, v[46:47], off nt
	s_nop 0
	global_load_dword v46, v[48:49], off nt
	global_load_dword v47, v[50:51], off nt
	s_nop 0
	global_load_dword v48, v[52:53], off nt
	global_load_dword v49, v[54:55], off nt
	global_load_dword v50, v[56:57], off nt
	s_nop 0
	global_load_dword v42, v[42:43], off nt
	s_waitcnt vmcnt(30)
	ds_write2_b32 v29, v2, v27 offset1:66
	s_waitcnt vmcnt(28)
	ds_write2_b32 v29, v60, v61 offset0:132 offset1:198
	s_waitcnt vmcnt(26)
	ds_write2_b32 v35, v62, v63 offset0:8 offset1:74
	s_waitcnt vmcnt(24)
	ds_write2_b32 v35, v64, v65 offset0:140 offset1:206
	s_waitcnt vmcnt(22)
	ds_write2_b32 v36, v66, v67 offset0:16 offset1:82
	s_waitcnt vmcnt(20)
	ds_write2_b32 v36, v68, v69 offset0:148 offset1:214
	s_waitcnt vmcnt(18)
	ds_write2_b32 v37, v70, v71 offset0:24 offset1:90
	s_waitcnt vmcnt(16)
	ds_write2_b32 v37, v72, v73 offset0:156 offset1:222
	s_waitcnt vmcnt(14)
	ds_write2_b32 v38, v74, v75 offset0:32 offset1:98
	s_waitcnt vmcnt(12)
	ds_write2_b32 v38, v76, v77 offset0:164 offset1:230
	s_waitcnt vmcnt(10)
	ds_write2_b32 v39, v78, v79 offset0:40 offset1:106
	s_waitcnt vmcnt(8)
	ds_write2_b32 v39, v80, v58 offset0:172 offset1:238
	s_waitcnt vmcnt(6)
	ds_write2_b32 v40, v44, v45 offset0:48 offset1:114
	s_waitcnt vmcnt(4)
	ds_write2_b32 v40, v46, v47 offset0:180 offset1:246
	s_waitcnt vmcnt(2)
	ds_write2_b32 v41, v48, v49 offset0:56 offset1:122
	s_waitcnt vmcnt(0)
	ds_write2_b32 v41, v50, v42 offset0:188 offset1:254
	s_waitcnt lgkmcnt(0)
	ds_read2_b32 v[46:47], v31 offset1:8
	ds_read2_b32 v[50:51], v31 offset0:33 offset1:41
	ds_read2_b32 v[52:53], v31 offset0:66 offset1:74
	ds_read2_b32 v[54:55], v31 offset0:99 offset1:107
	ds_read2_b32 v[56:57], v31 offset0:132 offset1:140
	s_waitcnt lgkmcnt(4)
	v_bfe_u32 v2, v46, 16, 1
	v_add3_u32 v2, v46, v2, s52
	s_waitcnt lgkmcnt(3)
	v_bfe_u32 v27, v50, 16, 1
	v_lshrrev_b32_e32 v2, 16, v2
	v_add3_u32 v27, v50, v27, s52
	ds_read2_b32 v[58:59], v31 offset0:165 offset1:173
	v_and_or_b32 v42, v27, s53, v2
	s_waitcnt lgkmcnt(3)
	v_bfe_u32 v2, v52, 16, 1
	v_add3_u32 v2, v52, v2, s52
	s_waitcnt lgkmcnt(2)
	v_bfe_u32 v27, v54, 16, 1
	ds_read2_b32 v[60:61], v31 offset0:198 offset1:206
	v_lshrrev_b32_e32 v2, 16, v2
	v_add3_u32 v27, v54, v27, s52
	ds_read2_b32 v[62:63], v31 offset0:231 offset1:239
	v_and_or_b32 v43, v27, s53, v2
	s_waitcnt lgkmcnt(3)
	v_bfe_u32 v2, v56, 16, 1
	v_add3_u32 v2, v56, v2, s52
	s_waitcnt lgkmcnt(2)
	v_bfe_u32 v27, v58, 16, 1
	v_lshrrev_b32_e32 v2, 16, v2
	v_add3_u32 v27, v58, v27, s52
	v_and_or_b32 v44, v27, s53, v2
	s_waitcnt lgkmcnt(1)
	v_bfe_u32 v2, v60, 16, 1
	v_add3_u32 v2, v60, v2, s52
	s_waitcnt lgkmcnt(0)
	v_bfe_u32 v27, v62, 16, 1
	v_lshrrev_b32_e32 v2, 16, v2
	v_add3_u32 v27, v62, v27, s52
	v_and_or_b32 v45, v27, s53, v2
	v_or_b32_e32 v2, s4, v30
	v_lshl_add_u64 v[48:49], v[8:9], 0, s[2:3]
	v_mul_u32_u24_e32 v2, 0x2c00, v2
	v_lshl_add_u64 v[64:65], v[48:49], 0, v[2:3]
	v_bfe_u32 v2, v47, 16, 1
	v_add3_u32 v2, v47, v2, s52
	v_bfe_u32 v27, v51, 16, 1
	v_lshrrev_b32_e32 v2, 16, v2
	v_add3_u32 v27, v51, v27, s52
	global_store_dwordx4 v[64:65], v[42:45], off nt
	ds_read2_b32 v[46:47], v31 offset0:16 offset1:24
	s_nop 0
	v_and_or_b32 v42, v27, s53, v2
	v_bfe_u32 v2, v53, 16, 1
	v_add3_u32 v2, v53, v2, s52
	v_bfe_u32 v27, v55, 16, 1
	v_lshrrev_b32_e32 v2, 16, v2
	v_add3_u32 v27, v55, v27, s52
	v_and_or_b32 v43, v27, s53, v2
	v_bfe_u32 v2, v57, 16, 1
	v_add3_u32 v2, v57, v2, s52
	v_bfe_u32 v27, v59, 16, 1
	v_lshrrev_b32_e32 v2, 16, v2
	v_add3_u32 v27, v59, v27, s52
	v_and_or_b32 v44, v27, s53, v2
	v_bfe_u32 v2, v61, 16, 1
	v_add3_u32 v2, v61, v2, s52
	v_bfe_u32 v27, v63, 16, 1
	v_lshrrev_b32_e32 v2, 16, v2
	v_add3_u32 v27, v63, v27, s52
	v_and_or_b32 v45, v27, s53, v2
	v_or_b32_e32 v2, s4, v32
	v_mul_u32_u24_e32 v2, 0x2c00, v2
	v_lshl_add_u64 v[50:51], v[48:49], 0, v[2:3]
	global_store_dwordx4 v[50:51], v[42:45], off nt
	ds_read2_b32 v[50:51], v31 offset0:49 offset1:57
	ds_read2_b32 v[52:53], v31 offset0:82 offset1:90
	ds_read2_b32 v[54:55], v31 offset0:115 offset1:123
	s_waitcnt lgkmcnt(3)
	v_bfe_u32 v2, v46, 16, 1
	v_add3_u32 v2, v46, v2, s52
	s_waitcnt lgkmcnt(2)
	v_bfe_u32 v27, v50, 16, 1
	ds_read2_b32 v[56:57], v31 offset0:148 offset1:156
	v_lshrrev_b32_e32 v2, 16, v2
	v_add3_u32 v27, v50, v27, s52
	ds_read2_b32 v[58:59], v31 offset0:181 offset1:189
	v_and_or_b32 v42, v27, s53, v2
	s_waitcnt lgkmcnt(3)
	v_bfe_u32 v2, v52, 16, 1
	v_add3_u32 v2, v52, v2, s52
	s_waitcnt lgkmcnt(2)
	v_bfe_u32 v27, v54, 16, 1
	ds_read2_b32 v[60:61], v31 offset0:214 offset1:222
	v_lshrrev_b32_e32 v2, 16, v2
	v_add3_u32 v27, v54, v27, s52
	ds_read2_b32 v[62:63], v31 offset0:247 offset1:255
	v_and_or_b32 v43, v27, s53, v2
	s_waitcnt lgkmcnt(3)
	v_bfe_u32 v2, v56, 16, 1
	v_add3_u32 v2, v56, v2, s52
	s_waitcnt lgkmcnt(2)
	v_bfe_u32 v27, v58, 16, 1
	v_lshrrev_b32_e32 v2, 16, v2
	v_add3_u32 v27, v58, v27, s52
	v_and_or_b32 v44, v27, s53, v2
	s_waitcnt lgkmcnt(1)
	v_bfe_u32 v2, v60, 16, 1
	v_add3_u32 v2, v60, v2, s52
	s_waitcnt lgkmcnt(0)
	v_bfe_u32 v27, v62, 16, 1
	v_lshrrev_b32_e32 v2, 16, v2
	v_add3_u32 v27, v62, v27, s52
	v_and_or_b32 v45, v27, s53, v2
	v_or_b32_e32 v2, s4, v33
	v_mul_u32_u24_e32 v2, 0x2c00, v2
	v_lshl_add_u64 v[64:65], v[48:49], 0, v[2:3]
	v_bfe_u32 v2, v47, 16, 1
	v_add3_u32 v2, v47, v2, s52
	v_bfe_u32 v27, v51, 16, 1
	v_lshrrev_b32_e32 v2, 16, v2
	v_add3_u32 v27, v51, v27, s52
	global_store_dwordx4 v[64:65], v[42:45], off nt
	s_nop 1
	v_and_or_b32 v42, v27, s53, v2
	v_bfe_u32 v2, v53, 16, 1
	v_add3_u32 v2, v53, v2, s52
	v_bfe_u32 v27, v55, 16, 1
	v_lshrrev_b32_e32 v2, 16, v2
	v_add3_u32 v27, v55, v27, s52
	v_and_or_b32 v43, v27, s53, v2
	v_bfe_u32 v2, v57, 16, 1
	v_add3_u32 v2, v57, v2, s52
	v_bfe_u32 v27, v59, 16, 1
	v_lshrrev_b32_e32 v2, 16, v2
	v_add3_u32 v27, v59, v27, s52
	v_and_or_b32 v44, v27, s53, v2
	v_bfe_u32 v2, v61, 16, 1
	v_add3_u32 v2, v61, v2, s52
	v_bfe_u32 v27, v63, 16, 1
	v_lshrrev_b32_e32 v2, 16, v2
	v_add3_u32 v27, v63, v27, s52
	v_and_or_b32 v45, v27, s53, v2
	v_or_b32_e32 v2, s4, v34
	v_mul_u32_u24_e32 v2, 0x2c00, v2
	v_lshl_add_u64 v[46:47], v[48:49], 0, v[2:3]
	global_store_dwordx4 v[46:47], v[42:45], off nt
	s_waitcnt lgkmcnt(0)
	s_mov_b64 s[4:5], 0
.LBB0_40:
	s_andn2_b64 vcc, exec, s[4:5]
	s_cbranch_vccnz .LBB0_42
	s_add_i32 s2, s15, 0x91c0
	s_and_b32 s4, s2, 0xffff
	s_mul_i32 s4, s4, 0xba2f
	s_lshr_b32 s4, s4, 24
	s_mul_i32 s5, s4, 0x160
	s_sub_i32 s2, s2, s5
	s_lshl_b32 s5, s2, 5
	s_and_b32 s6, s5, 0xffe0
	s_and_b32 s2, s2, 0xffff
	s_add_i32 s5, s6, 0xffffea00
	s_cmpk_gt_u32 s2, 0xaf
	s_cselect_b32 s7, s5, s6
	s_cselect_b32 s5, 0x80, 0
	v_lshl_or_b32 v2, s4, 6, v28
	s_lshl_b32 s2, s6, 2
	v_lshl_add_u64 v[42:43], v[10:11], 0, s[2:3]
	v_mul_u32_u24_e32 v2, 0xb000, v2
	v_lshl_add_u64 v[42:43], v[42:43], 0, v[2:3]
	v_add_co_u32_e32 v44, vcc, s54, v42
	s_lshl_b32 s2, s7, 1
	s_nop 0
	v_addc_co_u32_e32 v45, vcc, 0, v43, vcc
	v_add_co_u32_e32 v46, vcc, s30, v42
	s_and_b32 s6, s7, 0x60
	s_nop 0
	v_addc_co_u32_e32 v47, vcc, 0, v43, vcc
	v_add_co_u32_e32 v48, vcc, s55, v42
	s_and_b32 s2, s2, 0xffffff00
	s_nop 0
	v_addc_co_u32_e32 v49, vcc, 0, v43, vcc
	v_add_co_u32_e32 v50, vcc, s42, v42
	s_or_b32 s5, s6, s5
	s_nop 0
	v_addc_co_u32_e32 v51, vcc, 0, v43, vcc
	v_add_co_u32_e32 v52, vcc, s56, v42
	s_or_b32 s5, s5, s2
	s_nop 0
	v_addc_co_u32_e32 v53, vcc, 0, v43, vcc
	v_add_co_u32_e32 v54, vcc, s57, v42
	s_lshl_b32 s2, s4, 7
	s_nop 0
	v_addc_co_u32_e32 v55, vcc, 0, v43, vcc
	v_add_co_u32_e32 v56, vcc, s58, v42
	s_nop 1
	v_addc_co_u32_e32 v57, vcc, 0, v43, vcc
	global_load_dword v2, v[42:43], off nt
	global_load_dword v27, v[44:45], off nt
	global_load_dword v60, v[46:47], off nt
	global_load_dword v61, v[48:49], off nt
	global_load_dword v62, v[50:51], off nt
	global_load_dword v63, v[52:53], off nt
	global_load_dword v64, v[54:55], off nt
	global_load_dword v65, v[56:57], off nt
	v_add_co_u32_e32 v44, vcc, s59, v42
	s_nop 1
	v_addc_co_u32_e32 v45, vcc, 0, v43, vcc
	v_add_co_u32_e32 v46, vcc, s60, v42
	s_nop 1
	v_addc_co_u32_e32 v47, vcc, 0, v43, vcc
	v_add_co_u32_e32 v48, vcc, s61, v42
	s_nop 1
	v_addc_co_u32_e32 v49, vcc, 0, v43, vcc
	v_add_co_u32_e32 v50, vcc, s62, v42
	s_nop 1
	v_addc_co_u32_e32 v51, vcc, 0, v43, vcc
	v_add_co_u32_e32 v52, vcc, s63, v42
	s_nop 1
	v_addc_co_u32_e32 v53, vcc, 0, v43, vcc
	v_add_co_u32_e32 v54, vcc, s64, v42
	s_nop 1
	v_addc_co_u32_e32 v55, vcc, 0, v43, vcc
	v_add_co_u32_e32 v56, vcc, s65, v42
	s_nop 1
	v_addc_co_u32_e32 v57, vcc, 0, v43, vcc
	v_add_co_u32_e32 v58, vcc, s66, v42
	s_nop 1
	v_addc_co_u32_e32 v59, vcc, 0, v43, vcc
	global_load_dword v66, v[44:45], off nt
	global_load_dword v67, v[46:47], off nt
	global_load_dword v68, v[48:49], off nt
	global_load_dword v69, v[50:51], off nt
	global_load_dword v70, v[52:53], off nt
	global_load_dword v71, v[54:55], off nt
	global_load_dword v72, v[56:57], off nt
	global_load_dword v73, v[58:59], off nt
	v_add_co_u32_e32 v44, vcc, s67, v42
	s_nop 1
	v_addc_co_u32_e32 v45, vcc, 0, v43, vcc
	v_add_co_u32_e32 v46, vcc, s68, v42
	s_nop 1
	v_addc_co_u32_e32 v47, vcc, 0, v43, vcc
	v_add_co_u32_e32 v48, vcc, s69, v42
	s_nop 1
	v_addc_co_u32_e32 v49, vcc, 0, v43, vcc
	v_add_co_u32_e32 v50, vcc, s70, v42
	s_nop 1
	v_addc_co_u32_e32 v51, vcc, 0, v43, vcc
	v_add_co_u32_e32 v52, vcc, s71, v42
	s_nop 1
	v_addc_co_u32_e32 v53, vcc, 0, v43, vcc
	v_add_co_u32_e32 v54, vcc, s72, v42
	s_nop 1
	v_addc_co_u32_e32 v55, vcc, 0, v43, vcc
	v_add_co_u32_e32 v56, vcc, s73, v42
	s_nop 1
	v_addc_co_u32_e32 v57, vcc, 0, v43, vcc
	v_add_co_u32_e32 v58, vcc, s74, v42
	s_nop 1
	v_addc_co_u32_e32 v59, vcc, 0, v43, vcc
	global_load_dword v74, v[44:45], off nt
	global_load_dword v75, v[46:47], off nt
	global_load_dword v76, v[48:49], off nt
	global_load_dword v77, v[50:51], off nt
	global_load_dword v78, v[52:53], off nt
	global_load_dword v79, v[54:55], off nt
	global_load_dword v80, v[56:57], off nt
	s_nop 0
	global_load_dword v58, v[58:59], off nt
	v_add_co_u32_e32 v44, vcc, s75, v42
	s_nop 1
	v_addc_co_u32_e32 v45, vcc, 0, v43, vcc
	v_add_co_u32_e32 v46, vcc, s76, v42
	s_nop 1
	v_addc_co_u32_e32 v47, vcc, 0, v43, vcc
	v_add_co_u32_e32 v48, vcc, s77, v42
	s_nop 1
	v_addc_co_u32_e32 v49, vcc, 0, v43, vcc
	v_add_co_u32_e32 v50, vcc, s78, v42
	s_nop 1
	v_addc_co_u32_e32 v51, vcc, 0, v43, vcc
	v_add_co_u32_e32 v52, vcc, s79, v42
	s_nop 1
	v_addc_co_u32_e32 v53, vcc, 0, v43, vcc
	v_add_co_u32_e32 v54, vcc, s80, v42
	s_nop 1
	v_addc_co_u32_e32 v55, vcc, 0, v43, vcc
	v_add_co_u32_e32 v56, vcc, s81, v42
	s_nop 1
	v_addc_co_u32_e32 v57, vcc, 0, v43, vcc
	v_add_co_u32_e32 v42, vcc, s82, v42
	s_nop 1
	v_addc_co_u32_e32 v43, vcc, 0, v43, vcc
	global_load_dword v44, v[44:45], off nt
	s_nop 0
	global_load_dword v45, v[46:47], off nt
	s_nop 0
	global_load_dword v46, v[48:49], off nt
	global_load_dword v47, v[50:51], off nt
	s_nop 0
	global_load_dword v48, v[52:53], off nt
	global_load_dword v49, v[54:55], off nt
	global_load_dword v50, v[56:57], off nt
	s_nop 0
	global_load_dword v42, v[42:43], off nt
	s_waitcnt vmcnt(30)
	ds_write2_b32 v29, v2, v27 offset1:66
	s_waitcnt vmcnt(28)
	ds_write2_b32 v29, v60, v61 offset0:132 offset1:198
	s_waitcnt vmcnt(26)
	ds_write2_b32 v35, v62, v63 offset0:8 offset1:74
	s_waitcnt vmcnt(24)
	ds_write2_b32 v35, v64, v65 offset0:140 offset1:206
	s_waitcnt vmcnt(22)
	ds_write2_b32 v36, v66, v67 offset0:16 offset1:82
	s_waitcnt vmcnt(20)
	ds_write2_b32 v36, v68, v69 offset0:148 offset1:214
	s_waitcnt vmcnt(18)
	ds_write2_b32 v37, v70, v71 offset0:24 offset1:90
	s_waitcnt vmcnt(16)
	ds_write2_b32 v37, v72, v73 offset0:156 offset1:222
	s_waitcnt vmcnt(14)
	ds_write2_b32 v38, v74, v75 offset0:32 offset1:98
	s_waitcnt vmcnt(12)
	ds_write2_b32 v38, v76, v77 offset0:164 offset1:230
	s_waitcnt vmcnt(10)
	ds_write2_b32 v39, v78, v79 offset0:40 offset1:106
	s_waitcnt vmcnt(8)
	ds_write2_b32 v39, v80, v58 offset0:172 offset1:238
	s_waitcnt vmcnt(6)
	ds_write2_b32 v40, v44, v45 offset0:48 offset1:114
	s_waitcnt vmcnt(4)
	ds_write2_b32 v40, v46, v47 offset0:180 offset1:246
	s_waitcnt vmcnt(2)
	ds_write2_b32 v41, v48, v49 offset0:56 offset1:122
	s_waitcnt vmcnt(0)
	ds_write2_b32 v41, v50, v42 offset0:188 offset1:254
	s_waitcnt lgkmcnt(0)
	ds_read2_b32 v[46:47], v31 offset1:8
	ds_read2_b32 v[50:51], v31 offset0:33 offset1:41
	ds_read2_b32 v[52:53], v31 offset0:66 offset1:74
	ds_read2_b32 v[54:55], v31 offset0:99 offset1:107
	ds_read2_b32 v[56:57], v31 offset0:132 offset1:140
	s_waitcnt lgkmcnt(4)
	v_bfe_u32 v2, v46, 16, 1
	v_add3_u32 v2, v46, v2, s52
	s_waitcnt lgkmcnt(3)
	v_bfe_u32 v27, v50, 16, 1
	v_lshrrev_b32_e32 v2, 16, v2
	v_add3_u32 v27, v50, v27, s52
	ds_read2_b32 v[58:59], v31 offset0:165 offset1:173
	v_and_or_b32 v42, v27, s53, v2
	s_waitcnt lgkmcnt(3)
	v_bfe_u32 v2, v52, 16, 1
	v_add3_u32 v2, v52, v2, s52
	s_waitcnt lgkmcnt(2)
	v_bfe_u32 v27, v54, 16, 1
	ds_read2_b32 v[60:61], v31 offset0:198 offset1:206
	v_lshrrev_b32_e32 v2, 16, v2
	v_add3_u32 v27, v54, v27, s52
	ds_read2_b32 v[62:63], v31 offset0:231 offset1:239
	v_and_or_b32 v43, v27, s53, v2
	s_waitcnt lgkmcnt(3)
	v_bfe_u32 v2, v56, 16, 1
	v_add3_u32 v2, v56, v2, s52
	s_waitcnt lgkmcnt(2)
	v_bfe_u32 v27, v58, 16, 1
	v_lshrrev_b32_e32 v2, 16, v2
	v_add3_u32 v27, v58, v27, s52
	v_and_or_b32 v44, v27, s53, v2
	s_waitcnt lgkmcnt(1)
	v_bfe_u32 v2, v60, 16, 1
	v_add3_u32 v2, v60, v2, s52
	s_waitcnt lgkmcnt(0)
	v_bfe_u32 v27, v62, 16, 1
	v_lshrrev_b32_e32 v2, 16, v2
	v_add3_u32 v27, v62, v27, s52
	v_or_b32_e32 v64, s5, v30
	v_and_or_b32 v45, v27, s53, v2
	v_ashrrev_i32_e32 v65, 31, v64
	v_bfe_u32 v2, v47, 16, 1
	v_lshl_add_u64 v[48:49], v[12:13], 0, s[2:3]
	v_lshlrev_b64 v[64:65], 12, v[64:65]
	v_add3_u32 v2, v47, v2, s52
	v_bfe_u32 v27, v51, 16, 1
	v_lshl_add_u64 v[64:65], v[48:49], 0, v[64:65]
	v_lshrrev_b32_e32 v2, 16, v2
	v_add3_u32 v27, v51, v27, s52
	global_store_dwordx4 v[64:65], v[42:45], off nt
	v_or_b32_e32 v46, s5, v32
	v_ashrrev_i32_e32 v47, 31, v46
	v_and_or_b32 v42, v27, s53, v2
	v_bfe_u32 v2, v53, 16, 1
	v_add3_u32 v2, v53, v2, s52
	v_bfe_u32 v27, v55, 16, 1
	v_lshrrev_b32_e32 v2, 16, v2
	v_add3_u32 v27, v55, v27, s52
	v_and_or_b32 v43, v27, s53, v2
	v_bfe_u32 v2, v57, 16, 1
	v_add3_u32 v2, v57, v2, s52
	v_bfe_u32 v27, v59, 16, 1
	v_lshrrev_b32_e32 v2, 16, v2
	v_add3_u32 v27, v59, v27, s52
	v_and_or_b32 v44, v27, s53, v2
	v_bfe_u32 v2, v61, 16, 1
	v_add3_u32 v2, v61, v2, s52
	v_bfe_u32 v27, v63, 16, 1
	v_lshrrev_b32_e32 v2, 16, v2
	v_add3_u32 v27, v63, v27, s52
	v_lshlrev_b64 v[46:47], 12, v[46:47]
	v_and_or_b32 v45, v27, s53, v2
	ds_read2_b32 v[50:51], v31 offset0:16 offset1:24
	v_lshl_add_u64 v[46:47], v[48:49], 0, v[46:47]
	global_store_dwordx4 v[46:47], v[42:45], off nt
	ds_read2_b32 v[46:47], v31 offset0:49 offset1:57
	ds_read2_b32 v[52:53], v31 offset0:82 offset1:90
	ds_read2_b32 v[54:55], v31 offset0:115 offset1:123
	s_waitcnt lgkmcnt(3)
	v_bfe_u32 v2, v50, 16, 1
	v_add3_u32 v2, v50, v2, s52
	s_waitcnt lgkmcnt(2)
	v_bfe_u32 v27, v46, 16, 1
	ds_read2_b32 v[56:57], v31 offset0:148 offset1:156
	v_lshrrev_b32_e32 v2, 16, v2
	v_add3_u32 v27, v46, v27, s52
	ds_read2_b32 v[58:59], v31 offset0:181 offset1:189
	v_and_or_b32 v42, v27, s53, v2
	s_waitcnt lgkmcnt(3)
	v_bfe_u32 v2, v52, 16, 1
	v_add3_u32 v2, v52, v2, s52
	s_waitcnt lgkmcnt(2)
	v_bfe_u32 v27, v54, 16, 1
	ds_read2_b32 v[60:61], v31 offset0:214 offset1:222
	v_lshrrev_b32_e32 v2, 16, v2
	v_add3_u32 v27, v54, v27, s52
	ds_read2_b32 v[62:63], v31 offset0:247 offset1:255
	v_and_or_b32 v43, v27, s53, v2
	s_waitcnt lgkmcnt(3)
	v_bfe_u32 v2, v56, 16, 1
	v_add3_u32 v2, v56, v2, s52
	s_waitcnt lgkmcnt(2)
	v_bfe_u32 v27, v58, 16, 1
	v_lshrrev_b32_e32 v2, 16, v2
	v_add3_u32 v27, v58, v27, s52
	v_and_or_b32 v44, v27, s53, v2
	s_waitcnt lgkmcnt(1)
	v_bfe_u32 v2, v60, 16, 1
	v_add3_u32 v2, v60, v2, s52
	s_waitcnt lgkmcnt(0)
	v_bfe_u32 v27, v62, 16, 1
	v_lshrrev_b32_e32 v2, 16, v2
	v_add3_u32 v27, v62, v27, s52
	v_or_b32_e32 v64, s5, v33
	v_and_or_b32 v45, v27, s53, v2
	v_ashrrev_i32_e32 v65, 31, v64
	v_bfe_u32 v2, v51, 16, 1
	v_lshlrev_b64 v[64:65], 12, v[64:65]
	v_add3_u32 v2, v51, v2, s52
	v_bfe_u32 v27, v47, 16, 1
	v_lshl_add_u64 v[64:65], v[48:49], 0, v[64:65]
	v_lshrrev_b32_e32 v2, 16, v2
	v_add3_u32 v27, v47, v27, s52
	global_store_dwordx4 v[64:65], v[42:45], off nt
	v_or_b32_e32 v46, s5, v34
	v_ashrrev_i32_e32 v47, 31, v46
	v_and_or_b32 v42, v27, s53, v2
	v_bfe_u32 v2, v53, 16, 1
	v_add3_u32 v2, v53, v2, s52
	v_bfe_u32 v27, v55, 16, 1
	v_lshrrev_b32_e32 v2, 16, v2
	v_add3_u32 v27, v55, v27, s52
	v_and_or_b32 v43, v27, s53, v2
	v_bfe_u32 v2, v57, 16, 1
	v_add3_u32 v2, v57, v2, s52
	v_bfe_u32 v27, v59, 16, 1
	v_lshrrev_b32_e32 v2, 16, v2
	v_add3_u32 v27, v59, v27, s52
	v_and_or_b32 v44, v27, s53, v2
	v_bfe_u32 v2, v61, 16, 1
	v_add3_u32 v2, v61, v2, s52
	v_bfe_u32 v27, v63, 16, 1
	v_lshrrev_b32_e32 v2, 16, v2
	v_add3_u32 v27, v63, v27, s52
	v_lshlrev_b64 v[46:47], 12, v[46:47]
	v_and_or_b32 v45, v27, s53, v2
	v_lshl_add_u64 v[46:47], v[48:49], 0, v[46:47]
	global_store_dwordx4 v[46:47], v[42:45], off nt
	s_waitcnt lgkmcnt(0)

.LBB0_43:
	s_andn2_b64 vcc, exec, s[4:5]
	s_cbranch_vccnz .LBB0_45
	s_add_i32 s2, s15, 0x99c0
	s_and_b32 s4, s2, 0xffc0
	s_lshl_b32 s2, s15, 5
	s_and_b32 s6, s2, 0x7e0
	v_or_b32_e32 v2, s4, v28
	s_lshl_b32 s2, s6, 2
	v_lshl_add_u64 v[42:43], v[14:15], 0, s[2:3]
	v_lshlrev_b32_e32 v2, 13, v2
	v_lshl_add_u64 v[42:43], v[42:43], 0, v[2:3]
	v_add_co_u32_e32 v44, vcc, 0x4000, v42
	s_mov_b32 s5, s3
	s_nop 0
	v_addc_co_u32_e32 v45, vcc, 0, v43, vcc
	v_add_co_u32_e32 v46, vcc, 0x8000, v42
	s_nop 1
	v_addc_co_u32_e32 v47, vcc, 0, v43, vcc
	v_add_co_u32_e32 v48, vcc, 0xc000, v42
	s_nop 1
	v_addc_co_u32_e32 v49, vcc, 0, v43, vcc
	v_add_co_u32_e32 v50, vcc, 0x10000, v42
	s_nop 1
	v_addc_co_u32_e32 v51, vcc, 0, v43, vcc
	v_add_co_u32_e32 v52, vcc, 0x14000, v42
	s_nop 1
	v_addc_co_u32_e32 v53, vcc, 0, v43, vcc
	v_add_co_u32_e32 v54, vcc, 0x18000, v42
	s_nop 1
	v_addc_co_u32_e32 v55, vcc, 0, v43, vcc
	v_add_co_u32_e32 v56, vcc, 0x1c000, v42
	s_nop 1
	v_addc_co_u32_e32 v57, vcc, 0, v43, vcc
	global_load_dword v2, v[42:43], off nt
	global_load_dword v27, v[44:45], off nt
	global_load_dword v60, v[46:47], off nt
	global_load_dword v61, v[48:49], off nt
	global_load_dword v62, v[50:51], off nt
	global_load_dword v63, v[52:53], off nt
	global_load_dword v64, v[54:55], off nt
	global_load_dword v65, v[56:57], off nt
	v_add_co_u32_e32 v44, vcc, 0x20000, v42
	s_waitcnt vmcnt(7)
	v_mul_f32_e32 v2, 0x43000000, v2
	v_addc_co_u32_e32 v45, vcc, 0, v43, vcc
	v_add_co_u32_e32 v46, vcc, 0x24000, v42
	s_waitcnt vmcnt(6)
	v_mul_f32_e32 v27, 0x43000000, v27
	v_addc_co_u32_e32 v47, vcc, 0, v43, vcc
	v_add_co_u32_e32 v48, vcc, 0x28000, v42
	s_nop 1
	v_addc_co_u32_e32 v49, vcc, 0, v43, vcc
	v_add_co_u32_e32 v50, vcc, 0x2c000, v42
	s_nop 1
	v_addc_co_u32_e32 v51, vcc, 0, v43, vcc
	v_add_co_u32_e32 v52, vcc, 0x30000, v42
	s_nop 1
	v_addc_co_u32_e32 v53, vcc, 0, v43, vcc
	v_add_co_u32_e32 v54, vcc, 0x34000, v42
	s_nop 1
	v_addc_co_u32_e32 v55, vcc, 0, v43, vcc
	v_add_co_u32_e32 v56, vcc, 0x38000, v42
	s_nop 1
	v_addc_co_u32_e32 v57, vcc, 0, v43, vcc
	v_add_co_u32_e32 v58, vcc, 0x3c000, v42
	s_nop 1
	v_addc_co_u32_e32 v59, vcc, 0, v43, vcc
	global_load_dword v66, v[44:45], off nt
	global_load_dword v67, v[46:47], off nt
	global_load_dword v68, v[48:49], off nt
	global_load_dword v69, v[50:51], off nt
	global_load_dword v70, v[52:53], off nt
	global_load_dword v71, v[54:55], off nt
	global_load_dword v72, v[56:57], off nt
	global_load_dword v73, v[58:59], off nt
	v_add_co_u32_e32 v44, vcc, 0x40000, v42
	s_nop 1
	v_addc_co_u32_e32 v45, vcc, 0, v43, vcc
	v_add_co_u32_e32 v46, vcc, 0x44000, v42
	s_nop 1
	v_addc_co_u32_e32 v47, vcc, 0, v43, vcc
	v_add_co_u32_e32 v48, vcc, 0x48000, v42
	s_nop 1
	v_addc_co_u32_e32 v49, vcc, 0, v43, vcc
	v_add_co_u32_e32 v50, vcc, 0x4c000, v42
	s_nop 1
	v_addc_co_u32_e32 v51, vcc, 0, v43, vcc
	v_add_co_u32_e32 v52, vcc, 0x50000, v42
	s_nop 1
	v_addc_co_u32_e32 v53, vcc, 0, v43, vcc
	v_add_co_u32_e32 v54, vcc, 0x54000, v42
	s_nop 1
	v_addc_co_u32_e32 v55, vcc, 0, v43, vcc
	v_add_co_u32_e32 v56, vcc, 0x58000, v42
	s_nop 1
	v_addc_co_u32_e32 v57, vcc, 0, v43, vcc
	v_add_co_u32_e32 v58, vcc, 0x5c000, v42
	s_nop 1
	v_addc_co_u32_e32 v59, vcc, 0, v43, vcc
	global_load_dword v74, v[44:45], off nt
	global_load_dword v75, v[46:47], off nt
	global_load_dword v76, v[48:49], off nt
	global_load_dword v77, v[50:51], off nt
	global_load_dword v78, v[52:53], off nt
	global_load_dword v79, v[54:55], off nt
	s_nop 0
	global_load_dword v56, v[56:57], off nt
	s_nop 0
	global_load_dword v57, v[58:59], off nt
	v_add_co_u32_e32 v44, vcc, 0x60000, v42
	s_nop 1
	v_addc_co_u32_e32 v45, vcc, 0, v43, vcc
	v_add_co_u32_e32 v46, vcc, 0x64000, v42
	s_nop 1
	v_addc_co_u32_e32 v47, vcc, 0, v43, vcc
	v_add_co_u32_e32 v48, vcc, 0x68000, v42
	s_nop 1
	v_addc_co_u32_e32 v49, vcc, 0, v43, vcc
	v_add_co_u32_e32 v50, vcc, 0x6c000, v42
	s_nop 1
	v_addc_co_u32_e32 v51, vcc, 0, v43, vcc
	v_add_co_u32_e32 v52, vcc, 0x70000, v42
	s_nop 1
	v_addc_co_u32_e32 v53, vcc, 0, v43, vcc
	v_add_co_u32_e32 v54, vcc, 0x74000, v42
	s_nop 1
	v_addc_co_u32_e32 v55, vcc, 0, v43, vcc
	global_load_dword v58, v[44:45], off nt
	s_nop 0
	global_load_dword v46, v[46:47], off nt
	s_nop 0
	global_load_dword v47, v[48:49], off nt
	s_nop 0
	global_load_dword v48, v[50:51], off nt
	global_load_dword v49, v[52:53], off nt
	s_nop 0
	global_load_dword v50, v[54:55], off nt
	v_add_co_u32_e32 v44, vcc, 0x78000, v42
	v_mov_b32_e32 v51, v3
	s_nop 0
	v_addc_co_u32_e32 v45, vcc, 0, v43, vcc
	v_add_co_u32_e32 v42, vcc, 0x7c000, v42
	s_nop 1
	v_addc_co_u32_e32 v43, vcc, 0, v43, vcc
	global_load_dword v44, v[44:45], off nt
	s_nop 0
	global_load_dword v42, v[42:43], off nt
	ds_write2_b32 v29, v2, v27 offset1:66
	s_waitcnt vmcnt(29)
	v_mul_f32_e32 v2, 0x43000000, v60
	s_waitcnt vmcnt(28)
	v_mul_f32_e32 v27, 0x43000000, v61
	ds_write2_b32 v29, v2, v27 offset0:132 offset1:198
	s_waitcnt vmcnt(27)
	v_mul_f32_e32 v2, 0x43000000, v62
	s_waitcnt vmcnt(26)
	v_mul_f32_e32 v27, 0x43000000, v63
	ds_write2_b32 v35, v2, v27 offset0:8 offset1:74
	s_waitcnt vmcnt(25)
	v_mul_f32_e32 v2, 0x43000000, v64
	s_waitcnt vmcnt(24)
	v_mul_f32_e32 v27, 0x43000000, v65
	ds_write2_b32 v35, v2, v27 offset0:140 offset1:206
	s_waitcnt vmcnt(23)
	v_mul_f32_e32 v2, 0x43000000, v66
	s_waitcnt vmcnt(22)
	v_mul_f32_e32 v27, 0x43000000, v67
	ds_write2_b32 v36, v2, v27 offset0:16 offset1:82
	s_waitcnt vmcnt(21)
	v_mul_f32_e32 v2, 0x43000000, v68
	s_waitcnt vmcnt(20)
	v_mul_f32_e32 v27, 0x43000000, v69
	ds_write2_b32 v36, v2, v27 offset0:148 offset1:214
	s_waitcnt vmcnt(19)
	v_mul_f32_e32 v2, 0x43000000, v70
	s_waitcnt vmcnt(18)
	v_mul_f32_e32 v27, 0x43000000, v71
	ds_write2_b32 v37, v2, v27 offset0:24 offset1:90
	s_waitcnt vmcnt(17)
	v_mul_f32_e32 v2, 0x43000000, v72
	s_waitcnt vmcnt(16)
	v_mul_f32_e32 v27, 0x43000000, v73
	ds_write2_b32 v37, v2, v27 offset0:156 offset1:222
	v_lshl_add_u64 v[60:61], v[16:17], 0, s[4:5]
	s_waitcnt vmcnt(15)
	v_mul_f32_e32 v2, 0x43000000, v74
	s_waitcnt vmcnt(14)
	v_mul_f32_e32 v27, 0x43000000, v75
	ds_write2_b32 v38, v2, v27 offset0:32 offset1:98
	s_waitcnt vmcnt(13)
	v_mul_f32_e32 v2, 0x43000000, v76
	s_waitcnt vmcnt(12)
	v_mul_f32_e32 v27, 0x43000000, v77
	ds_write2_b32 v38, v2, v27 offset0:164 offset1:230
	s_waitcnt vmcnt(11)
	v_mul_f32_e32 v2, 0x43000000, v78
	s_waitcnt vmcnt(10)
	v_mul_f32_e32 v27, 0x43000000, v79
	ds_write2_b32 v39, v2, v27 offset0:40 offset1:106
	s_waitcnt vmcnt(9)
	v_mul_f32_e32 v2, 0x43000000, v56
	s_waitcnt vmcnt(8)
	v_mul_f32_e32 v27, 0x43000000, v57
	ds_write2_b32 v39, v2, v27 offset0:172 offset1:238
	s_waitcnt vmcnt(7)
	v_mul_f32_e32 v2, 0x43000000, v58
	s_waitcnt vmcnt(6)
	v_mul_f32_e32 v27, 0x43000000, v46
	ds_write2_b32 v40, v2, v27 offset0:48 offset1:114
	s_waitcnt vmcnt(5)
	v_mul_f32_e32 v2, 0x43000000, v47
	s_waitcnt vmcnt(4)
	v_mul_f32_e32 v27, 0x43000000, v48
	ds_write2_b32 v40, v2, v27 offset0:180 offset1:246
	s_waitcnt vmcnt(3)
	v_mul_f32_e32 v2, 0x43000000, v49
	s_waitcnt vmcnt(2)
	v_mul_f32_e32 v27, 0x43000000, v50
	ds_write2_b32 v41, v2, v27 offset0:56 offset1:122
	v_mov_b32_e32 v50, v3
	s_waitcnt vmcnt(1)
	v_mul_f32_e32 v2, 0x43000000, v44
	s_waitcnt vmcnt(0)
	v_mul_f32_e32 v27, 0x43000000, v42
	ds_write2_b32 v41, v2, v27 offset0:188 offset1:254
	s_waitcnt lgkmcnt(0)
	ds_read2_b32 v[42:43], v31 offset0:33 offset1:41
	ds_read2_b32 v[44:45], v31 offset0:66 offset1:74
	ds_read2_b32 v[46:47], v31 offset1:8
	ds_read2_b32 v[48:49], v31 offset0:99 offset1:107
	ds_read2_b32 v[52:53], v31 offset0:132 offset1:140
	ds_read2_b32 v[54:55], v31 offset0:165 offset1:173
	ds_read2_b32 v[56:57], v31 offset0:198 offset1:206
	ds_read2_b32 v[58:59], v31 offset0:231 offset1:239
	v_or_b32_e32 v2, s6, v30
	s_waitcnt lgkmcnt(5)
	v_cvt_pk_fp8_f32 v50, v46, v42
	v_mov_b32_e32 v42, v3
	s_waitcnt lgkmcnt(2)
	v_cvt_pk_fp8_f32 v51, v52, v54
	v_cvt_pk_fp8_f32 v42, v47, v43
	v_cvt_pk_fp8_f32 v50, v44, v48 op_sel:[0,0,1]
	v_mov_b32_e32 v43, v3
	s_waitcnt lgkmcnt(0)
	v_cvt_pk_fp8_f32 v51, v56, v58 op_sel:[0,0,1]
	v_cvt_pk_fp8_f32 v43, v53, v55
	v_lshlrev_b32_e32 v2, 11, v2
	v_lshl_add_u64 v[46:47], v[60:61], 0, v[2:3]
	global_store_dwordx2 v[46:47], v[50:51], off nt
	v_cvt_pk_fp8_f32 v42, v45, v49 op_sel:[0,0,1]
	v_cvt_pk_fp8_f32 v43, v57, v59 op_sel:[0,0,1]
	ds_read2_b32 v[44:45], v31 offset0:49 offset1:57
	ds_read2_b32 v[46:47], v31 offset0:82 offset1:90
	ds_read2_b32 v[48:49], v31 offset0:16 offset1:24
	ds_read2_b32 v[50:51], v31 offset0:115 offset1:123
	ds_read2_b32 v[54:55], v31 offset0:148 offset1:156
	ds_read2_b32 v[56:57], v31 offset0:181 offset1:189
	v_or_b32_e32 v2, s6, v32
	v_lshlrev_b32_e32 v2, 11, v2
	v_mov_b32_e32 v52, v3
	ds_read2_b32 v[58:59], v31 offset0:214 offset1:222
	ds_read2_b32 v[62:63], v31 offset0:247 offset1:255
	v_mov_b32_e32 v53, v3
	v_lshl_add_u64 v[64:65], v[60:61], 0, v[2:3]
	s_waitcnt lgkmcnt(5)
	v_cvt_pk_fp8_f32 v52, v48, v44
	s_waitcnt lgkmcnt(2)
	v_cvt_pk_fp8_f32 v53, v54, v56
	global_store_dwordx2 v[64:65], v[42:43], off nt
	v_mov_b32_e32 v42, v3
	v_mov_b32_e32 v43, v3
	v_cvt_pk_fp8_f32 v42, v49, v45
	v_cvt_pk_fp8_f32 v43, v55, v57
	v_cvt_pk_fp8_f32 v52, v46, v50 op_sel:[0,0,1]
	s_waitcnt lgkmcnt(0)
	v_cvt_pk_fp8_f32 v53, v58, v62 op_sel:[0,0,1]
	v_or_b32_e32 v2, s6, v33
	v_lshlrev_b32_e32 v2, 11, v2
	v_cvt_pk_fp8_f32 v42, v47, v51 op_sel:[0,0,1]
	v_cvt_pk_fp8_f32 v43, v59, v63 op_sel:[0,0,1]
	v_lshl_add_u64 v[44:45], v[60:61], 0, v[2:3]
	v_or_b32_e32 v2, s6, v34
	v_lshlrev_b32_e32 v2, 11, v2
	global_store_dwordx2 v[44:45], v[52:53], off nt
	v_lshl_add_u64 v[44:45], v[60:61], 0, v[2:3]
	global_store_dwordx2 v[44:45], v[42:43], off nt
	s_waitcnt lgkmcnt(0)

.LBB0_46:
	s_andn2_b64 vcc, exec, s[4:5]
	s_cbranch_vccnz .LBB0_48
	s_add_i32 s84, s15, 0xffffb1c0
	s_lshr_b32 s2, s84, 11
	s_lshl_b64 s[4:5], s[2:3], 24
	s_add_u32 s85, s16, s4
	s_addc_u32 s86, s17, s5
	s_and_b32 s2, s84, 0xfffff800
	s_lshl_b64 s[6:7], s[2:3], 11
	s_add_u32 s5, s9, s6
	s_addc_u32 s4, s10, s7
	s_lshl_b32 s2, s15, 5
	s_and_b32 s2, s2, 0x7e0
	s_and_b32 s6, s84, 0x7c0
	s_lshl_b32 s7, s2, 2
	s_add_u32 s84, s85, s7
	v_or_b32_e32 v2, s6, v28
	s_addc_u32 s85, s86, 0
	v_mov_b32_e32 v27, v3
	v_lshl_add_u64 v[42:43], s[84:85], 0, v[26:27]
	v_lshlrev_b32_e32 v2, 13, v2
	v_lshl_add_u64 v[42:43], v[42:43], 0, v[2:3]
	v_add_co_u32_e32 v44, vcc, s20, v42
	s_add_u32 s6, s5, s6
	s_nop 0
	v_addc_co_u32_e32 v45, vcc, 0, v43, vcc
	v_add_co_u32_e32 v46, vcc, s21, v42
	s_addc_u32 s7, s4, 0
	s_nop 0
	v_addc_co_u32_e32 v47, vcc, 0, v43, vcc
	v_add_co_u32_e32 v48, vcc, s22, v42
	s_nop 1
	v_addc_co_u32_e32 v49, vcc, 0, v43, vcc
	v_add_co_u32_e32 v50, vcc, s23, v42
	s_nop 1
	v_addc_co_u32_e32 v51, vcc, 0, v43, vcc
	v_add_co_u32_e32 v52, vcc, s24, v42
	s_nop 1
	v_addc_co_u32_e32 v53, vcc, 0, v43, vcc
	v_add_co_u32_e32 v54, vcc, s25, v42
	s_nop 1
	v_addc_co_u32_e32 v55, vcc, 0, v43, vcc
	v_add_co_u32_e32 v56, vcc, s26, v42
	s_nop 1
	v_addc_co_u32_e32 v57, vcc, 0, v43, vcc
	global_load_dword v2, v[42:43], off nt
	global_load_dword v27, v[44:45], off nt
	global_load_dword v60, v[46:47], off nt
	global_load_dword v61, v[48:49], off nt
	global_load_dword v62, v[50:51], off nt
	global_load_dword v63, v[52:53], off nt
	global_load_dword v64, v[54:55], off nt
	global_load_dword v65, v[56:57], off nt
	v_add_co_u32_e32 v44, vcc, s27, v42
	s_waitcnt vmcnt(7)
	v_mul_f32_e32 v2, 0x43000000, v2
	v_addc_co_u32_e32 v45, vcc, 0, v43, vcc
	v_add_co_u32_e32 v46, vcc, s28, v42
	s_waitcnt vmcnt(6)
	v_mul_f32_e32 v27, 0x43000000, v27
	v_addc_co_u32_e32 v47, vcc, 0, v43, vcc
	v_add_co_u32_e32 v48, vcc, s29, v42
	s_nop 1
	v_addc_co_u32_e32 v49, vcc, 0, v43, vcc
	v_add_co_u32_e32 v50, vcc, s30, v42
	s_nop 1
	v_addc_co_u32_e32 v51, vcc, 0, v43, vcc
	v_add_co_u32_e32 v52, vcc, s31, v42
	s_nop 1
	v_addc_co_u32_e32 v53, vcc, 0, v43, vcc
	v_add_co_u32_e32 v54, vcc, s33, v42
	s_nop 1
	v_addc_co_u32_e32 v55, vcc, 0, v43, vcc
	v_add_co_u32_e32 v56, vcc, s34, v42
	s_nop 1
	v_addc_co_u32_e32 v57, vcc, 0, v43, vcc
	v_add_co_u32_e32 v58, vcc, s35, v42
	s_nop 1
	v_addc_co_u32_e32 v59, vcc, 0, v43, vcc
	global_load_dword v66, v[44:45], off nt
	global_load_dword v67, v[46:47], off nt
	global_load_dword v68, v[48:49], off nt
	global_load_dword v69, v[50:51], off nt
	global_load_dword v70, v[52:53], off nt
	global_load_dword v71, v[54:55], off nt
	global_load_dword v72, v[56:57], off nt
	global_load_dword v73, v[58:59], off nt
	v_add_co_u32_e32 v44, vcc, s36, v42
	s_nop 1
	v_addc_co_u32_e32 v45, vcc, 0, v43, vcc
	v_add_co_u32_e32 v46, vcc, s37, v42
	s_nop 1
	v_addc_co_u32_e32 v47, vcc, 0, v43, vcc
	v_add_co_u32_e32 v48, vcc, s38, v42
	s_nop 1
	v_addc_co_u32_e32 v49, vcc, 0, v43, vcc
	v_add_co_u32_e32 v50, vcc, s39, v42
	s_nop 1
	v_addc_co_u32_e32 v51, vcc, 0, v43, vcc
	v_add_co_u32_e32 v52, vcc, s40, v42
	s_nop 1
	v_addc_co_u32_e32 v53, vcc, 0, v43, vcc
	v_add_co_u32_e32 v54, vcc, s41, v42
	s_nop 1
	v_addc_co_u32_e32 v55, vcc, 0, v43, vcc
	v_add_co_u32_e32 v56, vcc, s42, v42
	s_nop 1
	v_addc_co_u32_e32 v57, vcc, 0, v43, vcc
	v_add_co_u32_e32 v58, vcc, s43, v42
	s_nop 1
	v_addc_co_u32_e32 v59, vcc, 0, v43, vcc
	global_load_dword v74, v[44:45], off nt
	global_load_dword v75, v[46:47], off nt
	global_load_dword v76, v[48:49], off nt
	global_load_dword v77, v[50:51], off nt
	global_load_dword v78, v[52:53], off nt
	global_load_dword v79, v[54:55], off nt
	s_nop 0
	global_load_dword v56, v[56:57], off nt
	s_nop 0
	global_load_dword v57, v[58:59], off nt
	v_add_co_u32_e32 v44, vcc, s44, v42
	s_nop 1
	v_addc_co_u32_e32 v45, vcc, 0, v43, vcc
	v_add_co_u32_e32 v46, vcc, s45, v42
	s_nop 1
	v_addc_co_u32_e32 v47, vcc, 0, v43, vcc
	v_add_co_u32_e32 v48, vcc, s46, v42
	s_nop 1
	v_addc_co_u32_e32 v49, vcc, 0, v43, vcc
	v_add_co_u32_e32 v50, vcc, s47, v42
	s_nop 1
	v_addc_co_u32_e32 v51, vcc, 0, v43, vcc
	v_add_co_u32_e32 v52, vcc, s48, v42
	s_nop 1
	v_addc_co_u32_e32 v53, vcc, 0, v43, vcc
	v_add_co_u32_e32 v54, vcc, s49, v42
	s_nop 1
	v_addc_co_u32_e32 v55, vcc, 0, v43, vcc
	global_load_dword v58, v[44:45], off nt
	s_nop 0
	global_load_dword v46, v[46:47], off nt
	s_nop 0
	global_load_dword v47, v[48:49], off nt
	s_nop 0
	global_load_dword v48, v[50:51], off nt
	global_load_dword v49, v[52:53], off nt
	s_nop 0
	global_load_dword v50, v[54:55], off nt
	v_add_co_u32_e32 v44, vcc, s50, v42
	v_mov_b32_e32 v51, v3
	s_nop 0
	v_addc_co_u32_e32 v45, vcc, 0, v43, vcc
	v_add_co_u32_e32 v42, vcc, s51, v42
	s_nop 1
	v_addc_co_u32_e32 v43, vcc, 0, v43, vcc
	global_load_dword v44, v[44:45], off nt
	s_nop 0
	global_load_dword v42, v[42:43], off nt
	ds_write2_b32 v29, v2, v27 offset1:66
	s_waitcnt vmcnt(29)
	v_mul_f32_e32 v2, 0x43000000, v60
	s_waitcnt vmcnt(28)
	v_mul_f32_e32 v27, 0x43000000, v61
	ds_write2_b32 v29, v2, v27 offset0:132 offset1:198
	s_waitcnt vmcnt(27)
	v_mul_f32_e32 v2, 0x43000000, v62
	s_waitcnt vmcnt(26)
	v_mul_f32_e32 v27, 0x43000000, v63
	ds_write2_b32 v35, v2, v27 offset0:8 offset1:74
	s_waitcnt vmcnt(25)
	v_mul_f32_e32 v2, 0x43000000, v64
	s_waitcnt vmcnt(24)
	v_mul_f32_e32 v27, 0x43000000, v65
	ds_write2_b32 v35, v2, v27 offset0:140 offset1:206
	s_waitcnt vmcnt(23)
	v_mul_f32_e32 v2, 0x43000000, v66
	s_waitcnt vmcnt(22)
	v_mul_f32_e32 v27, 0x43000000, v67
	ds_write2_b32 v36, v2, v27 offset0:16 offset1:82
	s_waitcnt vmcnt(21)
	v_mul_f32_e32 v2, 0x43000000, v68
	s_waitcnt vmcnt(20)
	v_mul_f32_e32 v27, 0x43000000, v69
	ds_write2_b32 v36, v2, v27 offset0:148 offset1:214
	s_waitcnt vmcnt(19)
	v_mul_f32_e32 v2, 0x43000000, v70
	s_waitcnt vmcnt(18)
	v_mul_f32_e32 v27, 0x43000000, v71
	ds_write2_b32 v37, v2, v27 offset0:24 offset1:90
	s_waitcnt vmcnt(17)
	v_mul_f32_e32 v2, 0x43000000, v72
	s_waitcnt vmcnt(16)
	v_mul_f32_e32 v27, 0x43000000, v73
	ds_write2_b32 v37, v2, v27 offset0:156 offset1:222
	v_lshl_add_u64 v[60:61], s[6:7], 0, v[6:7]
	s_waitcnt vmcnt(15)
	v_mul_f32_e32 v2, 0x43000000, v74
	s_waitcnt vmcnt(14)
	v_mul_f32_e32 v27, 0x43000000, v75
	ds_write2_b32 v38, v2, v27 offset0:32 offset1:98
	s_waitcnt vmcnt(13)
	v_mul_f32_e32 v2, 0x43000000, v76
	s_waitcnt vmcnt(12)
	v_mul_f32_e32 v27, 0x43000000, v77
	ds_write2_b32 v38, v2, v27 offset0:164 offset1:230
	s_waitcnt vmcnt(11)
	v_mul_f32_e32 v2, 0x43000000, v78
	s_waitcnt vmcnt(10)
	v_mul_f32_e32 v27, 0x43000000, v79
	ds_write2_b32 v39, v2, v27 offset0:40 offset1:106
	s_waitcnt vmcnt(9)
	v_mul_f32_e32 v2, 0x43000000, v56
	s_waitcnt vmcnt(8)
	v_mul_f32_e32 v27, 0x43000000, v57
	ds_write2_b32 v39, v2, v27 offset0:172 offset1:238
	s_waitcnt vmcnt(7)
	v_mul_f32_e32 v2, 0x43000000, v58
	s_waitcnt vmcnt(6)
	v_mul_f32_e32 v27, 0x43000000, v46
	ds_write2_b32 v40, v2, v27 offset0:48 offset1:114
	s_waitcnt vmcnt(5)
	v_mul_f32_e32 v2, 0x43000000, v47
	s_waitcnt vmcnt(4)
	v_mul_f32_e32 v27, 0x43000000, v48
	ds_write2_b32 v40, v2, v27 offset0:180 offset1:246
	s_waitcnt vmcnt(3)
	v_mul_f32_e32 v2, 0x43000000, v49
	s_waitcnt vmcnt(2)
	v_mul_f32_e32 v27, 0x43000000, v50
	ds_write2_b32 v41, v2, v27 offset0:56 offset1:122
	v_mov_b32_e32 v50, v3
	s_waitcnt vmcnt(1)
	v_mul_f32_e32 v2, 0x43000000, v44
	s_waitcnt vmcnt(0)
	v_mul_f32_e32 v27, 0x43000000, v42
	ds_write2_b32 v41, v2, v27 offset0:188 offset1:254
	s_waitcnt lgkmcnt(0)
	ds_read2_b32 v[42:43], v31 offset0:33 offset1:41
	ds_read2_b32 v[44:45], v31 offset0:66 offset1:74
	ds_read2_b32 v[46:47], v31 offset1:8
	ds_read2_b32 v[48:49], v31 offset0:99 offset1:107
	ds_read2_b32 v[52:53], v31 offset0:132 offset1:140
	ds_read2_b32 v[54:55], v31 offset0:165 offset1:173
	ds_read2_b32 v[56:57], v31 offset0:198 offset1:206
	ds_read2_b32 v[58:59], v31 offset0:231 offset1:239
	v_or_b32_e32 v2, s2, v30
	s_waitcnt lgkmcnt(5)
	v_cvt_pk_fp8_f32 v50, v46, v42
	v_mov_b32_e32 v42, v3
	s_waitcnt lgkmcnt(2)
	v_cvt_pk_fp8_f32 v51, v52, v54
	v_cvt_pk_fp8_f32 v42, v47, v43
	v_cvt_pk_fp8_f32 v50, v44, v48 op_sel:[0,0,1]
	v_mov_b32_e32 v43, v3
	s_waitcnt lgkmcnt(0)
	v_cvt_pk_fp8_f32 v51, v56, v58 op_sel:[0,0,1]
	v_cvt_pk_fp8_f32 v43, v53, v55
	v_lshlrev_b32_e32 v2, 11, v2
	v_lshl_add_u64 v[46:47], v[60:61], 0, v[2:3]
	global_store_dwordx2 v[46:47], v[50:51], off nt
	v_cvt_pk_fp8_f32 v42, v45, v49 op_sel:[0,0,1]
	v_cvt_pk_fp8_f32 v43, v57, v59 op_sel:[0,0,1]
	ds_read2_b32 v[44:45], v31 offset0:49 offset1:57
	ds_read2_b32 v[46:47], v31 offset0:82 offset1:90
	ds_read2_b32 v[48:49], v31 offset0:16 offset1:24
	ds_read2_b32 v[50:51], v31 offset0:115 offset1:123
	ds_read2_b32 v[54:55], v31 offset0:148 offset1:156
	ds_read2_b32 v[56:57], v31 offset0:181 offset1:189
	v_or_b32_e32 v2, s2, v32
	v_lshlrev_b32_e32 v2, 11, v2
	v_mov_b32_e32 v52, v3
	ds_read2_b32 v[58:59], v31 offset0:214 offset1:222
	ds_read2_b32 v[62:63], v31 offset0:247 offset1:255
	v_mov_b32_e32 v53, v3
	v_lshl_add_u64 v[64:65], v[60:61], 0, v[2:3]
	s_waitcnt lgkmcnt(5)
	v_cvt_pk_fp8_f32 v52, v48, v44
	s_waitcnt lgkmcnt(2)
	v_cvt_pk_fp8_f32 v53, v54, v56
	global_store_dwordx2 v[64:65], v[42:43], off nt
	v_mov_b32_e32 v42, v3
	v_mov_b32_e32 v43, v3
	v_cvt_pk_fp8_f32 v42, v49, v45
	v_cvt_pk_fp8_f32 v43, v55, v57
	v_cvt_pk_fp8_f32 v52, v46, v50 op_sel:[0,0,1]
	s_waitcnt lgkmcnt(0)
	v_cvt_pk_fp8_f32 v53, v58, v62 op_sel:[0,0,1]
	v_or_b32_e32 v2, s2, v33
	v_lshlrev_b32_e32 v2, 11, v2
	v_cvt_pk_fp8_f32 v42, v47, v51 op_sel:[0,0,1]
	v_cvt_pk_fp8_f32 v43, v59, v63 op_sel:[0,0,1]
	v_lshl_add_u64 v[44:45], v[60:61], 0, v[2:3]
	v_or_b32_e32 v2, s2, v34
	v_lshlrev_b32_e32 v2, 11, v2
	global_store_dwordx2 v[44:45], v[52:53], off nt
	v_lshl_add_u64 v[44:45], v[60:61], 0, v[2:3]
	global_store_dwordx2 v[44:45], v[42:43], off nt
	s_waitcnt lgkmcnt(0)

.LBB0_49:
	s_andn2_b64 vcc, exec, s[4:5]
	s_cbranch_vccnz .LBB0_51
	s_add_i32 s2, s15, 0xb5c0
	s_lshr_b32 s4, s2, 1
	s_lshl_b32 s2, s2, 5
	s_and_b32 s4, s4, 0x7fc0
	s_and_b32 s6, s2, 0xfe0
	v_or_b32_e32 v2, s4, v28
	s_lshl_b32 s2, s6, 2
	v_lshl_add_u64 v[42:43], v[18:19], 0, s[2:3]
	v_lshlrev_b32_e32 v2, 14, v2
	v_lshl_add_u64 v[42:43], v[42:43], 0, v[2:3]
	v_add_co_u32_e32 v44, vcc, 0x8000, v42
	s_mov_b32 s5, s3
	s_nop 0
	v_addc_co_u32_e32 v45, vcc, 0, v43, vcc
	v_add_co_u32_e32 v46, vcc, 0x10000, v42
	s_nop 1
	v_addc_co_u32_e32 v47, vcc, 0, v43, vcc
	v_add_co_u32_e32 v48, vcc, 0x18000, v42
	s_nop 1
	v_addc_co_u32_e32 v49, vcc, 0, v43, vcc
	v_add_co_u32_e32 v50, vcc, 0x20000, v42
	s_nop 1
	v_addc_co_u32_e32 v51, vcc, 0, v43, vcc
	v_add_co_u32_e32 v52, vcc, 0x28000, v42
	s_nop 1
	v_addc_co_u32_e32 v53, vcc, 0, v43, vcc
	v_add_co_u32_e32 v54, vcc, 0x30000, v42
	s_nop 1
	v_addc_co_u32_e32 v55, vcc, 0, v43, vcc
	v_add_co_u32_e32 v56, vcc, 0x38000, v42
	s_nop 1
	v_addc_co_u32_e32 v57, vcc, 0, v43, vcc
	global_load_dword v2, v[42:43], off nt
	global_load_dword v27, v[44:45], off nt
	global_load_dword v60, v[46:47], off nt
	global_load_dword v61, v[48:49], off nt
	global_load_dword v62, v[50:51], off nt
	global_load_dword v63, v[52:53], off nt
	global_load_dword v64, v[54:55], off nt
	global_load_dword v65, v[56:57], off nt
	v_add_co_u32_e32 v44, vcc, 0x40000, v42
	s_waitcnt vmcnt(7)
	v_mul_f32_e32 v2, 0x42000000, v2
	v_addc_co_u32_e32 v45, vcc, 0, v43, vcc
	v_add_co_u32_e32 v46, vcc, 0x48000, v42
	s_waitcnt vmcnt(6)
	v_mul_f32_e32 v27, 0x42000000, v27
	v_addc_co_u32_e32 v47, vcc, 0, v43, vcc
	v_add_co_u32_e32 v48, vcc, 0x50000, v42
	s_nop 1
	v_addc_co_u32_e32 v49, vcc, 0, v43, vcc
	v_add_co_u32_e32 v50, vcc, 0x58000, v42
	s_nop 1
	v_addc_co_u32_e32 v51, vcc, 0, v43, vcc
	v_add_co_u32_e32 v52, vcc, 0x60000, v42
	s_nop 1
	v_addc_co_u32_e32 v53, vcc, 0, v43, vcc
	v_add_co_u32_e32 v54, vcc, 0x68000, v42
	s_nop 1
	v_addc_co_u32_e32 v55, vcc, 0, v43, vcc
	v_add_co_u32_e32 v56, vcc, 0x70000, v42
	s_nop 1
	v_addc_co_u32_e32 v57, vcc, 0, v43, vcc
	v_add_co_u32_e32 v58, vcc, 0x78000, v42
	s_nop 1
	v_addc_co_u32_e32 v59, vcc, 0, v43, vcc
	global_load_dword v66, v[44:45], off nt
	global_load_dword v67, v[46:47], off nt
	global_load_dword v68, v[48:49], off nt
	global_load_dword v69, v[50:51], off nt
	global_load_dword v70, v[52:53], off nt
	global_load_dword v71, v[54:55], off nt
	global_load_dword v72, v[56:57], off nt
	global_load_dword v73, v[58:59], off nt
	v_add_co_u32_e32 v44, vcc, 0x80000, v42
	s_nop 1
	v_addc_co_u32_e32 v45, vcc, 0, v43, vcc
	v_add_co_u32_e32 v46, vcc, 0x88000, v42
	s_nop 1
	v_addc_co_u32_e32 v47, vcc, 0, v43, vcc
	v_add_co_u32_e32 v48, vcc, 0x90000, v42
	s_nop 1
	v_addc_co_u32_e32 v49, vcc, 0, v43, vcc
	v_add_co_u32_e32 v50, vcc, 0x98000, v42
	s_nop 1
	v_addc_co_u32_e32 v51, vcc, 0, v43, vcc
	v_add_co_u32_e32 v52, vcc, 0xa0000, v42
	s_nop 1
	v_addc_co_u32_e32 v53, vcc, 0, v43, vcc
	v_add_co_u32_e32 v54, vcc, 0xa8000, v42
	s_nop 1
	v_addc_co_u32_e32 v55, vcc, 0, v43, vcc
	v_add_co_u32_e32 v56, vcc, s59, v42
	s_nop 1
	v_addc_co_u32_e32 v57, vcc, 0, v43, vcc
	v_add_co_u32_e32 v58, vcc, 0xb8000, v42
	s_nop 1
	v_addc_co_u32_e32 v59, vcc, 0, v43, vcc
	global_load_dword v74, v[44:45], off nt
	global_load_dword v75, v[46:47], off nt
	global_load_dword v76, v[48:49], off nt
	global_load_dword v77, v[50:51], off nt
	global_load_dword v78, v[52:53], off nt
	global_load_dword v79, v[54:55], off nt
	s_nop 0
	global_load_dword v56, v[56:57], off nt
	s_nop 0
	global_load_dword v57, v[58:59], off nt
	v_add_co_u32_e32 v44, vcc, 0xc0000, v42
	s_nop 1
	v_addc_co_u32_e32 v45, vcc, 0, v43, vcc
	v_add_co_u32_e32 v46, vcc, 0xc8000, v42
	s_nop 1
	v_addc_co_u32_e32 v47, vcc, 0, v43, vcc
	v_add_co_u32_e32 v48, vcc, 0xd0000, v42
	s_nop 1
	v_addc_co_u32_e32 v49, vcc, 0, v43, vcc
	v_add_co_u32_e32 v50, vcc, 0xd8000, v42
	s_nop 1
	v_addc_co_u32_e32 v51, vcc, 0, v43, vcc
	v_add_co_u32_e32 v52, vcc, 0xe0000, v42
	s_nop 1
	v_addc_co_u32_e32 v53, vcc, 0, v43, vcc
	v_add_co_u32_e32 v54, vcc, 0xe8000, v42
	s_nop 1
	v_addc_co_u32_e32 v55, vcc, 0, v43, vcc
	global_load_dword v58, v[44:45], off nt
	s_nop 0
	global_load_dword v46, v[46:47], off nt
	s_nop 0
	global_load_dword v47, v[48:49], off nt
	s_nop 0
	global_load_dword v48, v[50:51], off nt
	global_load_dword v49, v[52:53], off nt
	s_nop 0
	global_load_dword v50, v[54:55], off nt
	v_add_co_u32_e32 v44, vcc, 0xf0000, v42
	v_mov_b32_e32 v51, v3
	s_nop 0
	v_addc_co_u32_e32 v45, vcc, 0, v43, vcc
	v_add_co_u32_e32 v42, vcc, 0xf8000, v42
	s_nop 1
	v_addc_co_u32_e32 v43, vcc, 0, v43, vcc
	global_load_dword v44, v[44:45], off nt
	s_nop 0
	global_load_dword v42, v[42:43], off nt
	ds_write2_b32 v29, v2, v27 offset1:66
	s_waitcnt vmcnt(29)
	v_mul_f32_e32 v2, 0x42000000, v60
	s_waitcnt vmcnt(28)
	v_mul_f32_e32 v27, 0x42000000, v61
	ds_write2_b32 v29, v2, v27 offset0:132 offset1:198
	s_waitcnt vmcnt(27)
	v_mul_f32_e32 v2, 0x42000000, v62
	s_waitcnt vmcnt(26)
	v_mul_f32_e32 v27, 0x42000000, v63
	ds_write2_b32 v35, v2, v27 offset0:8 offset1:74
	s_waitcnt vmcnt(25)
	v_mul_f32_e32 v2, 0x42000000, v64
	s_waitcnt vmcnt(24)
	v_mul_f32_e32 v27, 0x42000000, v65
	ds_write2_b32 v35, v2, v27 offset0:140 offset1:206
	s_waitcnt vmcnt(23)
	v_mul_f32_e32 v2, 0x42000000, v66
	s_waitcnt vmcnt(22)
	v_mul_f32_e32 v27, 0x42000000, v67
	ds_write2_b32 v36, v2, v27 offset0:16 offset1:82
	s_waitcnt vmcnt(21)
	v_mul_f32_e32 v2, 0x42000000, v68
	s_waitcnt vmcnt(20)
	v_mul_f32_e32 v27, 0x42000000, v69
	ds_write2_b32 v36, v2, v27 offset0:148 offset1:214
	s_waitcnt vmcnt(19)
	v_mul_f32_e32 v2, 0x42000000, v70
	s_waitcnt vmcnt(18)
	v_mul_f32_e32 v27, 0x42000000, v71
	ds_write2_b32 v37, v2, v27 offset0:24 offset1:90
	s_waitcnt vmcnt(17)
	v_mul_f32_e32 v2, 0x42000000, v72
	s_waitcnt vmcnt(16)
	v_mul_f32_e32 v27, 0x42000000, v73
	ds_write2_b32 v37, v2, v27 offset0:156 offset1:222
	v_lshl_add_u64 v[60:61], v[20:21], 0, s[4:5]
	s_waitcnt vmcnt(15)
	v_mul_f32_e32 v2, 0x42000000, v74
	s_waitcnt vmcnt(14)
	v_mul_f32_e32 v27, 0x42000000, v75
	ds_write2_b32 v38, v2, v27 offset0:32 offset1:98
	s_waitcnt vmcnt(13)
	v_mul_f32_e32 v2, 0x42000000, v76
	s_waitcnt vmcnt(12)
	v_mul_f32_e32 v27, 0x42000000, v77
	ds_write2_b32 v38, v2, v27 offset0:164 offset1:230
	s_waitcnt vmcnt(11)
	v_mul_f32_e32 v2, 0x42000000, v78
	s_waitcnt vmcnt(10)
	v_mul_f32_e32 v27, 0x42000000, v79
	ds_write2_b32 v39, v2, v27 offset0:40 offset1:106
	s_waitcnt vmcnt(9)
	v_mul_f32_e32 v2, 0x42000000, v56
	s_waitcnt vmcnt(8)
	v_mul_f32_e32 v27, 0x42000000, v57
	ds_write2_b32 v39, v2, v27 offset0:172 offset1:238
	s_waitcnt vmcnt(7)
	v_mul_f32_e32 v2, 0x42000000, v58
	s_waitcnt vmcnt(6)
	v_mul_f32_e32 v27, 0x42000000, v46
	ds_write2_b32 v40, v2, v27 offset0:48 offset1:114
	s_waitcnt vmcnt(5)
	v_mul_f32_e32 v2, 0x42000000, v47
	s_waitcnt vmcnt(4)
	v_mul_f32_e32 v27, 0x42000000, v48
	ds_write2_b32 v40, v2, v27 offset0:180 offset1:246
	s_waitcnt vmcnt(3)
	v_mul_f32_e32 v2, 0x42000000, v49
	s_waitcnt vmcnt(2)
	v_mul_f32_e32 v27, 0x42000000, v50
	ds_write2_b32 v41, v2, v27 offset0:56 offset1:122
	v_mov_b32_e32 v50, v3
	s_waitcnt vmcnt(1)
	v_mul_f32_e32 v2, 0x42000000, v44
	s_waitcnt vmcnt(0)
	v_mul_f32_e32 v27, 0x42000000, v42
	ds_write2_b32 v41, v2, v27 offset0:188 offset1:254
	s_waitcnt lgkmcnt(0)
	ds_read2_b32 v[42:43], v31 offset0:33 offset1:41
	ds_read2_b32 v[44:45], v31 offset0:66 offset1:74
	ds_read2_b32 v[46:47], v31 offset1:8
	ds_read2_b32 v[48:49], v31 offset0:99 offset1:107
	ds_read2_b32 v[52:53], v31 offset0:132 offset1:140
	ds_read2_b32 v[54:55], v31 offset0:165 offset1:173
	ds_read2_b32 v[56:57], v31 offset0:198 offset1:206
	ds_read2_b32 v[58:59], v31 offset0:231 offset1:239
	v_or_b32_e32 v2, s6, v30
	s_waitcnt lgkmcnt(5)
	v_cvt_pk_fp8_f32 v50, v46, v42
	v_mov_b32_e32 v42, v3
	s_waitcnt lgkmcnt(2)
	v_cvt_pk_fp8_f32 v51, v52, v54
	v_cvt_pk_fp8_f32 v42, v47, v43
	v_cvt_pk_fp8_f32 v50, v44, v48 op_sel:[0,0,1]
	v_mov_b32_e32 v43, v3
	s_waitcnt lgkmcnt(0)
	v_cvt_pk_fp8_f32 v51, v56, v58 op_sel:[0,0,1]
	v_cvt_pk_fp8_f32 v43, v53, v55
	v_lshlrev_b32_e32 v2, 9, v2
	v_lshl_add_u64 v[46:47], v[60:61], 0, v[2:3]
	global_store_dwordx2 v[46:47], v[50:51], off nt
	v_cvt_pk_fp8_f32 v42, v45, v49 op_sel:[0,0,1]
	v_cvt_pk_fp8_f32 v43, v57, v59 op_sel:[0,0,1]
	ds_read2_b32 v[44:45], v31 offset0:49 offset1:57
	ds_read2_b32 v[46:47], v31 offset0:82 offset1:90
	ds_read2_b32 v[48:49], v31 offset0:16 offset1:24
	ds_read2_b32 v[50:51], v31 offset0:115 offset1:123
	ds_read2_b32 v[54:55], v31 offset0:148 offset1:156
	ds_read2_b32 v[56:57], v31 offset0:181 offset1:189
	v_or_b32_e32 v2, s6, v32
	v_lshlrev_b32_e32 v2, 9, v2
	v_mov_b32_e32 v52, v3
	ds_read2_b32 v[58:59], v31 offset0:214 offset1:222
	ds_read2_b32 v[62:63], v31 offset0:247 offset1:255
	v_mov_b32_e32 v53, v3
	v_lshl_add_u64 v[64:65], v[60:61], 0, v[2:3]
	s_waitcnt lgkmcnt(5)
	v_cvt_pk_fp8_f32 v52, v48, v44
	s_waitcnt lgkmcnt(2)
	v_cvt_pk_fp8_f32 v53, v54, v56
	global_store_dwordx2 v[64:65], v[42:43], off nt
	v_mov_b32_e32 v42, v3
	v_mov_b32_e32 v43, v3
	v_cvt_pk_fp8_f32 v42, v49, v45
	v_cvt_pk_fp8_f32 v43, v55, v57
	v_cvt_pk_fp8_f32 v52, v46, v50 op_sel:[0,0,1]
	s_waitcnt lgkmcnt(0)
	v_cvt_pk_fp8_f32 v53, v58, v62 op_sel:[0,0,1]
	v_or_b32_e32 v2, s6, v33
	v_lshlrev_b32_e32 v2, 9, v2
	v_cvt_pk_fp8_f32 v42, v47, v51 op_sel:[0,0,1]
	v_cvt_pk_fp8_f32 v43, v59, v63 op_sel:[0,0,1]
	v_lshl_add_u64 v[44:45], v[60:61], 0, v[2:3]
	v_or_b32_e32 v2, s6, v34
	v_lshlrev_b32_e32 v2, 9, v2
	global_store_dwordx2 v[44:45], v[52:53], off nt
	v_lshl_add_u64 v[44:45], v[60:61], 0, v[2:3]
	global_store_dwordx2 v[44:45], v[42:43], off nt
	s_waitcnt lgkmcnt(0)

.LBB0_52:
	s_andn2_b64 vcc, exec, s[4:5]
	s_cbranch_vccnz .LBB0_33
	s_mul_hi_i32 s2, s15, 0x6e5478ad
	s_lshr_b32 s4, s2, 31
	s_ashr_i32 s2, s2, 8
	s_add_i32 s2, s2, s4
	s_mul_i32 s5, s2, 0xffffb5c0
	s_lshl_b32 s4, s2, 6
	s_add_i32 s6, s11, s5
	v_or_b32_e32 v2, s4, v28
	s_ashr_i32 s7, s6, 31
	v_lshl_add_u64 v[42:43], s[6:7], 2, v[22:23]
	v_or_b32_e32 v27, 2, v2
	v_mad_i64_i32 v[46:47], s[84:85], v27, s83, v[42:43]
	v_or_b32_e32 v27, 4, v2
	v_mad_i64_i32 v[48:49], s[84:85], v27, s83, v[42:43]
	v_or_b32_e32 v27, 6, v2
	v_mad_i64_i32 v[50:51], s[84:85], v27, s83, v[42:43]
	v_or_b32_e32 v27, 8, v2
	v_mad_i64_i32 v[52:53], s[84:85], v27, s83, v[42:43]
	v_or_b32_e32 v27, 10, v2
	v_mad_i64_i32 v[54:55], s[84:85], v27, s83, v[42:43]
	v_or_b32_e32 v27, 12, v2
	v_mad_i64_i32 v[44:45], s[84:85], v2, s83, v[42:43]
	v_mad_i64_i32 v[56:57], s[84:85], v27, s83, v[42:43]
	v_or_b32_e32 v27, 14, v2
	v_mad_i64_i32 v[58:59], s[84:85], v27, s83, v[42:43]
	global_load_dword v27, v[44:45], off nt
	global_load_dword v60, v[46:47], off nt
	global_load_dword v61, v[48:49], off nt
	global_load_dword v62, v[50:51], off nt
	global_load_dword v63, v[52:53], off nt
	global_load_dword v64, v[54:55], off nt
	global_load_dword v65, v[56:57], off nt
	global_load_dword v66, v[58:59], off nt
	v_or_b32_e32 v44, 16, v2
	v_mad_i64_i32 v[44:45], s[84:85], v44, s83, v[42:43]
	v_or_b32_e32 v46, 18, v2
	v_or_b32_e32 v48, 20, v2
	v_or_b32_e32 v50, 22, v2
	v_or_b32_e32 v52, 24, v2
	v_or_b32_e32 v54, 26, v2
	v_or_b32_e32 v56, 28, v2
	v_or_b32_e32 v58, 30, v2
	v_mad_i64_i32 v[46:47], s[84:85], v46, s83, v[42:43]
	v_mad_i64_i32 v[48:49], s[84:85], v48, s83, v[42:43]
	v_mad_i64_i32 v[50:51], s[84:85], v50, s83, v[42:43]
	v_mad_i64_i32 v[52:53], s[84:85], v52, s83, v[42:43]
	v_mad_i64_i32 v[54:55], s[84:85], v54, s83, v[42:43]
	v_mad_i64_i32 v[56:57], s[84:85], v56, s83, v[42:43]
	v_mad_i64_i32 v[58:59], s[84:85], v58, s83, v[42:43]
	global_load_dword v67, v[44:45], off nt
	global_load_dword v68, v[46:47], off nt
	global_load_dword v69, v[48:49], off nt
	global_load_dword v70, v[50:51], off nt
	global_load_dword v71, v[52:53], off nt
	global_load_dword v72, v[54:55], off nt
	global_load_dword v73, v[56:57], off nt
	global_load_dword v74, v[58:59], off nt
	v_or_b32_e32 v44, 32, v2
	v_or_b32_e32 v46, 34, v2
	v_or_b32_e32 v48, 36, v2
	v_or_b32_e32 v50, 38, v2
	v_or_b32_e32 v56, 44, v2
	v_mad_i64_i32 v[44:45], s[84:85], v44, s83, v[42:43]
	v_mad_i64_i32 v[46:47], s[84:85], v46, s83, v[42:43]
	v_mad_i64_i32 v[48:49], s[84:85], v48, s83, v[42:43]
	v_mad_i64_i32 v[50:51], s[84:85], v50, s83, v[42:43]
	v_or_b32_e32 v52, 40, v2
	v_or_b32_e32 v54, 42, v2
	v_mad_i64_i32 v[56:57], s[84:85], v56, s83, v[42:43]
	v_or_b32_e32 v58, 46, v2
	v_mad_i64_i32 v[52:53], s[84:85], v52, s83, v[42:43]
	v_mad_i64_i32 v[54:55], s[84:85], v54, s83, v[42:43]
	v_mad_i64_i32 v[58:59], s[84:85], v58, s83, v[42:43]
	global_load_dword v75, v[44:45], off nt
	global_load_dword v76, v[46:47], off nt
	global_load_dword v77, v[48:49], off nt
	global_load_dword v78, v[50:51], off nt
	global_load_dword v79, v[52:53], off nt
	global_load_dword v80, v[54:55], off nt
	s_nop 0
	global_load_dword v56, v[56:57], off nt
	s_nop 0
	global_load_dword v57, v[58:59], off nt
	v_or_b32_e32 v44, 48, v2
	v_or_b32_e32 v46, 50, v2
	v_or_b32_e32 v48, 52, v2
	v_or_b32_e32 v50, 54, v2
	v_mad_i64_i32 v[44:45], s[84:85], v44, s83, v[42:43]
	v_mad_i64_i32 v[46:47], s[84:85], v46, s83, v[42:43]
	v_mad_i64_i32 v[48:49], s[84:85], v48, s83, v[42:43]
	v_mad_i64_i32 v[50:51], s[84:85], v50, s83, v[42:43]
	v_or_b32_e32 v52, 56, v2
	v_or_b32_e32 v54, 58, v2
	v_mad_i64_i32 v[52:53], s[84:85], v52, s83, v[42:43]
	v_mad_i64_i32 v[54:55], s[84:85], v54, s83, v[42:43]
	global_load_dword v58, v[44:45], off nt
	s_nop 0
	global_load_dword v46, v[46:47], off nt
	s_nop 0
	global_load_dword v47, v[48:49], off nt
	s_nop 0
	global_load_dword v48, v[50:51], off nt
	global_load_dword v49, v[52:53], off nt
	s_nop 0
	global_load_dword v50, v[54:55], off nt
	v_or_b32_e32 v44, 60, v2
	v_or_b32_e32 v2, 62, v2
	v_mad_i64_i32 v[44:45], s[84:85], v44, s83, v[42:43]
	v_mad_i64_i32 v[42:43], s[84:85], v2, s83, v[42:43]
	global_load_dword v2, v[44:45], off nt
	s_nop 0
	global_load_dword v42, v[42:43], off nt
	s_waitcnt vmcnt(31)
	v_mul_f32_e32 v27, 0x42800000, v27
	s_waitcnt vmcnt(30)
	v_mul_f32_e32 v43, 0x42800000, v60
	ds_write2_b32 v29, v27, v43 offset1:66
	s_waitcnt vmcnt(29)
	v_mul_f32_e32 v27, 0x42800000, v61
	s_waitcnt vmcnt(28)
	v_mul_f32_e32 v43, 0x42800000, v62
	ds_write2_b32 v29, v27, v43 offset0:132 offset1:198
	s_waitcnt vmcnt(27)
	v_mul_f32_e32 v27, 0x42800000, v63
	s_waitcnt vmcnt(26)
	v_mul_f32_e32 v43, 0x42800000, v64
	ds_write2_b32 v35, v27, v43 offset0:8 offset1:74
	s_waitcnt vmcnt(25)
	v_mul_f32_e32 v27, 0x42800000, v65
	s_waitcnt vmcnt(24)
	v_mul_f32_e32 v43, 0x42800000, v66
	ds_write2_b32 v35, v27, v43 offset0:140 offset1:206
	s_lshl_b32 s2, s2, 1
	s_sub_i32 s2, s15, s2
	v_mov_b32_e32 v51, 0
	s_and_b32 s5, s13, 4
	s_bfe_u32 s2, s2, 0x20001
	s_or_b32 s2, s5, s2
	s_lshl_b32 s2, s2, 5
	s_and_b32 s5, s6, 0xffffff00
	s_or_b32 s2, s2, s5
	s_waitcnt vmcnt(23)
	v_mul_f32_e32 v27, 0x42800000, v67
	s_waitcnt vmcnt(22)
	v_mul_f32_e32 v43, 0x42800000, v68
	ds_write2_b32 v36, v27, v43 offset0:16 offset1:82
	s_waitcnt vmcnt(21)
	v_mul_f32_e32 v27, 0x42800000, v69
	s_waitcnt vmcnt(20)
	v_mul_f32_e32 v43, 0x42800000, v70
	ds_write2_b32 v36, v27, v43 offset0:148 offset1:214
	s_waitcnt vmcnt(19)
	v_mul_f32_e32 v27, 0x42800000, v71
	s_waitcnt vmcnt(18)
	v_mul_f32_e32 v43, 0x42800000, v72
	ds_write2_b32 v37, v27, v43 offset0:24 offset1:90
	s_waitcnt vmcnt(17)
	v_mul_f32_e32 v27, 0x42800000, v73
	s_waitcnt vmcnt(16)
	v_mul_f32_e32 v43, 0x42800000, v74
	ds_write2_b32 v37, v27, v43 offset0:156 offset1:222
	v_or_b32_e32 v62, s2, v30
	s_ashr_i32 s5, s4, 31
	v_ashrrev_i32_e32 v63, 31, v62
	v_lshl_add_u64 v[60:61], v[24:25], 0, s[4:5]
	v_lshlrev_b64 v[62:63], 11, v[62:63]
	s_waitcnt vmcnt(15)
	v_mul_f32_e32 v27, 0x42800000, v75
	s_waitcnt vmcnt(14)
	v_mul_f32_e32 v43, 0x42800000, v76
	ds_write2_b32 v38, v27, v43 offset0:32 offset1:98
	s_waitcnt vmcnt(13)
	v_mul_f32_e32 v27, 0x42800000, v77
	s_waitcnt vmcnt(12)
	v_mul_f32_e32 v43, 0x42800000, v78
	ds_write2_b32 v38, v27, v43 offset0:164 offset1:230
	s_waitcnt vmcnt(11)
	v_mul_f32_e32 v27, 0x42800000, v79
	s_waitcnt vmcnt(10)
	v_mul_f32_e32 v43, 0x42800000, v80
	ds_write2_b32 v39, v27, v43 offset0:40 offset1:106
	s_waitcnt vmcnt(9)
	v_mul_f32_e32 v27, 0x42800000, v56
	s_waitcnt vmcnt(8)
	v_mul_f32_e32 v43, 0x42800000, v57
	ds_write2_b32 v39, v27, v43 offset0:172 offset1:238
	s_waitcnt vmcnt(7)
	v_mul_f32_e32 v27, 0x42800000, v58
	s_waitcnt vmcnt(6)
	v_mul_f32_e32 v43, 0x42800000, v46
	ds_write2_b32 v40, v27, v43 offset0:48 offset1:114
	s_waitcnt vmcnt(5)
	v_mul_f32_e32 v27, 0x42800000, v47
	s_waitcnt vmcnt(4)
	v_mul_f32_e32 v43, 0x42800000, v48
	ds_write2_b32 v40, v27, v43 offset0:180 offset1:246
	s_waitcnt vmcnt(3)
	v_mul_f32_e32 v27, 0x42800000, v49
	s_waitcnt vmcnt(2)
	v_mul_f32_e32 v43, 0x42800000, v50
	ds_write2_b32 v41, v27, v43 offset0:56 offset1:122
	v_mov_b32_e32 v50, 0
	s_waitcnt vmcnt(1)
	v_mul_f32_e32 v2, 0x42800000, v2
	s_waitcnt vmcnt(0)
	v_mul_f32_e32 v27, 0x42800000, v42
	ds_write2_b32 v41, v2, v27 offset0:188 offset1:254
	s_waitcnt lgkmcnt(0)
	ds_read2_b32 v[42:43], v31 offset0:33 offset1:41
	ds_read2_b32 v[44:45], v31 offset0:66 offset1:74
	ds_read2_b32 v[46:47], v31 offset1:8
	ds_read2_b32 v[48:49], v31 offset0:99 offset1:107
	ds_read2_b32 v[52:53], v31 offset0:132 offset1:140
	ds_read2_b32 v[54:55], v31 offset0:165 offset1:173
	ds_read2_b32 v[56:57], v31 offset0:198 offset1:206
	ds_read2_b32 v[58:59], v31 offset0:231 offset1:239
	s_waitcnt lgkmcnt(5)
	v_cvt_pk_fp8_f32 v50, v46, v42
	v_mov_b32_e32 v42, 0
	s_waitcnt lgkmcnt(2)
	v_cvt_pk_fp8_f32 v51, v52, v54
	v_cvt_pk_fp8_f32 v42, v47, v43
	v_cvt_pk_fp8_f32 v50, v44, v48 op_sel:[0,0,1]
	v_mov_b32_e32 v43, 0
	s_waitcnt lgkmcnt(0)
	v_cvt_pk_fp8_f32 v51, v56, v58 op_sel:[0,0,1]
	v_cvt_pk_fp8_f32 v43, v53, v55
	v_lshl_add_u64 v[46:47], v[60:61], 0, v[62:63]
	v_cvt_pk_fp8_f32 v42, v45, v49 op_sel:[0,0,1]
	global_store_dwordx2 v[46:47], v[50:51], off nt
	v_cvt_pk_fp8_f32 v43, v57, v59 op_sel:[0,0,1]
	ds_read2_b32 v[46:47], v31 offset0:49 offset1:57
	ds_read2_b32 v[48:49], v31 offset0:82 offset1:90
	ds_read2_b32 v[50:51], v31 offset0:16 offset1:24
	ds_read2_b32 v[52:53], v31 offset0:115 offset1:123
	ds_read2_b32 v[56:57], v31 offset0:148 offset1:156
	ds_read2_b32 v[58:59], v31 offset0:181 offset1:189
	v_or_b32_e32 v44, s2, v32
	v_mov_b32_e32 v54, 0
	ds_read2_b32 v[62:63], v31 offset0:214 offset1:222
	ds_read2_b32 v[64:65], v31 offset0:247 offset1:255
	v_mov_b32_e32 v55, 0
	v_ashrrev_i32_e32 v45, 31, v44
	s_waitcnt lgkmcnt(5)
	v_cvt_pk_fp8_f32 v54, v50, v46
	s_waitcnt lgkmcnt(2)
	v_cvt_pk_fp8_f32 v55, v56, v58
	v_lshlrev_b64 v[44:45], 11, v[44:45]
	v_lshl_add_u64 v[44:45], v[60:61], 0, v[44:45]
	global_store_dwordx2 v[44:45], v[42:43], off nt
	v_mov_b32_e32 v44, 0
	v_mov_b32_e32 v45, 0
	v_cvt_pk_fp8_f32 v54, v48, v52 op_sel:[0,0,1]
	s_waitcnt lgkmcnt(0)
	v_cvt_pk_fp8_f32 v55, v62, v64 op_sel:[0,0,1]
	v_or_b32_e32 v42, s2, v33
	v_cvt_pk_fp8_f32 v44, v51, v47
	v_cvt_pk_fp8_f32 v45, v57, v59
	v_ashrrev_i32_e32 v43, 31, v42
	v_lshlrev_b64 v[42:43], 11, v[42:43]
	v_lshl_add_u64 v[42:43], v[60:61], 0, v[42:43]
	global_store_dwordx2 v[42:43], v[54:55], off nt
	v_cvt_pk_fp8_f32 v44, v49, v53 op_sel:[0,0,1]
	v_cvt_pk_fp8_f32 v45, v63, v65 op_sel:[0,0,1]
	v_or_b32_e32 v42, s2, v34
	v_ashrrev_i32_e32 v43, 31, v42
	v_lshlrev_b64 v[42:43], 11, v[42:43]
	v_lshl_add_u64 v[42:43], v[60:61], 0, v[42:43]
	global_store_dwordx2 v[42:43], v[44:45], off nt
	s_waitcnt lgkmcnt(0)
	s_branch .LBB0_33
.LBB0_54:
	s_cmp_eq_u32 s101, 1
	s_cbranch_scc1 .Lret_c3
	s_cmp_eq_u32 s101, 2
	s_cbranch_scc1 .Lret_c7
	v_lshl_add_u32 v1, s14, 9, v1
	s_movk_i32 s2, 0x6000
	v_cmp_gt_i32_e32 vcc, s2, v1
	s_and_saveexec_b64 s[2:3], vcc
	s_cbranch_execz .LBB0_57
	s_add_u32 s0, s0, 0x3500000
	v_mov_b32_e32 v2, 0
	s_addc_u32 s1, s1, 0
	s_lshl_b32 s6, s8, 9
	s_mov_b64 s[4:5], 0
	v_mov_b32_e32 v3, v2
	v_mov_b32_e32 v4, v2
	v_mov_b32_e32 v5, v2
	s_movk_i32 s7, 0x5fff

.LBB0_268:
	v_readlane_b32 s14, v252, 2
	v_mov_b32_e32 v1, v0
	s_cmp_lt_u32 s14, 24
	s_cbranch_scc1 .Lret_c3
	s_sub_u32 s14, s14, 24
	s_movk_i32 s8, 232
	s_mov_b32 s9, 0
	s_mov_b32 s99, 19008
	s_mov_b32 s100, 26175
	s_mov_b32 s101, 1
	s_branch .Lconv0_entry

.LBB0_997:
	v_readlane_b32 s14, v252, 2
	v_mov_b32_e32 v1, v0
	s_cmp_lt_u32 s14, 64
	s_cbranch_scc1 .Lret_c7
	s_sub_u32 s14, s14, 64
	s_movk_i32 s8, 192
	s_mov_b32 s9, 0
	s_mov_b32 s99, 26176
	s_mov_b32 s100, 45119
	s_mov_b32 s101, 2
	s_branch .Lconv0_entry

.LBB0_1076:
	v_readlane_b32 s13, v252, 2
	v_mov_b32_e32 v1, v0
	s_cmp_lt_u32 s13, 64
	s_cbranch_scc1 .Lret_c8
	s_sub_u32 s13, s13, 64
	s_movk_i32 s12, 192
	s_mov_b32 s22, 0
	s_mov_b32 s99, 0
	s_mov_b32 s100, 4607
	s_mov_b32 s101, 3
	s_branch .Lconv1_entry
.Lret_c8:
	s_mov_b32 s11, 0
	v_mov_b32_e32 v1, v0
	s_mov_b32 s0, s87
	s_mov_b32 s0, s88
	s_add_i32 s0, s11, 0x202b8
	v_mov_b32_e32 v1, s0
	s_add_i32 s0, s11, 0x202bc
	v_mov_b32_e32 v2, s0
	s_add_i32 s0, s11, 0x20168
	v_mov_b32_e32 v3, s0
	ds_read_b32 v1, v1
	ds_read_b32 v2, v2
	ds_read_b32 v3, v3
	s_waitcnt vmcnt(0)
	s_waitcnt vmcnt(0) lgkmcnt(0)
	v_readfirstlane_b32 s2, v1
	v_readfirstlane_b32 s3, v2
	v_readfirstlane_b32 s33, v3
	s_barrier
	s_mov_b64 s[0:1], exec
	v_readlane_b32 s4, v252, 3
	v_readlane_b32 s5, v252, 4
	s_and_b64 s[4:5], s[0:1], s[4:5]
	s_mov_b64 exec, s[4:5]
	s_cbranch_execz .LBB0_1128
	s_add_i32 s46, s11, 0x20160
	v_mov_b32_e32 v1, s46
	s_waitcnt vmcnt(0) expcnt(0) lgkmcnt(0)
	ds_read_b32 v3, v1
	s_add_i32 s47, s11, 0x20164
	v_mov_b32_e32 v1, s47
	ds_read_b32 v1, v1
	s_waitcnt lgkmcnt(1)
	v_cmp_ne_u32_e32 vcc, 0, v3
	s_cbranch_vccnz .LBB0_1092
	v_readlane_b32 s4, v252, 0
	v_readlane_b32 s5, v252, 1
	s_load_dwordx2 s[8:9], s[4:5], 0x4
	s_add_u32 s4, s2, 0x4200
	s_addc_u32 s5, s3, 0
	s_add_u32 s6, s2, 0x4400
	s_addc_u32 s7, s3, 0
	s_waitcnt lgkmcnt(0)
	s_mul_i32 s48, s8, s87
	s_add_u32 s8, s2, 0x4500
	s_mul_i32 s48, s48, s9
	s_addc_u32 s9, s3, 0
	s_add_u32 s10, s2, 0x4600
	s_addc_u32 s11, s3, 0
	s_add_u32 s12, s2, 0x4700
	s_addc_u32 s13, s3, 0
	s_add_u32 s14, s2, 0x4800
	s_addc_u32 s15, s3, 0
	s_add_u32 s16, s2, 0x4900
	s_addc_u32 s17, s3, 0
	s_add_u32 s18, s2, 0x4a00
	s_addc_u32 s19, s3, 0
	s_add_u32 s20, s2, 0x4b00
	s_addc_u32 s21, s3, 0
	s_add_u32 s22, s2, 0x4c00
	s_addc_u32 s23, s3, 0
	s_add_u32 s24, s2, 0x4d00
	s_addc_u32 s25, s3, 0
	s_add_u32 s26, s2, 0x4e00
	s_addc_u32 s27, s3, 0
	s_add_u32 s28, s2, 0x4f00
	s_addc_u32 s29, s3, 0
	s_add_u32 s30, s2, 0x5000
	s_addc_u32 s31, s3, 0
	s_add_u32 s34, s2, 0x5100
	s_addc_u32 s35, s3, 0
	s_add_u32 s36, s2, 0x5200
	s_addc_u32 s37, s3, 0
	s_add_u32 s38, s2, 0x5300
	s_addc_u32 s39, s3, 0
	s_mov_b32 s49, 1
	v_mov_b32_e32 v17, 0
	s_branch .LBB0_1080

.LBB0_1263:
	v_readlane_b32 s13, v252, 2
	v_mov_b32_e32 v1, v0
	s_cmp_lt_u32 s13, 96
	s_cbranch_scc1 .Lret_c10
	s_sub_u32 s13, s13, 96
	s_movk_i32 s12, 160
	s_mov_b32 s22, 0
	s_mov_b32 s99, 4608
	s_mov_b32 s100, 14847
	s_mov_b32 s101, 4
	s_branch .Lconv1_entry

.LBB0_1411:
	v_readlane_b32 s13, v252, 2
	v_mov_b32_e32 v1, v0
	s_cmp_lt_u32 s13, 64
	s_cbranch_scc1 .Lret_c12
	s_sub_u32 s13, s13, 64
	s_movk_i32 s12, 192
	s_mov_b32 s22, 0
	s_mov_b32 s99, 14848
	s_mov_b32 s100, 37887
	s_mov_b32 s101, 5
	s_branch .Lconv1_entry
.Lret_c12:
	s_mov_b32 s33, 0
	v_mov_b32_e32 v1, v0
	s_mov_b32 s0, s87
	s_mov_b32 s0, s88
	s_add_i32 s0, s33, 0x202b8
	v_mov_b32_e32 v1, s0
	s_add_i32 s0, s33, 0x202bc
	v_mov_b32_e32 v2, s0
	s_add_i32 s0, s33, 0x20168
	v_mov_b32_e32 v3, s0
	ds_read_b32 v1, v1
	ds_read_b32 v2, v2
	ds_read_b32 v3, v3
	s_waitcnt vmcnt(0)
	s_waitcnt vmcnt(0) lgkmcnt(0)
	v_readfirstlane_b32 s2, v1
	v_readfirstlane_b32 s3, v2
	v_readfirstlane_b32 s46, v3
	s_barrier
	s_mov_b64 s[0:1], exec
	v_readlane_b32 s4, v252, 3
	v_readlane_b32 s5, v252, 4
	s_and_b64 s[4:5], s[0:1], s[4:5]
	s_mov_b64 exec, s[4:5]
	s_cbranch_execz .LBB0_1463
	s_add_i32 s47, s33, 0x20160
	v_mov_b32_e32 v1, s47
	s_waitcnt vmcnt(0) expcnt(0) lgkmcnt(0)
	ds_read_b32 v3, v1
	s_add_i32 s33, s33, 0x20164
	v_mov_b32_e32 v1, s33
	ds_read_b32 v1, v1
	s_waitcnt lgkmcnt(1)
	v_cmp_ne_u32_e32 vcc, 0, v3
	s_cbranch_vccnz .LBB0_1427
	v_readlane_b32 s4, v252, 0
	v_readlane_b32 s5, v252, 1
	s_load_dwordx2 s[8:9], s[4:5], 0x4
	s_add_u32 s4, s2, 0x4200
	s_addc_u32 s5, s3, 0
	s_add_u32 s6, s2, 0x4400
	s_addc_u32 s7, s3, 0
	s_waitcnt lgkmcnt(0)
	s_mul_i32 s48, s8, s87
	s_add_u32 s8, s2, 0x4500
	s_mul_i32 s48, s48, s9
	s_addc_u32 s9, s3, 0
	s_add_u32 s10, s2, 0x4600
	s_addc_u32 s11, s3, 0
	s_add_u32 s12, s2, 0x4700
	s_addc_u32 s13, s3, 0
	s_add_u32 s14, s2, 0x4800
	s_addc_u32 s15, s3, 0
	s_add_u32 s16, s2, 0x4900
	s_addc_u32 s17, s3, 0
	s_add_u32 s18, s2, 0x4a00
	s_addc_u32 s19, s3, 0
	s_add_u32 s20, s2, 0x4b00
	s_addc_u32 s21, s3, 0
	s_add_u32 s22, s2, 0x4c00
	s_addc_u32 s23, s3, 0
	s_add_u32 s24, s2, 0x4d00
	s_addc_u32 s25, s3, 0
	s_add_u32 s26, s2, 0x4e00
	s_addc_u32 s27, s3, 0
	s_add_u32 s28, s2, 0x4f00
	s_addc_u32 s29, s3, 0
	s_add_u32 s30, s2, 0x5000
	s_addc_u32 s31, s3, 0
	s_add_u32 s34, s2, 0x5100
	s_addc_u32 s35, s3, 0
	s_add_u32 s36, s2, 0x5200
	s_addc_u32 s37, s3, 0
	s_add_u32 s38, s2, 0x5300
	s_addc_u32 s39, s3, 0
	s_mov_b32 s49, 1
	v_mov_b32_e32 v17, 0
	s_branch .LBB0_1415

.LBB0_1492:
	v_mov_b32_e32 v1, v0
	s_barrier
	s_mov_b32 s12, s87
	s_mov_b32 s13, s88
	s_mov_b32 s99, 37888
	s_mov_b32 s100, 0xb03f
	s_mov_b32 s101, 0
.Lconv1_entry:
	v_readfirstlane_b32 s0, v1
	s_nop 0
	s_ashr_i32 s18, s0, 6
	s_lshl_b32 s0, s13, 3
	s_add_i32 s14, s0, s18
	s_add_i32 s14, s14, s99
	s_add_i32 s0, s22, 0x202b8
	v_mov_b32_e32 v2, s0
	s_add_i32 s0, s22, 0x202bc
	ds_read_b32 v2, v2
	v_mov_b32_e32 v3, s0
	s_add_i32 s0, s22, 0x20230
	ds_read_b32 v3, v3
	v_mov_b32_e32 v4, s0
	s_add_i32 s0, s22, 0x20234
	ds_read_b32 v4, v4
	v_mov_b32_e32 v5, s0
	ds_read_b32 v5, v5
	s_add_i32 s0, s22, 0x20240
	s_add_i32 s5, s22, 0x20244
	v_mov_b32_e32 v6, s0
	s_waitcnt lgkmcnt(3)
	v_readfirstlane_b32 s0, v2
	v_mov_b32_e32 v2, s5
	s_add_i32 s5, s22, 0x20260
	ds_read_b32 v6, v6
	s_waitcnt lgkmcnt(3)
	v_readfirstlane_b32 s1, v3
	ds_read_b32 v2, v2
	v_mov_b32_e32 v3, s5
	s_add_i32 s5, s22, 0x20264
	s_waitcnt lgkmcnt(3)
	v_readfirstlane_b32 s2, v4
	ds_read_b32 v3, v3
	v_mov_b32_e32 v4, s5
	s_add_i32 s5, s22, 0x20268
	s_waitcnt lgkmcnt(3)
	v_readfirstlane_b32 s3, v5
	ds_read_b32 v4, v4
	v_mov_b32_e32 v5, s5
	ds_read_b32 v5, v5
	s_add_i32 s5, s22, 0x2026c
	s_add_i32 s8, s22, 0x20280
	s_waitcnt lgkmcnt(4)
	v_readfirstlane_b32 s4, v6
	v_mov_b32_e32 v6, s5
	s_waitcnt lgkmcnt(3)
	v_readfirstlane_b32 s5, v2
	v_mov_b32_e32 v2, s8
	s_add_i32 s8, s22, 0x20284
	s_waitcnt lgkmcnt(2)
	v_readfirstlane_b32 s15, v3
	v_mov_b32_e32 v3, s8
	s_add_i32 s8, s22, 0x20298
	s_waitcnt lgkmcnt(1)
	v_readfirstlane_b32 s16, v4
	v_mov_b32_e32 v4, s8
	s_add_i32 s8, s22, 0x2029c
	s_waitcnt lgkmcnt(0)
	v_readfirstlane_b32 s6, v5
	v_mov_b32_e32 v5, s8
	ds_read_b32 v6, v6
	ds_read_b32 v2, v2
	ds_read_b32 v3, v3
	ds_read_b32 v4, v4
	ds_read_b32 v5, v5
	s_waitcnt lgkmcnt(4)
	v_readfirstlane_b32 s7, v6
	s_waitcnt lgkmcnt(3)
	v_readfirstlane_b32 s8, v2
	s_waitcnt lgkmcnt(2)
	v_readfirstlane_b32 s9, v3
	s_waitcnt lgkmcnt(1)
	v_readfirstlane_b32 s10, v4
	s_cmp_gt_i32 s14, s100
	s_waitcnt lgkmcnt(0)
	v_readfirstlane_b32 s11, v5
	s_cbranch_scc1 .LBB0_1515
	s_lshl_b32 s18, s18, 14
	v_bfe_u32 v28, v1, 5, 1
	v_and_b32_e32 v26, 31, v1
	s_add_i32 s22, s22, s18
	v_lshlrev_b32_e32 v2, 2, v26
	v_mul_u32_u24_e32 v6, 0x84, v28
	v_add3_u32 v29, s22, v2, v6
	v_lshlrev_b32_e32 v6, 3, v1
	v_bfe_u32 v30, v1, 3, 3
	v_and_b32_e32 v6, 56, v6
	v_mov_b32_e32 v3, 0
	v_mul_u32_u24_e32 v10, 0x84, v6
	v_lshlrev_b32_e32 v11, 2, v30
	v_lshl_add_u64 v[4:5], s[10:11], 0, v[2:3]
	s_mov_b64 s[10:11], 0x2c00000
	v_lshlrev_b32_e32 v8, 1, v6
	v_mov_b32_e32 v9, v3
	v_add3_u32 v31, s22, v10, v11
	v_lshl_add_u64 v[10:11], s[8:9], 0, v[2:3]
	s_mov_b64 s[8:9], 0x5800000
	s_lshl_b32 s17, s12, 3
	v_lshl_add_u64 v[4:5], v[4:5], 0, s[10:11]
	v_mov_b32_e32 v7, v3
	v_lshl_add_u64 v[12:13], s[0:1], 0, v[8:9]
	s_mov_b64 s[10:11], 0xd000000
	v_lshl_add_u64 v[10:11], v[10:11], 0, s[8:9]
	s_mov_b64 s[8:9], 0xa400000
	v_lshl_add_u64 v[14:15], s[6:7], 0, v[2:3]
	s_mov_b64 s[6:7], 0x1000000
	v_lshl_add_u64 v[18:19], s[4:5], 0, v[2:3]
	s_mov_b64 s[4:5], 0x800000
	v_lshl_add_u64 v[22:23], s[2:3], 0, v[2:3]
	s_mov_b64 s[2:3], 0x9480000
	v_lshl_add_u64 v[8:9], v[12:13], 0, s[10:11]
	v_lshl_add_u64 v[12:13], v[12:13], 0, s[8:9]
	v_lshl_add_u64 v[14:15], v[14:15], 0, s[6:7]
	v_lshl_add_u64 v[24:25], s[0:1], 0, v[6:7]
	s_mov_b64 s[6:7], 0x9c00000
	s_add_u32 s8, s0, 0x8400000
	v_lshl_add_u64 v[18:19], v[18:19], 0, s[4:5]
	s_mov_b64 s[4:5], 0x8000000
	v_lshl_add_u64 v[22:23], v[22:23], 0, s[2:3]
	s_mov_b64 s[2:3], 0x3500000
	v_or_b32_e32 v32, 8, v30
	v_or_b32_e32 v33, 16, v30
	v_or_b32_e32 v34, 24, v30
	v_lshl_add_u64 v[16:17], v[24:25], 0, s[6:7]
	s_addc_u32 s9, s1, 0
	v_lshl_add_u64 v[20:21], v[24:25], 0, s[4:5]
	v_lshl_add_u64 v[24:25], v[24:25], 0, s[2:3]
	s_lshl_b32 s10, s14, 5
	s_lshl_b32 s11, s12, 8
	s_lshl_b32 s18, s14, 2
	s_lshl_b32 s19, s12, 5
	s_mov_b32 s3, 0
	s_movk_i32 s20, 0x4000
	s_mov_b32 s21, 0x8000
	s_mov_b32 s22, 0xc000
	s_mov_b32 s23, 0x10000
	s_mov_b32 s24, 0x14000
	s_mov_b32 s25, 0x18000
	s_mov_b32 s26, 0x1c000
	s_mov_b32 s27, 0x20000
	s_mov_b32 s28, 0x24000
	s_mov_b32 s29, 0x28000
	s_mov_b32 s30, 0x2c000
	s_mov_b32 s31, 0x30000
	s_mov_b32 s33, 0x34000
	s_mov_b32 s34, 0x38000
	s_mov_b32 s35, 0x3c000
	s_mov_b32 s36, 0x40000
	s_mov_b32 s37, 0x44000
	s_mov_b32 s38, 0x48000
	s_mov_b32 s39, 0x4c000
	s_mov_b32 s40, 0x50000
	s_mov_b32 s41, 0x54000
	s_mov_b32 s42, 0x58000
	s_mov_b32 s43, 0x5c000
	s_mov_b32 s44, 0x60000
	s_mov_b32 s45, 0x64000
	s_mov_b32 s46, 0x68000
	s_mov_b32 s47, 0x6c000
	s_mov_b32 s48, 0x70000
	s_mov_b32 s49, 0x74000
	s_mov_b32 s50, 0x78000
	s_mov_b32 s51, 0x7c000
	s_movk_i32 s52, 0x7fff
	s_mov_b32 s53, 0xffff0000
	s_mov_b32 s54, 0x16000
	s_mov_b32 s55, 0x42000
	s_mov_b32 s56, 0x6e000
	s_mov_b32 s57, 0x84000
	s_mov_b32 s58, 0x9a000
	s_mov_b32 s59, 0xb0000
	s_mov_b32 s60, 0xc6000
	s_mov_b32 s61, 0xdc000
	s_mov_b32 s62, 0xf2000
	s_mov_b32 s63, 0x108000
	s_mov_b32 s64, 0x11e000
	s_mov_b32 s65, 0x134000
	s_mov_b32 s66, 0x14a000
	s_mov_b32 s67, 0x160000
	s_mov_b32 s68, 0x176000
	s_mov_b32 s69, 0x18c000
	s_mov_b32 s70, 0x1a2000
	s_mov_b32 s71, 0x1b8000
	s_mov_b32 s72, 0x1ce000
	s_mov_b32 s73, 0x1e4000
	s_mov_b32 s74, 0x1fa000
	s_mov_b32 s75, 0x210000
	s_mov_b32 s76, 0x226000
	s_mov_b32 s77, 0x23c000
	s_mov_b32 s78, 0x252000
	s_mov_b32 s79, 0x268000
	s_mov_b32 s80, 0x27e000
	s_mov_b32 s81, 0x294000
	s_mov_b32 s82, 0x2aa000
	v_lshlrev_b32_e32 v26, 2, v26
	s_mov_b32 s83, 0x12900
	v_add_u32_e32 v35, 0x400, v29
	v_add_u32_e32 v36, 0x800, v29
	v_add_u32_e32 v37, 0xc00, v29
	v_add_u32_e32 v38, 0x1000, v29
	v_add_u32_e32 v39, 0x1400, v29
	v_add_u32_e32 v40, 0x1800, v29
	v_add_u32_e32 v41, 0x1c00, v29
	s_branch .LBB0_1495
.LBB0_1494:
	s_add_i32 s14, s14, s17
	s_add_i32 s10, s10, s11
	s_add_i32 s18, s18, s19
	s_cmp_gt_i32 s14, s100
	s_cbranch_scc1 .LBB0_1515
.LBB0_1495:
	s_cmpk_gt_i32 s14, 0x4a3f
	s_mov_b64 s[4:5], -1
	s_cbranch_scc0 .LBB0_1513
	s_cmpk_gt_u32 s14, 0x4e3f
	s_cbranch_scc0 .LBB0_1510
	s_cmpk_gt_u32 s14, 0x663f
	s_cbranch_scc0 .LBB0_1507
	s_cmpk_gt_u32 s14, 0x6e3f
	s_cbranch_scc0 .LBB0_1504
	s_cmpk_gt_u32 s14, 0x9a3f
	s_cbranch_scc0 .LBB0_1501
	s_add_i32 s2, s14, 0xffff65c0
	s_and_b32 s5, s2, 0x1fc0
	s_add_i32 s2, s10, 0xffecb800
	s_and_b32 s4, s2, 0x7e0
	v_or_b32_e32 v2, s5, v28
	s_lshl_b32 s2, s4, 2
	v_lshl_add_u64 v[42:43], v[4:5], 0, s[2:3]
	v_lshlrev_b32_e32 v2, 13, v2
	v_lshl_add_u64 v[42:43], v[42:43], 0, v[2:3]
	v_add_co_u32_e32 v44, vcc, 0x4000, v42
	s_lshl_b32 s2, s5, 1
	s_nop 0
	v_addc_co_u32_e32 v45, vcc, 0, v43, vcc
	v_add_co_u32_e32 v46, vcc, 0x8000, v42
	s_nop 1
	v_addc_co_u32_e32 v47, vcc, 0, v43, vcc
	v_add_co_u32_e32 v48, vcc, 0xc000, v42
	s_nop 1
	v_addc_co_u32_e32 v49, vcc, 0, v43, vcc
	v_add_co_u32_e32 v50, vcc, 0x10000, v42
	s_nop 1
	v_addc_co_u32_e32 v51, vcc, 0, v43, vcc
	v_add_co_u32_e32 v52, vcc, 0x14000, v42
	s_nop 1
	v_addc_co_u32_e32 v53, vcc, 0, v43, vcc
	v_add_co_u32_e32 v54, vcc, 0x18000, v42
	s_nop 1
	v_addc_co_u32_e32 v55, vcc, 0, v43, vcc
	v_add_co_u32_e32 v56, vcc, 0x1c000, v42
	s_nop 1
	v_addc_co_u32_e32 v57, vcc, 0, v43, vcc
	global_load_dword v2, v[42:43], off nt
	global_load_dword v27, v[44:45], off nt
	global_load_dword v60, v[46:47], off nt
	global_load_dword v61, v[48:49], off nt
	global_load_dword v62, v[50:51], off nt
	global_load_dword v63, v[52:53], off nt
	global_load_dword v64, v[54:55], off nt
	global_load_dword v65, v[56:57], off nt
	v_add_co_u32_e32 v44, vcc, 0x20000, v42
	s_nop 1
	v_addc_co_u32_e32 v45, vcc, 0, v43, vcc
	v_add_co_u32_e32 v46, vcc, 0x24000, v42
	s_nop 1
	v_addc_co_u32_e32 v47, vcc, 0, v43, vcc
	v_add_co_u32_e32 v48, vcc, 0x28000, v42
	s_nop 1
	v_addc_co_u32_e32 v49, vcc, 0, v43, vcc
	v_add_co_u32_e32 v50, vcc, 0x2c000, v42
	s_nop 1
	v_addc_co_u32_e32 v51, vcc, 0, v43, vcc
	v_add_co_u32_e32 v52, vcc, 0x30000, v42
	s_nop 1
	v_addc_co_u32_e32 v53, vcc, 0, v43, vcc
	v_add_co_u32_e32 v54, vcc, 0x34000, v42
	s_nop 1
	v_addc_co_u32_e32 v55, vcc, 0, v43, vcc
	v_add_co_u32_e32 v56, vcc, 0x38000, v42
	s_nop 1
	v_addc_co_u32_e32 v57, vcc, 0, v43, vcc
	v_add_co_u32_e32 v58, vcc, 0x3c000, v42
	s_nop 1
	v_addc_co_u32_e32 v59, vcc, 0, v43, vcc
	global_load_dword v66, v[44:45], off nt
	global_load_dword v67, v[46:47], off nt
	global_load_dword v68, v[48:49], off nt
	global_load_dword v69, v[50:51], off nt
	global_load_dword v70, v[52:53], off nt
	global_load_dword v71, v[54:55], off nt
	global_load_dword v72, v[56:57], off nt
	global_load_dword v73, v[58:59], off nt
	v_add_co_u32_e32 v44, vcc, 0x40000, v42
	s_nop 1
	v_addc_co_u32_e32 v45, vcc, 0, v43, vcc
	v_add_co_u32_e32 v46, vcc, 0x44000, v42
	s_nop 1
	v_addc_co_u32_e32 v47, vcc, 0, v43, vcc
	v_add_co_u32_e32 v48, vcc, 0x48000, v42
	s_nop 1
	v_addc_co_u32_e32 v49, vcc, 0, v43, vcc
	v_add_co_u32_e32 v50, vcc, 0x4c000, v42
	s_nop 1
	v_addc_co_u32_e32 v51, vcc, 0, v43, vcc
	v_add_co_u32_e32 v52, vcc, 0x50000, v42
	s_nop 1
	v_addc_co_u32_e32 v53, vcc, 0, v43, vcc
	v_add_co_u32_e32 v54, vcc, 0x54000, v42
	s_nop 1
	v_addc_co_u32_e32 v55, vcc, 0, v43, vcc
	v_add_co_u32_e32 v56, vcc, 0x58000, v42
	s_nop 1
	v_addc_co_u32_e32 v57, vcc, 0, v43, vcc
	v_add_co_u32_e32 v58, vcc, 0x5c000, v42
	s_nop 1
	v_addc_co_u32_e32 v59, vcc, 0, v43, vcc
	global_load_dword v74, v[44:45], off nt
	global_load_dword v75, v[46:47], off nt
	global_load_dword v76, v[48:49], off nt
	global_load_dword v77, v[50:51], off nt
	global_load_dword v78, v[52:53], off nt
	global_load_dword v79, v[54:55], off nt
	global_load_dword v80, v[56:57], off nt
	s_nop 0
	global_load_dword v58, v[58:59], off nt
	v_add_co_u32_e32 v44, vcc, 0x60000, v42
	s_nop 1
	v_addc_co_u32_e32 v45, vcc, 0, v43, vcc
	v_add_co_u32_e32 v46, vcc, 0x64000, v42
	s_nop 1
	v_addc_co_u32_e32 v47, vcc, 0, v43, vcc
	v_add_co_u32_e32 v48, vcc, 0x68000, v42
	s_nop 1
	v_addc_co_u32_e32 v49, vcc, 0, v43, vcc
	v_add_co_u32_e32 v50, vcc, 0x6c000, v42
	s_nop 1
	v_addc_co_u32_e32 v51, vcc, 0, v43, vcc
	v_add_co_u32_e32 v52, vcc, 0x70000, v42
	s_nop 1
	v_addc_co_u32_e32 v53, vcc, 0, v43, vcc
	v_add_co_u32_e32 v54, vcc, 0x74000, v42
	s_nop 1
	v_addc_co_u32_e32 v55, vcc, 0, v43, vcc
	v_add_co_u32_e32 v56, vcc, 0x78000, v42
	s_nop 1
	v_addc_co_u32_e32 v57, vcc, 0, v43, vcc
	v_add_co_u32_e32 v42, vcc, 0x7c000, v42
	s_nop 1
	v_addc_co_u32_e32 v43, vcc, 0, v43, vcc
	global_load_dword v44, v[44:45], off nt
	s_nop 0
	global_load_dword v45, v[46:47], off nt
	s_nop 0
	global_load_dword v46, v[48:49], off nt
	global_load_dword v47, v[50:51], off nt
	s_nop 0
	global_load_dword v48, v[52:53], off nt
	global_load_dword v49, v[54:55], off nt
	global_load_dword v50, v[56:57], off nt
	s_nop 0
	global_load_dword v42, v[42:43], off nt
	s_waitcnt vmcnt(30)
	ds_write2_b32 v29, v2, v27 offset1:66
	s_waitcnt vmcnt(28)
	ds_write2_b32 v29, v60, v61 offset0:132 offset1:198
	s_waitcnt vmcnt(26)
	ds_write2_b32 v35, v62, v63 offset0:8 offset1:74
	s_waitcnt vmcnt(24)
	ds_write2_b32 v35, v64, v65 offset0:140 offset1:206
	s_waitcnt vmcnt(22)
	ds_write2_b32 v36, v66, v67 offset0:16 offset1:82
	s_waitcnt vmcnt(20)
	ds_write2_b32 v36, v68, v69 offset0:148 offset1:214
	s_waitcnt vmcnt(18)
	ds_write2_b32 v37, v70, v71 offset0:24 offset1:90
	s_waitcnt vmcnt(16)
	ds_write2_b32 v37, v72, v73 offset0:156 offset1:222
	s_waitcnt vmcnt(14)
	ds_write2_b32 v38, v74, v75 offset0:32 offset1:98
	s_waitcnt vmcnt(12)
	ds_write2_b32 v38, v76, v77 offset0:164 offset1:230
	s_waitcnt vmcnt(10)
	ds_write2_b32 v39, v78, v79 offset0:40 offset1:106
	s_waitcnt vmcnt(8)
	ds_write2_b32 v39, v80, v58 offset0:172 offset1:238
	s_waitcnt vmcnt(6)
	ds_write2_b32 v40, v44, v45 offset0:48 offset1:114
	s_waitcnt vmcnt(4)
	ds_write2_b32 v40, v46, v47 offset0:180 offset1:246
	s_waitcnt vmcnt(2)
	ds_write2_b32 v41, v48, v49 offset0:56 offset1:122
	s_waitcnt vmcnt(0)
	ds_write2_b32 v41, v50, v42 offset0:188 offset1:254
	s_waitcnt lgkmcnt(0)
	ds_read2_b32 v[46:47], v31 offset1:8
	ds_read2_b32 v[50:51], v31 offset0:33 offset1:41
	ds_read2_b32 v[52:53], v31 offset0:66 offset1:74
	ds_read2_b32 v[54:55], v31 offset0:99 offset1:107
	ds_read2_b32 v[56:57], v31 offset0:132 offset1:140
	s_waitcnt lgkmcnt(4)
	v_bfe_u32 v2, v46, 16, 1
	v_add3_u32 v2, v46, v2, s52
	s_waitcnt lgkmcnt(3)
	v_bfe_u32 v27, v50, 16, 1
	v_lshrrev_b32_e32 v2, 16, v2
	v_add3_u32 v27, v50, v27, s52
	ds_read2_b32 v[58:59], v31 offset0:165 offset1:173
	v_and_or_b32 v42, v27, s53, v2
	s_waitcnt lgkmcnt(3)
	v_bfe_u32 v2, v52, 16, 1
	v_add3_u32 v2, v52, v2, s52
	s_waitcnt lgkmcnt(2)
	v_bfe_u32 v27, v54, 16, 1
	ds_read2_b32 v[60:61], v31 offset0:198 offset1:206
	v_lshrrev_b32_e32 v2, 16, v2
	v_add3_u32 v27, v54, v27, s52
	ds_read2_b32 v[62:63], v31 offset0:231 offset1:239
	v_and_or_b32 v43, v27, s53, v2
	s_waitcnt lgkmcnt(3)
	v_bfe_u32 v2, v56, 16, 1
	v_add3_u32 v2, v56, v2, s52
	s_waitcnt lgkmcnt(2)
	v_bfe_u32 v27, v58, 16, 1
	v_lshrrev_b32_e32 v2, 16, v2
	v_add3_u32 v27, v58, v27, s52
	v_and_or_b32 v44, v27, s53, v2
	s_waitcnt lgkmcnt(1)
	v_bfe_u32 v2, v60, 16, 1
	v_add3_u32 v2, v60, v2, s52
	s_waitcnt lgkmcnt(0)
	v_bfe_u32 v27, v62, 16, 1
	v_lshrrev_b32_e32 v2, 16, v2
	v_add3_u32 v27, v62, v27, s52
	v_and_or_b32 v45, v27, s53, v2
	v_or_b32_e32 v2, s4, v30
	v_lshl_add_u64 v[48:49], v[8:9], 0, s[2:3]
	v_mul_u32_u24_e32 v2, 0x2c00, v2
	v_lshl_add_u64 v[64:65], v[48:49], 0, v[2:3]
	v_bfe_u32 v2, v47, 16, 1
	v_add3_u32 v2, v47, v2, s52
	v_bfe_u32 v27, v51, 16, 1
	v_lshrrev_b32_e32 v2, 16, v2
	v_add3_u32 v27, v51, v27, s52
	global_store_dwordx4 v[64:65], v[42:45], off nt
	ds_read2_b32 v[46:47], v31 offset0:16 offset1:24
	s_nop 0
	v_and_or_b32 v42, v27, s53, v2
	v_bfe_u32 v2, v53, 16, 1
	v_add3_u32 v2, v53, v2, s52
	v_bfe_u32 v27, v55, 16, 1
	v_lshrrev_b32_e32 v2, 16, v2
	v_add3_u32 v27, v55, v27, s52
	v_and_or_b32 v43, v27, s53, v2
	v_bfe_u32 v2, v57, 16, 1
	v_add3_u32 v2, v57, v2, s52
	v_bfe_u32 v27, v59, 16, 1
	v_lshrrev_b32_e32 v2, 16, v2
	v_add3_u32 v27, v59, v27, s52
	v_and_or_b32 v44, v27, s53, v2
	v_bfe_u32 v2, v61, 16, 1
	v_add3_u32 v2, v61, v2, s52
	v_bfe_u32 v27, v63, 16, 1
	v_lshrrev_b32_e32 v2, 16, v2
	v_add3_u32 v27, v63, v27, s52
	v_and_or_b32 v45, v27, s53, v2
	v_or_b32_e32 v2, s4, v32
	v_mul_u32_u24_e32 v2, 0x2c00, v2
	v_lshl_add_u64 v[50:51], v[48:49], 0, v[2:3]
	global_store_dwordx4 v[50:51], v[42:45], off nt
	ds_read2_b32 v[50:51], v31 offset0:49 offset1:57
	ds_read2_b32 v[52:53], v31 offset0:82 offset1:90
	ds_read2_b32 v[54:55], v31 offset0:115 offset1:123
	s_waitcnt lgkmcnt(3)
	v_bfe_u32 v2, v46, 16, 1
	v_add3_u32 v2, v46, v2, s52
	s_waitcnt lgkmcnt(2)
	v_bfe_u32 v27, v50, 16, 1
	ds_read2_b32 v[56:57], v31 offset0:148 offset1:156
	v_lshrrev_b32_e32 v2, 16, v2
	v_add3_u32 v27, v50, v27, s52
	ds_read2_b32 v[58:59], v31 offset0:181 offset1:189
	v_and_or_b32 v42, v27, s53, v2
	s_waitcnt lgkmcnt(3)
	v_bfe_u32 v2, v52, 16, 1
	v_add3_u32 v2, v52, v2, s52
	s_waitcnt lgkmcnt(2)
	v_bfe_u32 v27, v54, 16, 1
	ds_read2_b32 v[60:61], v31 offset0:214 offset1:222
	v_lshrrev_b32_e32 v2, 16, v2
	v_add3_u32 v27, v54, v27, s52
	ds_read2_b32 v[62:63], v31 offset0:247 offset1:255
	v_and_or_b32 v43, v27, s53, v2
	s_waitcnt lgkmcnt(3)
	v_bfe_u32 v2, v56, 16, 1
	v_add3_u32 v2, v56, v2, s52
	s_waitcnt lgkmcnt(2)
	v_bfe_u32 v27, v58, 16, 1
	v_lshrrev_b32_e32 v2, 16, v2
	v_add3_u32 v27, v58, v27, s52
	v_and_or_b32 v44, v27, s53, v2
	s_waitcnt lgkmcnt(1)
	v_bfe_u32 v2, v60, 16, 1
	v_add3_u32 v2, v60, v2, s52
	s_waitcnt lgkmcnt(0)
	v_bfe_u32 v27, v62, 16, 1
	v_lshrrev_b32_e32 v2, 16, v2
	v_add3_u32 v27, v62, v27, s52
	v_and_or_b32 v45, v27, s53, v2
	v_or_b32_e32 v2, s4, v33
	v_mul_u32_u24_e32 v2, 0x2c00, v2
	v_lshl_add_u64 v[64:65], v[48:49], 0, v[2:3]
	v_bfe_u32 v2, v47, 16, 1
	v_add3_u32 v2, v47, v2, s52
	v_bfe_u32 v27, v51, 16, 1
	v_lshrrev_b32_e32 v2, 16, v2
	v_add3_u32 v27, v51, v27, s52
	global_store_dwordx4 v[64:65], v[42:45], off nt
	s_nop 1
	v_and_or_b32 v42, v27, s53, v2
	v_bfe_u32 v2, v53, 16, 1
	v_add3_u32 v2, v53, v2, s52
	v_bfe_u32 v27, v55, 16, 1
	v_lshrrev_b32_e32 v2, 16, v2
	v_add3_u32 v27, v55, v27, s52
	v_and_or_b32 v43, v27, s53, v2
	v_bfe_u32 v2, v57, 16, 1
	v_add3_u32 v2, v57, v2, s52
	v_bfe_u32 v27, v59, 16, 1
	v_lshrrev_b32_e32 v2, 16, v2
	v_add3_u32 v27, v59, v27, s52
	v_and_or_b32 v44, v27, s53, v2
	v_bfe_u32 v2, v61, 16, 1
	v_add3_u32 v2, v61, v2, s52
	v_bfe_u32 v27, v63, 16, 1
	v_lshrrev_b32_e32 v2, 16, v2
	v_add3_u32 v27, v63, v27, s52
	v_and_or_b32 v45, v27, s53, v2
	v_or_b32_e32 v2, s4, v34
	v_mul_u32_u24_e32 v2, 0x2c00, v2
	v_lshl_add_u64 v[46:47], v[48:49], 0, v[2:3]
	global_store_dwordx4 v[46:47], v[42:45], off nt
	s_waitcnt lgkmcnt(0)
	s_mov_b64 s[4:5], 0
.LBB0_1501:
	s_andn2_b64 vcc, exec, s[4:5]
	s_cbranch_vccnz .LBB0_1503
	s_add_i32 s2, s14, 0x91c0
	s_and_b32 s4, s2, 0xffff
	s_mul_i32 s4, s4, 0xba2f
	s_lshr_b32 s4, s4, 24
	s_mul_i32 s5, s4, 0x160
	s_sub_i32 s2, s2, s5
	s_lshl_b32 s5, s2, 5
	s_and_b32 s6, s5, 0xffe0
	s_and_b32 s2, s2, 0xffff
	s_add_i32 s5, s6, 0xffffea00
	s_cmpk_gt_u32 s2, 0xaf
	s_cselect_b32 s7, s5, s6
	s_cselect_b32 s5, 0x80, 0
	v_lshl_or_b32 v2, s4, 6, v28
	s_lshl_b32 s2, s6, 2
	v_lshl_add_u64 v[42:43], v[10:11], 0, s[2:3]
	v_mul_u32_u24_e32 v2, 0xb000, v2
	v_lshl_add_u64 v[42:43], v[42:43], 0, v[2:3]
	v_add_co_u32_e32 v44, vcc, s54, v42
	s_lshl_b32 s2, s7, 1
	s_nop 0
	v_addc_co_u32_e32 v45, vcc, 0, v43, vcc
	v_add_co_u32_e32 v46, vcc, s30, v42
	s_and_b32 s6, s7, 0x60
	s_nop 0
	v_addc_co_u32_e32 v47, vcc, 0, v43, vcc
	v_add_co_u32_e32 v48, vcc, s55, v42
	s_and_b32 s2, s2, 0xffffff00
	s_nop 0
	v_addc_co_u32_e32 v49, vcc, 0, v43, vcc
	v_add_co_u32_e32 v50, vcc, s42, v42
	s_or_b32 s5, s6, s5
	s_nop 0
	v_addc_co_u32_e32 v51, vcc, 0, v43, vcc
	v_add_co_u32_e32 v52, vcc, s56, v42
	s_or_b32 s5, s5, s2
	s_nop 0
	v_addc_co_u32_e32 v53, vcc, 0, v43, vcc
	v_add_co_u32_e32 v54, vcc, s57, v42
	s_lshl_b32 s2, s4, 7
	s_nop 0
	v_addc_co_u32_e32 v55, vcc, 0, v43, vcc
	v_add_co_u32_e32 v56, vcc, s58, v42
	s_nop 1
	v_addc_co_u32_e32 v57, vcc, 0, v43, vcc
	global_load_dword v2, v[42:43], off nt
	global_load_dword v27, v[44:45], off nt
	global_load_dword v60, v[46:47], off nt
	global_load_dword v61, v[48:49], off nt
	global_load_dword v62, v[50:51], off nt
	global_load_dword v63, v[52:53], off nt
	global_load_dword v64, v[54:55], off nt
	global_load_dword v65, v[56:57], off nt
	v_add_co_u32_e32 v44, vcc, s59, v42
	s_nop 1
	v_addc_co_u32_e32 v45, vcc, 0, v43, vcc
	v_add_co_u32_e32 v46, vcc, s60, v42
	s_nop 1
	v_addc_co_u32_e32 v47, vcc, 0, v43, vcc
	v_add_co_u32_e32 v48, vcc, s61, v42
	s_nop 1
	v_addc_co_u32_e32 v49, vcc, 0, v43, vcc
	v_add_co_u32_e32 v50, vcc, s62, v42
	s_nop 1
	v_addc_co_u32_e32 v51, vcc, 0, v43, vcc
	v_add_co_u32_e32 v52, vcc, s63, v42
	s_nop 1
	v_addc_co_u32_e32 v53, vcc, 0, v43, vcc
	v_add_co_u32_e32 v54, vcc, s64, v42
	s_nop 1
	v_addc_co_u32_e32 v55, vcc, 0, v43, vcc
	v_add_co_u32_e32 v56, vcc, s65, v42
	s_nop 1
	v_addc_co_u32_e32 v57, vcc, 0, v43, vcc
	v_add_co_u32_e32 v58, vcc, s66, v42
	s_nop 1
	v_addc_co_u32_e32 v59, vcc, 0, v43, vcc
	global_load_dword v66, v[44:45], off nt
	global_load_dword v67, v[46:47], off nt
	global_load_dword v68, v[48:49], off nt
	global_load_dword v69, v[50:51], off nt
	global_load_dword v70, v[52:53], off nt
	global_load_dword v71, v[54:55], off nt
	global_load_dword v72, v[56:57], off nt
	global_load_dword v73, v[58:59], off nt
	v_add_co_u32_e32 v44, vcc, s67, v42
	s_nop 1
	v_addc_co_u32_e32 v45, vcc, 0, v43, vcc
	v_add_co_u32_e32 v46, vcc, s68, v42
	s_nop 1
	v_addc_co_u32_e32 v47, vcc, 0, v43, vcc
	v_add_co_u32_e32 v48, vcc, s69, v42
	s_nop 1
	v_addc_co_u32_e32 v49, vcc, 0, v43, vcc
	v_add_co_u32_e32 v50, vcc, s70, v42
	s_nop 1
	v_addc_co_u32_e32 v51, vcc, 0, v43, vcc
	v_add_co_u32_e32 v52, vcc, s71, v42
	s_nop 1
	v_addc_co_u32_e32 v53, vcc, 0, v43, vcc
	v_add_co_u32_e32 v54, vcc, s72, v42
	s_nop 1
	v_addc_co_u32_e32 v55, vcc, 0, v43, vcc
	v_add_co_u32_e32 v56, vcc, s73, v42
	s_nop 1
	v_addc_co_u32_e32 v57, vcc, 0, v43, vcc
	v_add_co_u32_e32 v58, vcc, s74, v42
	s_nop 1
	v_addc_co_u32_e32 v59, vcc, 0, v43, vcc
	global_load_dword v74, v[44:45], off nt
	global_load_dword v75, v[46:47], off nt
	global_load_dword v76, v[48:49], off nt
	global_load_dword v77, v[50:51], off nt
	global_load_dword v78, v[52:53], off nt
	global_load_dword v79, v[54:55], off nt
	global_load_dword v80, v[56:57], off nt
	s_nop 0
	global_load_dword v58, v[58:59], off nt
	v_add_co_u32_e32 v44, vcc, s75, v42
	s_nop 1
	v_addc_co_u32_e32 v45, vcc, 0, v43, vcc
	v_add_co_u32_e32 v46, vcc, s76, v42
	s_nop 1
	v_addc_co_u32_e32 v47, vcc, 0, v43, vcc
	v_add_co_u32_e32 v48, vcc, s77, v42
	s_nop 1
	v_addc_co_u32_e32 v49, vcc, 0, v43, vcc
	v_add_co_u32_e32 v50, vcc, s78, v42
	s_nop 1
	v_addc_co_u32_e32 v51, vcc, 0, v43, vcc
	v_add_co_u32_e32 v52, vcc, s79, v42
	s_nop 1
	v_addc_co_u32_e32 v53, vcc, 0, v43, vcc
	v_add_co_u32_e32 v54, vcc, s80, v42
	s_nop 1
	v_addc_co_u32_e32 v55, vcc, 0, v43, vcc
	v_add_co_u32_e32 v56, vcc, s81, v42
	s_nop 1
	v_addc_co_u32_e32 v57, vcc, 0, v43, vcc
	v_add_co_u32_e32 v42, vcc, s82, v42
	s_nop 1
	v_addc_co_u32_e32 v43, vcc, 0, v43, vcc
	global_load_dword v44, v[44:45], off nt
	s_nop 0
	global_load_dword v45, v[46:47], off nt
	s_nop 0
	global_load_dword v46, v[48:49], off nt
	global_load_dword v47, v[50:51], off nt
	s_nop 0
	global_load_dword v48, v[52:53], off nt
	global_load_dword v49, v[54:55], off nt
	global_load_dword v50, v[56:57], off nt
	s_nop 0
	global_load_dword v42, v[42:43], off nt
	s_waitcnt vmcnt(30)
	ds_write2_b32 v29, v2, v27 offset1:66
	s_waitcnt vmcnt(28)
	ds_write2_b32 v29, v60, v61 offset0:132 offset1:198
	s_waitcnt vmcnt(26)
	ds_write2_b32 v35, v62, v63 offset0:8 offset1:74
	s_waitcnt vmcnt(24)
	ds_write2_b32 v35, v64, v65 offset0:140 offset1:206
	s_waitcnt vmcnt(22)
	ds_write2_b32 v36, v66, v67 offset0:16 offset1:82
	s_waitcnt vmcnt(20)
	ds_write2_b32 v36, v68, v69 offset0:148 offset1:214
	s_waitcnt vmcnt(18)
	ds_write2_b32 v37, v70, v71 offset0:24 offset1:90
	s_waitcnt vmcnt(16)
	ds_write2_b32 v37, v72, v73 offset0:156 offset1:222
	s_waitcnt vmcnt(14)
	ds_write2_b32 v38, v74, v75 offset0:32 offset1:98
	s_waitcnt vmcnt(12)
	ds_write2_b32 v38, v76, v77 offset0:164 offset1:230
	s_waitcnt vmcnt(10)
	ds_write2_b32 v39, v78, v79 offset0:40 offset1:106
	s_waitcnt vmcnt(8)
	ds_write2_b32 v39, v80, v58 offset0:172 offset1:238
	s_waitcnt vmcnt(6)
	ds_write2_b32 v40, v44, v45 offset0:48 offset1:114
	s_waitcnt vmcnt(4)
	ds_write2_b32 v40, v46, v47 offset0:180 offset1:246
	s_waitcnt vmcnt(2)
	ds_write2_b32 v41, v48, v49 offset0:56 offset1:122
	s_waitcnt vmcnt(0)
	ds_write2_b32 v41, v50, v42 offset0:188 offset1:254
	s_waitcnt lgkmcnt(0)
	ds_read2_b32 v[46:47], v31 offset1:8
	ds_read2_b32 v[50:51], v31 offset0:33 offset1:41
	ds_read2_b32 v[52:53], v31 offset0:66 offset1:74
	ds_read2_b32 v[54:55], v31 offset0:99 offset1:107
	ds_read2_b32 v[56:57], v31 offset0:132 offset1:140
	s_waitcnt lgkmcnt(4)
	v_bfe_u32 v2, v46, 16, 1
	v_add3_u32 v2, v46, v2, s52
	s_waitcnt lgkmcnt(3)
	v_bfe_u32 v27, v50, 16, 1
	v_lshrrev_b32_e32 v2, 16, v2
	v_add3_u32 v27, v50, v27, s52
	ds_read2_b32 v[58:59], v31 offset0:165 offset1:173
	v_and_or_b32 v42, v27, s53, v2
	s_waitcnt lgkmcnt(3)
	v_bfe_u32 v2, v52, 16, 1
	v_add3_u32 v2, v52, v2, s52
	s_waitcnt lgkmcnt(2)
	v_bfe_u32 v27, v54, 16, 1
	ds_read2_b32 v[60:61], v31 offset0:198 offset1:206
	v_lshrrev_b32_e32 v2, 16, v2
	v_add3_u32 v27, v54, v27, s52
	ds_read2_b32 v[62:63], v31 offset0:231 offset1:239
	v_and_or_b32 v43, v27, s53, v2
	s_waitcnt lgkmcnt(3)
	v_bfe_u32 v2, v56, 16, 1
	v_add3_u32 v2, v56, v2, s52
	s_waitcnt lgkmcnt(2)
	v_bfe_u32 v27, v58, 16, 1
	v_lshrrev_b32_e32 v2, 16, v2
	v_add3_u32 v27, v58, v27, s52
	v_and_or_b32 v44, v27, s53, v2
	s_waitcnt lgkmcnt(1)
	v_bfe_u32 v2, v60, 16, 1
	v_add3_u32 v2, v60, v2, s52
	s_waitcnt lgkmcnt(0)
	v_bfe_u32 v27, v62, 16, 1
	v_lshrrev_b32_e32 v2, 16, v2
	v_add3_u32 v27, v62, v27, s52
	v_or_b32_e32 v64, s5, v30
	v_and_or_b32 v45, v27, s53, v2
	v_ashrrev_i32_e32 v65, 31, v64
	v_bfe_u32 v2, v47, 16, 1
	v_lshl_add_u64 v[48:49], v[12:13], 0, s[2:3]
	v_lshlrev_b64 v[64:65], 12, v[64:65]
	v_add3_u32 v2, v47, v2, s52
	v_bfe_u32 v27, v51, 16, 1
	v_lshl_add_u64 v[64:65], v[48:49], 0, v[64:65]
	v_lshrrev_b32_e32 v2, 16, v2
	v_add3_u32 v27, v51, v27, s52
	global_store_dwordx4 v[64:65], v[42:45], off nt
	v_or_b32_e32 v46, s5, v32
	v_ashrrev_i32_e32 v47, 31, v46
	v_and_or_b32 v42, v27, s53, v2
	v_bfe_u32 v2, v53, 16, 1
	v_add3_u32 v2, v53, v2, s52
	v_bfe_u32 v27, v55, 16, 1
	v_lshrrev_b32_e32 v2, 16, v2
	v_add3_u32 v27, v55, v27, s52
	v_and_or_b32 v43, v27, s53, v2
	v_bfe_u32 v2, v57, 16, 1
	v_add3_u32 v2, v57, v2, s52
	v_bfe_u32 v27, v59, 16, 1
	v_lshrrev_b32_e32 v2, 16, v2
	v_add3_u32 v27, v59, v27, s52
	v_and_or_b32 v44, v27, s53, v2
	v_bfe_u32 v2, v61, 16, 1
	v_add3_u32 v2, v61, v2, s52
	v_bfe_u32 v27, v63, 16, 1
	v_lshrrev_b32_e32 v2, 16, v2
	v_add3_u32 v27, v63, v27, s52
	v_lshlrev_b64 v[46:47], 12, v[46:47]
	v_and_or_b32 v45, v27, s53, v2
	ds_read2_b32 v[50:51], v31 offset0:16 offset1:24
	v_lshl_add_u64 v[46:47], v[48:49], 0, v[46:47]
	global_store_dwordx4 v[46:47], v[42:45], off nt
	ds_read2_b32 v[46:47], v31 offset0:49 offset1:57
	ds_read2_b32 v[52:53], v31 offset0:82 offset1:90
	ds_read2_b32 v[54:55], v31 offset0:115 offset1:123
	s_waitcnt lgkmcnt(3)
	v_bfe_u32 v2, v50, 16, 1
	v_add3_u32 v2, v50, v2, s52
	s_waitcnt lgkmcnt(2)
	v_bfe_u32 v27, v46, 16, 1
	ds_read2_b32 v[56:57], v31 offset0:148 offset1:156
	v_lshrrev_b32_e32 v2, 16, v2
	v_add3_u32 v27, v46, v27, s52
	ds_read2_b32 v[58:59], v31 offset0:181 offset1:189
	v_and_or_b32 v42, v27, s53, v2
	s_waitcnt lgkmcnt(3)
	v_bfe_u32 v2, v52, 16, 1
	v_add3_u32 v2, v52, v2, s52
	s_waitcnt lgkmcnt(2)
	v_bfe_u32 v27, v54, 16, 1
	ds_read2_b32 v[60:61], v31 offset0:214 offset1:222
	v_lshrrev_b32_e32 v2, 16, v2
	v_add3_u32 v27, v54, v27, s52
	ds_read2_b32 v[62:63], v31 offset0:247 offset1:255
	v_and_or_b32 v43, v27, s53, v2
	s_waitcnt lgkmcnt(3)
	v_bfe_u32 v2, v56, 16, 1
	v_add3_u32 v2, v56, v2, s52
	s_waitcnt lgkmcnt(2)
	v_bfe_u32 v27, v58, 16, 1
	v_lshrrev_b32_e32 v2, 16, v2
	v_add3_u32 v27, v58, v27, s52
	v_and_or_b32 v44, v27, s53, v2
	s_waitcnt lgkmcnt(1)
	v_bfe_u32 v2, v60, 16, 1
	v_add3_u32 v2, v60, v2, s52
	s_waitcnt lgkmcnt(0)
	v_bfe_u32 v27, v62, 16, 1
	v_lshrrev_b32_e32 v2, 16, v2
	v_add3_u32 v27, v62, v27, s52
	v_or_b32_e32 v64, s5, v33
	v_and_or_b32 v45, v27, s53, v2
	v_ashrrev_i32_e32 v65, 31, v64
	v_bfe_u32 v2, v51, 16, 1
	v_lshlrev_b64 v[64:65], 12, v[64:65]
	v_add3_u32 v2, v51, v2, s52
	v_bfe_u32 v27, v47, 16, 1
	v_lshl_add_u64 v[64:65], v[48:49], 0, v[64:65]
	v_lshrrev_b32_e32 v2, 16, v2
	v_add3_u32 v27, v47, v27, s52
	global_store_dwordx4 v[64:65], v[42:45], off nt
	v_or_b32_e32 v46, s5, v34
	v_ashrrev_i32_e32 v47, 31, v46
	v_and_or_b32 v42, v27, s53, v2
	v_bfe_u32 v2, v53, 16, 1
	v_add3_u32 v2, v53, v2, s52
	v_bfe_u32 v27, v55, 16, 1
	v_lshrrev_b32_e32 v2, 16, v2
	v_add3_u32 v27, v55, v27, s52
	v_and_or_b32 v43, v27, s53, v2
	v_bfe_u32 v2, v57, 16, 1
	v_add3_u32 v2, v57, v2, s52
	v_bfe_u32 v27, v59, 16, 1
	v_lshrrev_b32_e32 v2, 16, v2
	v_add3_u32 v27, v59, v27, s52
	v_and_or_b32 v44, v27, s53, v2
	v_bfe_u32 v2, v61, 16, 1
	v_add3_u32 v2, v61, v2, s52
	v_bfe_u32 v27, v63, 16, 1
	v_lshrrev_b32_e32 v2, 16, v2
	v_add3_u32 v27, v63, v27, s52
	v_lshlrev_b64 v[46:47], 12, v[46:47]
	v_and_or_b32 v45, v27, s53, v2
	v_lshl_add_u64 v[46:47], v[48:49], 0, v[46:47]
	global_store_dwordx4 v[46:47], v[42:45], off nt
	s_waitcnt lgkmcnt(0)

.LBB0_1504:
	s_andn2_b64 vcc, exec, s[4:5]
	s_cbranch_vccnz .LBB0_1506
	s_add_i32 s2, s14, 0x99c0
	s_and_b32 s4, s2, 0xffc0
	s_lshl_b32 s2, s14, 5
	s_and_b32 s6, s2, 0x7e0
	v_or_b32_e32 v2, s4, v28
	s_lshl_b32 s2, s6, 2
	v_lshl_add_u64 v[42:43], v[14:15], 0, s[2:3]
	v_lshlrev_b32_e32 v2, 13, v2
	v_lshl_add_u64 v[42:43], v[42:43], 0, v[2:3]
	v_add_co_u32_e32 v44, vcc, 0x4000, v42
	s_mov_b32 s5, s3
	s_nop 0
	v_addc_co_u32_e32 v45, vcc, 0, v43, vcc
	v_add_co_u32_e32 v46, vcc, 0x8000, v42
	s_nop 1
	v_addc_co_u32_e32 v47, vcc, 0, v43, vcc
	v_add_co_u32_e32 v48, vcc, 0xc000, v42
	s_nop 1
	v_addc_co_u32_e32 v49, vcc, 0, v43, vcc
	v_add_co_u32_e32 v50, vcc, 0x10000, v42
	s_nop 1
	v_addc_co_u32_e32 v51, vcc, 0, v43, vcc
	v_add_co_u32_e32 v52, vcc, 0x14000, v42
	s_nop 1
	v_addc_co_u32_e32 v53, vcc, 0, v43, vcc
	v_add_co_u32_e32 v54, vcc, 0x18000, v42
	s_nop 1
	v_addc_co_u32_e32 v55, vcc, 0, v43, vcc
	v_add_co_u32_e32 v56, vcc, 0x1c000, v42
	s_nop 1
	v_addc_co_u32_e32 v57, vcc, 0, v43, vcc
	global_load_dword v2, v[42:43], off nt
	global_load_dword v27, v[44:45], off nt
	global_load_dword v60, v[46:47], off nt
	global_load_dword v61, v[48:49], off nt
	global_load_dword v62, v[50:51], off nt
	global_load_dword v63, v[52:53], off nt
	global_load_dword v64, v[54:55], off nt
	global_load_dword v65, v[56:57], off nt
	v_add_co_u32_e32 v44, vcc, 0x20000, v42
	s_waitcnt vmcnt(7)
	v_mul_f32_e32 v2, 0x43000000, v2
	v_addc_co_u32_e32 v45, vcc, 0, v43, vcc
	v_add_co_u32_e32 v46, vcc, 0x24000, v42
	s_waitcnt vmcnt(6)
	v_mul_f32_e32 v27, 0x43000000, v27
	v_addc_co_u32_e32 v47, vcc, 0, v43, vcc
	v_add_co_u32_e32 v48, vcc, 0x28000, v42
	s_nop 1
	v_addc_co_u32_e32 v49, vcc, 0, v43, vcc
	v_add_co_u32_e32 v50, vcc, 0x2c000, v42
	s_nop 1
	v_addc_co_u32_e32 v51, vcc, 0, v43, vcc
	v_add_co_u32_e32 v52, vcc, 0x30000, v42
	s_nop 1
	v_addc_co_u32_e32 v53, vcc, 0, v43, vcc
	v_add_co_u32_e32 v54, vcc, 0x34000, v42
	s_nop 1
	v_addc_co_u32_e32 v55, vcc, 0, v43, vcc
	v_add_co_u32_e32 v56, vcc, 0x38000, v42
	s_nop 1
	v_addc_co_u32_e32 v57, vcc, 0, v43, vcc
	v_add_co_u32_e32 v58, vcc, 0x3c000, v42
	s_nop 1
	v_addc_co_u32_e32 v59, vcc, 0, v43, vcc
	global_load_dword v66, v[44:45], off nt
	global_load_dword v67, v[46:47], off nt
	global_load_dword v68, v[48:49], off nt
	global_load_dword v69, v[50:51], off nt
	global_load_dword v70, v[52:53], off nt
	global_load_dword v71, v[54:55], off nt
	global_load_dword v72, v[56:57], off nt
	global_load_dword v73, v[58:59], off nt
	v_add_co_u32_e32 v44, vcc, 0x40000, v42
	s_nop 1
	v_addc_co_u32_e32 v45, vcc, 0, v43, vcc
	v_add_co_u32_e32 v46, vcc, 0x44000, v42
	s_nop 1
	v_addc_co_u32_e32 v47, vcc, 0, v43, vcc
	v_add_co_u32_e32 v48, vcc, 0x48000, v42
	s_nop 1
	v_addc_co_u32_e32 v49, vcc, 0, v43, vcc
	v_add_co_u32_e32 v50, vcc, 0x4c000, v42
	s_nop 1
	v_addc_co_u32_e32 v51, vcc, 0, v43, vcc
	v_add_co_u32_e32 v52, vcc, 0x50000, v42
	s_nop 1
	v_addc_co_u32_e32 v53, vcc, 0, v43, vcc
	v_add_co_u32_e32 v54, vcc, 0x54000, v42
	s_nop 1
	v_addc_co_u32_e32 v55, vcc, 0, v43, vcc
	v_add_co_u32_e32 v56, vcc, 0x58000, v42
	s_nop 1
	v_addc_co_u32_e32 v57, vcc, 0, v43, vcc
	v_add_co_u32_e32 v58, vcc, 0x5c000, v42
	s_nop 1
	v_addc_co_u32_e32 v59, vcc, 0, v43, vcc
	global_load_dword v74, v[44:45], off nt
	global_load_dword v75, v[46:47], off nt
	global_load_dword v76, v[48:49], off nt
	global_load_dword v77, v[50:51], off nt
	global_load_dword v78, v[52:53], off nt
	global_load_dword v79, v[54:55], off nt
	s_nop 0
	global_load_dword v56, v[56:57], off nt
	s_nop 0
	global_load_dword v57, v[58:59], off nt
	v_add_co_u32_e32 v44, vcc, 0x60000, v42
	s_nop 1
	v_addc_co_u32_e32 v45, vcc, 0, v43, vcc
	v_add_co_u32_e32 v46, vcc, 0x64000, v42
	s_nop 1
	v_addc_co_u32_e32 v47, vcc, 0, v43, vcc
	v_add_co_u32_e32 v48, vcc, 0x68000, v42
	s_nop 1
	v_addc_co_u32_e32 v49, vcc, 0, v43, vcc
	v_add_co_u32_e32 v50, vcc, 0x6c000, v42
	s_nop 1
	v_addc_co_u32_e32 v51, vcc, 0, v43, vcc
	v_add_co_u32_e32 v52, vcc, 0x70000, v42
	s_nop 1
	v_addc_co_u32_e32 v53, vcc, 0, v43, vcc
	v_add_co_u32_e32 v54, vcc, 0x74000, v42
	s_nop 1
	v_addc_co_u32_e32 v55, vcc, 0, v43, vcc
	global_load_dword v58, v[44:45], off nt
	s_nop 0
	global_load_dword v46, v[46:47], off nt
	s_nop 0
	global_load_dword v47, v[48:49], off nt
	s_nop 0
	global_load_dword v48, v[50:51], off nt
	global_load_dword v49, v[52:53], off nt
	s_nop 0
	global_load_dword v50, v[54:55], off nt
	v_add_co_u32_e32 v44, vcc, 0x78000, v42
	v_mov_b32_e32 v51, v3
	s_nop 0
	v_addc_co_u32_e32 v45, vcc, 0, v43, vcc
	v_add_co_u32_e32 v42, vcc, 0x7c000, v42
	s_nop 1
	v_addc_co_u32_e32 v43, vcc, 0, v43, vcc
	global_load_dword v44, v[44:45], off nt
	s_nop 0
	global_load_dword v42, v[42:43], off nt
	ds_write2_b32 v29, v2, v27 offset1:66
	s_waitcnt vmcnt(29)
	v_mul_f32_e32 v2, 0x43000000, v60
	s_waitcnt vmcnt(28)
	v_mul_f32_e32 v27, 0x43000000, v61
	ds_write2_b32 v29, v2, v27 offset0:132 offset1:198
	s_waitcnt vmcnt(27)
	v_mul_f32_e32 v2, 0x43000000, v62
	s_waitcnt vmcnt(26)
	v_mul_f32_e32 v27, 0x43000000, v63
	ds_write2_b32 v35, v2, v27 offset0:8 offset1:74
	s_waitcnt vmcnt(25)
	v_mul_f32_e32 v2, 0x43000000, v64
	s_waitcnt vmcnt(24)
	v_mul_f32_e32 v27, 0x43000000, v65
	ds_write2_b32 v35, v2, v27 offset0:140 offset1:206
	s_waitcnt vmcnt(23)
	v_mul_f32_e32 v2, 0x43000000, v66
	s_waitcnt vmcnt(22)
	v_mul_f32_e32 v27, 0x43000000, v67
	ds_write2_b32 v36, v2, v27 offset0:16 offset1:82
	s_waitcnt vmcnt(21)
	v_mul_f32_e32 v2, 0x43000000, v68
	s_waitcnt vmcnt(20)
	v_mul_f32_e32 v27, 0x43000000, v69
	ds_write2_b32 v36, v2, v27 offset0:148 offset1:214
	s_waitcnt vmcnt(19)
	v_mul_f32_e32 v2, 0x43000000, v70
	s_waitcnt vmcnt(18)
	v_mul_f32_e32 v27, 0x43000000, v71
	ds_write2_b32 v37, v2, v27 offset0:24 offset1:90
	s_waitcnt vmcnt(17)
	v_mul_f32_e32 v2, 0x43000000, v72
	s_waitcnt vmcnt(16)
	v_mul_f32_e32 v27, 0x43000000, v73
	ds_write2_b32 v37, v2, v27 offset0:156 offset1:222
	v_lshl_add_u64 v[60:61], v[16:17], 0, s[4:5]
	s_waitcnt vmcnt(15)
	v_mul_f32_e32 v2, 0x43000000, v74
	s_waitcnt vmcnt(14)
	v_mul_f32_e32 v27, 0x43000000, v75
	ds_write2_b32 v38, v2, v27 offset0:32 offset1:98
	s_waitcnt vmcnt(13)
	v_mul_f32_e32 v2, 0x43000000, v76
	s_waitcnt vmcnt(12)
	v_mul_f32_e32 v27, 0x43000000, v77
	ds_write2_b32 v38, v2, v27 offset0:164 offset1:230
	s_waitcnt vmcnt(11)
	v_mul_f32_e32 v2, 0x43000000, v78
	s_waitcnt vmcnt(10)
	v_mul_f32_e32 v27, 0x43000000, v79
	ds_write2_b32 v39, v2, v27 offset0:40 offset1:106
	s_waitcnt vmcnt(9)
	v_mul_f32_e32 v2, 0x43000000, v56
	s_waitcnt vmcnt(8)
	v_mul_f32_e32 v27, 0x43000000, v57
	ds_write2_b32 v39, v2, v27 offset0:172 offset1:238
	s_waitcnt vmcnt(7)
	v_mul_f32_e32 v2, 0x43000000, v58
	s_waitcnt vmcnt(6)
	v_mul_f32_e32 v27, 0x43000000, v46
	ds_write2_b32 v40, v2, v27 offset0:48 offset1:114
	s_waitcnt vmcnt(5)
	v_mul_f32_e32 v2, 0x43000000, v47
	s_waitcnt vmcnt(4)
	v_mul_f32_e32 v27, 0x43000000, v48
	ds_write2_b32 v40, v2, v27 offset0:180 offset1:246
	s_waitcnt vmcnt(3)
	v_mul_f32_e32 v2, 0x43000000, v49
	s_waitcnt vmcnt(2)
	v_mul_f32_e32 v27, 0x43000000, v50
	ds_write2_b32 v41, v2, v27 offset0:56 offset1:122
	v_mov_b32_e32 v50, v3
	s_waitcnt vmcnt(1)
	v_mul_f32_e32 v2, 0x43000000, v44
	s_waitcnt vmcnt(0)
	v_mul_f32_e32 v27, 0x43000000, v42
	ds_write2_b32 v41, v2, v27 offset0:188 offset1:254
	s_waitcnt lgkmcnt(0)
	ds_read2_b32 v[42:43], v31 offset0:33 offset1:41
	ds_read2_b32 v[44:45], v31 offset0:66 offset1:74
	ds_read2_b32 v[46:47], v31 offset1:8
	ds_read2_b32 v[48:49], v31 offset0:99 offset1:107
	ds_read2_b32 v[52:53], v31 offset0:132 offset1:140
	ds_read2_b32 v[54:55], v31 offset0:165 offset1:173
	ds_read2_b32 v[56:57], v31 offset0:198 offset1:206
	ds_read2_b32 v[58:59], v31 offset0:231 offset1:239
	v_or_b32_e32 v2, s6, v30
	s_waitcnt lgkmcnt(5)
	v_cvt_pk_fp8_f32 v50, v46, v42
	v_mov_b32_e32 v42, v3
	s_waitcnt lgkmcnt(2)
	v_cvt_pk_fp8_f32 v51, v52, v54
	v_cvt_pk_fp8_f32 v42, v47, v43
	v_cvt_pk_fp8_f32 v50, v44, v48 op_sel:[0,0,1]
	v_mov_b32_e32 v43, v3
	s_waitcnt lgkmcnt(0)
	v_cvt_pk_fp8_f32 v51, v56, v58 op_sel:[0,0,1]
	v_cvt_pk_fp8_f32 v43, v53, v55
	v_lshlrev_b32_e32 v2, 11, v2
	v_lshl_add_u64 v[46:47], v[60:61], 0, v[2:3]
	global_store_dwordx2 v[46:47], v[50:51], off nt
	v_cvt_pk_fp8_f32 v42, v45, v49 op_sel:[0,0,1]
	v_cvt_pk_fp8_f32 v43, v57, v59 op_sel:[0,0,1]
	ds_read2_b32 v[44:45], v31 offset0:49 offset1:57
	ds_read2_b32 v[46:47], v31 offset0:82 offset1:90
	ds_read2_b32 v[48:49], v31 offset0:16 offset1:24
	ds_read2_b32 v[50:51], v31 offset0:115 offset1:123
	ds_read2_b32 v[54:55], v31 offset0:148 offset1:156
	ds_read2_b32 v[56:57], v31 offset0:181 offset1:189
	v_or_b32_e32 v2, s6, v32
	v_lshlrev_b32_e32 v2, 11, v2
	v_mov_b32_e32 v52, v3
	ds_read2_b32 v[58:59], v31 offset0:214 offset1:222
	ds_read2_b32 v[62:63], v31 offset0:247 offset1:255
	v_mov_b32_e32 v53, v3
	v_lshl_add_u64 v[64:65], v[60:61], 0, v[2:3]
	s_waitcnt lgkmcnt(5)
	v_cvt_pk_fp8_f32 v52, v48, v44
	s_waitcnt lgkmcnt(2)
	v_cvt_pk_fp8_f32 v53, v54, v56
	global_store_dwordx2 v[64:65], v[42:43], off nt
	v_mov_b32_e32 v42, v3
	v_mov_b32_e32 v43, v3
	v_cvt_pk_fp8_f32 v42, v49, v45
	v_cvt_pk_fp8_f32 v43, v55, v57
	v_cvt_pk_fp8_f32 v52, v46, v50 op_sel:[0,0,1]
	s_waitcnt lgkmcnt(0)
	v_cvt_pk_fp8_f32 v53, v58, v62 op_sel:[0,0,1]
	v_or_b32_e32 v2, s6, v33
	v_lshlrev_b32_e32 v2, 11, v2
	v_cvt_pk_fp8_f32 v42, v47, v51 op_sel:[0,0,1]
	v_cvt_pk_fp8_f32 v43, v59, v63 op_sel:[0,0,1]
	v_lshl_add_u64 v[44:45], v[60:61], 0, v[2:3]
	v_or_b32_e32 v2, s6, v34
	v_lshlrev_b32_e32 v2, 11, v2
	global_store_dwordx2 v[44:45], v[52:53], off nt
	v_lshl_add_u64 v[44:45], v[60:61], 0, v[2:3]
	global_store_dwordx2 v[44:45], v[42:43], off nt
	s_waitcnt lgkmcnt(0)

.LBB0_1507:
	s_andn2_b64 vcc, exec, s[4:5]
	s_cbranch_vccnz .LBB0_1509
	s_add_i32 s84, s14, 0xffffb1c0
	s_lshr_b32 s2, s84, 11
	s_add_i32 s2, s2, 3
	s_lshl_b64 s[4:5], s[2:3], 24
	s_add_u32 s85, s15, s4
	s_addc_u32 s86, s16, s5
	s_and_b32 s2, s84, 0xfffff800
	s_lshl_b64 s[6:7], s[2:3], 11
	s_add_u32 s5, s8, s6
	s_addc_u32 s4, s9, s7
	s_lshl_b32 s2, s14, 5
	s_and_b32 s2, s2, 0x7e0
	s_and_b32 s6, s84, 0x7c0
	s_lshl_b32 s7, s2, 2
	s_add_u32 s84, s85, s7
	v_or_b32_e32 v2, s6, v28
	s_addc_u32 s85, s86, 0
	v_mov_b32_e32 v27, v3
	v_lshl_add_u64 v[42:43], s[84:85], 0, v[26:27]
	v_lshlrev_b32_e32 v2, 13, v2
	v_lshl_add_u64 v[42:43], v[42:43], 0, v[2:3]
	v_add_co_u32_e32 v44, vcc, s20, v42
	s_add_u32 s6, s5, s6
	s_nop 0
	v_addc_co_u32_e32 v45, vcc, 0, v43, vcc
	v_add_co_u32_e32 v46, vcc, s21, v42
	s_addc_u32 s7, s4, 0
	s_nop 0
	v_addc_co_u32_e32 v47, vcc, 0, v43, vcc
	v_add_co_u32_e32 v48, vcc, s22, v42
	s_nop 1
	v_addc_co_u32_e32 v49, vcc, 0, v43, vcc
	v_add_co_u32_e32 v50, vcc, s23, v42
	s_nop 1
	v_addc_co_u32_e32 v51, vcc, 0, v43, vcc
	v_add_co_u32_e32 v52, vcc, s24, v42
	s_nop 1
	v_addc_co_u32_e32 v53, vcc, 0, v43, vcc
	v_add_co_u32_e32 v54, vcc, s25, v42
	s_nop 1
	v_addc_co_u32_e32 v55, vcc, 0, v43, vcc
	v_add_co_u32_e32 v56, vcc, s26, v42
	s_nop 1
	v_addc_co_u32_e32 v57, vcc, 0, v43, vcc
	global_load_dword v2, v[42:43], off nt
	global_load_dword v27, v[44:45], off nt
	global_load_dword v60, v[46:47], off nt
	global_load_dword v61, v[48:49], off nt
	global_load_dword v62, v[50:51], off nt
	global_load_dword v63, v[52:53], off nt
	global_load_dword v64, v[54:55], off nt
	global_load_dword v65, v[56:57], off nt
	v_add_co_u32_e32 v44, vcc, s27, v42
	s_waitcnt vmcnt(7)
	v_mul_f32_e32 v2, 0x43000000, v2
	v_addc_co_u32_e32 v45, vcc, 0, v43, vcc
	v_add_co_u32_e32 v46, vcc, s28, v42
	s_waitcnt vmcnt(6)
	v_mul_f32_e32 v27, 0x43000000, v27
	v_addc_co_u32_e32 v47, vcc, 0, v43, vcc
	v_add_co_u32_e32 v48, vcc, s29, v42
	s_nop 1
	v_addc_co_u32_e32 v49, vcc, 0, v43, vcc
	v_add_co_u32_e32 v50, vcc, s30, v42
	s_nop 1
	v_addc_co_u32_e32 v51, vcc, 0, v43, vcc
	v_add_co_u32_e32 v52, vcc, s31, v42
	s_nop 1
	v_addc_co_u32_e32 v53, vcc, 0, v43, vcc
	v_add_co_u32_e32 v54, vcc, s33, v42
	s_nop 1
	v_addc_co_u32_e32 v55, vcc, 0, v43, vcc
	v_add_co_u32_e32 v56, vcc, s34, v42
	s_nop 1
	v_addc_co_u32_e32 v57, vcc, 0, v43, vcc
	v_add_co_u32_e32 v58, vcc, s35, v42
	s_nop 1
	v_addc_co_u32_e32 v59, vcc, 0, v43, vcc
	global_load_dword v66, v[44:45], off nt
	global_load_dword v67, v[46:47], off nt
	global_load_dword v68, v[48:49], off nt
	global_load_dword v69, v[50:51], off nt
	global_load_dword v70, v[52:53], off nt
	global_load_dword v71, v[54:55], off nt
	global_load_dword v72, v[56:57], off nt
	global_load_dword v73, v[58:59], off nt
	v_add_co_u32_e32 v44, vcc, s36, v42
	s_nop 1
	v_addc_co_u32_e32 v45, vcc, 0, v43, vcc
	v_add_co_u32_e32 v46, vcc, s37, v42
	s_nop 1
	v_addc_co_u32_e32 v47, vcc, 0, v43, vcc
	v_add_co_u32_e32 v48, vcc, s38, v42
	s_nop 1
	v_addc_co_u32_e32 v49, vcc, 0, v43, vcc
	v_add_co_u32_e32 v50, vcc, s39, v42
	s_nop 1
	v_addc_co_u32_e32 v51, vcc, 0, v43, vcc
	v_add_co_u32_e32 v52, vcc, s40, v42
	s_nop 1
	v_addc_co_u32_e32 v53, vcc, 0, v43, vcc
	v_add_co_u32_e32 v54, vcc, s41, v42
	s_nop 1
	v_addc_co_u32_e32 v55, vcc, 0, v43, vcc
	v_add_co_u32_e32 v56, vcc, s42, v42
	s_nop 1
	v_addc_co_u32_e32 v57, vcc, 0, v43, vcc
	v_add_co_u32_e32 v58, vcc, s43, v42
	s_nop 1
	v_addc_co_u32_e32 v59, vcc, 0, v43, vcc
	global_load_dword v74, v[44:45], off nt
	global_load_dword v75, v[46:47], off nt
	global_load_dword v76, v[48:49], off nt
	global_load_dword v77, v[50:51], off nt
	global_load_dword v78, v[52:53], off nt
	global_load_dword v79, v[54:55], off nt
	s_nop 0
	global_load_dword v56, v[56:57], off nt
	s_nop 0
	global_load_dword v57, v[58:59], off nt
	v_add_co_u32_e32 v44, vcc, s44, v42
	s_nop 1
	v_addc_co_u32_e32 v45, vcc, 0, v43, vcc
	v_add_co_u32_e32 v46, vcc, s45, v42
	s_nop 1
	v_addc_co_u32_e32 v47, vcc, 0, v43, vcc
	v_add_co_u32_e32 v48, vcc, s46, v42
	s_nop 1
	v_addc_co_u32_e32 v49, vcc, 0, v43, vcc
	v_add_co_u32_e32 v50, vcc, s47, v42
	s_nop 1
	v_addc_co_u32_e32 v51, vcc, 0, v43, vcc
	v_add_co_u32_e32 v52, vcc, s48, v42
	s_nop 1
	v_addc_co_u32_e32 v53, vcc, 0, v43, vcc
	v_add_co_u32_e32 v54, vcc, s49, v42
	s_nop 1
	v_addc_co_u32_e32 v55, vcc, 0, v43, vcc
	global_load_dword v58, v[44:45], off nt
	s_nop 0
	global_load_dword v46, v[46:47], off nt
	s_nop 0
	global_load_dword v47, v[48:49], off nt
	s_nop 0
	global_load_dword v48, v[50:51], off nt
	global_load_dword v49, v[52:53], off nt
	s_nop 0
	global_load_dword v50, v[54:55], off nt
	v_add_co_u32_e32 v44, vcc, s50, v42
	v_mov_b32_e32 v51, v3
	s_nop 0
	v_addc_co_u32_e32 v45, vcc, 0, v43, vcc
	v_add_co_u32_e32 v42, vcc, s51, v42
	s_nop 1
	v_addc_co_u32_e32 v43, vcc, 0, v43, vcc
	global_load_dword v44, v[44:45], off nt
	s_nop 0
	global_load_dword v42, v[42:43], off nt
	ds_write2_b32 v29, v2, v27 offset1:66
	s_waitcnt vmcnt(29)
	v_mul_f32_e32 v2, 0x43000000, v60
	s_waitcnt vmcnt(28)
	v_mul_f32_e32 v27, 0x43000000, v61
	ds_write2_b32 v29, v2, v27 offset0:132 offset1:198
	s_waitcnt vmcnt(27)
	v_mul_f32_e32 v2, 0x43000000, v62
	s_waitcnt vmcnt(26)
	v_mul_f32_e32 v27, 0x43000000, v63
	ds_write2_b32 v35, v2, v27 offset0:8 offset1:74
	s_waitcnt vmcnt(25)
	v_mul_f32_e32 v2, 0x43000000, v64
	s_waitcnt vmcnt(24)
	v_mul_f32_e32 v27, 0x43000000, v65
	ds_write2_b32 v35, v2, v27 offset0:140 offset1:206
	s_waitcnt vmcnt(23)
	v_mul_f32_e32 v2, 0x43000000, v66
	s_waitcnt vmcnt(22)
	v_mul_f32_e32 v27, 0x43000000, v67
	ds_write2_b32 v36, v2, v27 offset0:16 offset1:82
	s_waitcnt vmcnt(21)
	v_mul_f32_e32 v2, 0x43000000, v68
	s_waitcnt vmcnt(20)
	v_mul_f32_e32 v27, 0x43000000, v69
	ds_write2_b32 v36, v2, v27 offset0:148 offset1:214
	s_waitcnt vmcnt(19)
	v_mul_f32_e32 v2, 0x43000000, v70
	s_waitcnt vmcnt(18)
	v_mul_f32_e32 v27, 0x43000000, v71
	ds_write2_b32 v37, v2, v27 offset0:24 offset1:90
	s_waitcnt vmcnt(17)
	v_mul_f32_e32 v2, 0x43000000, v72
	s_waitcnt vmcnt(16)
	v_mul_f32_e32 v27, 0x43000000, v73
	ds_write2_b32 v37, v2, v27 offset0:156 offset1:222
	v_lshl_add_u64 v[60:61], s[6:7], 0, v[6:7]
	s_waitcnt vmcnt(15)
	v_mul_f32_e32 v2, 0x43000000, v74
	s_waitcnt vmcnt(14)
	v_mul_f32_e32 v27, 0x43000000, v75
	ds_write2_b32 v38, v2, v27 offset0:32 offset1:98
	s_waitcnt vmcnt(13)
	v_mul_f32_e32 v2, 0x43000000, v76
	s_waitcnt vmcnt(12)
	v_mul_f32_e32 v27, 0x43000000, v77
	ds_write2_b32 v38, v2, v27 offset0:164 offset1:230
	s_waitcnt vmcnt(11)
	v_mul_f32_e32 v2, 0x43000000, v78
	s_waitcnt vmcnt(10)
	v_mul_f32_e32 v27, 0x43000000, v79
	ds_write2_b32 v39, v2, v27 offset0:40 offset1:106
	s_waitcnt vmcnt(9)
	v_mul_f32_e32 v2, 0x43000000, v56
	s_waitcnt vmcnt(8)
	v_mul_f32_e32 v27, 0x43000000, v57
	ds_write2_b32 v39, v2, v27 offset0:172 offset1:238
	s_waitcnt vmcnt(7)
	v_mul_f32_e32 v2, 0x43000000, v58
	s_waitcnt vmcnt(6)
	v_mul_f32_e32 v27, 0x43000000, v46
	ds_write2_b32 v40, v2, v27 offset0:48 offset1:114
	s_waitcnt vmcnt(5)
	v_mul_f32_e32 v2, 0x43000000, v47
	s_waitcnt vmcnt(4)
	v_mul_f32_e32 v27, 0x43000000, v48
	ds_write2_b32 v40, v2, v27 offset0:180 offset1:246
	s_waitcnt vmcnt(3)
	v_mul_f32_e32 v2, 0x43000000, v49
	s_waitcnt vmcnt(2)
	v_mul_f32_e32 v27, 0x43000000, v50
	ds_write2_b32 v41, v2, v27 offset0:56 offset1:122
	v_mov_b32_e32 v50, v3
	s_waitcnt vmcnt(1)
	v_mul_f32_e32 v2, 0x43000000, v44
	s_waitcnt vmcnt(0)
	v_mul_f32_e32 v27, 0x43000000, v42
	ds_write2_b32 v41, v2, v27 offset0:188 offset1:254
	s_waitcnt lgkmcnt(0)
	ds_read2_b32 v[42:43], v31 offset0:33 offset1:41
	ds_read2_b32 v[44:45], v31 offset0:66 offset1:74
	ds_read2_b32 v[46:47], v31 offset1:8
	ds_read2_b32 v[48:49], v31 offset0:99 offset1:107
	ds_read2_b32 v[52:53], v31 offset0:132 offset1:140
	ds_read2_b32 v[54:55], v31 offset0:165 offset1:173
	ds_read2_b32 v[56:57], v31 offset0:198 offset1:206
	ds_read2_b32 v[58:59], v31 offset0:231 offset1:239
	v_or_b32_e32 v2, s2, v30
	s_waitcnt lgkmcnt(5)
	v_cvt_pk_fp8_f32 v50, v46, v42
	v_mov_b32_e32 v42, v3
	s_waitcnt lgkmcnt(2)
	v_cvt_pk_fp8_f32 v51, v52, v54
	v_cvt_pk_fp8_f32 v42, v47, v43
	v_cvt_pk_fp8_f32 v50, v44, v48 op_sel:[0,0,1]
	v_mov_b32_e32 v43, v3
	s_waitcnt lgkmcnt(0)
	v_cvt_pk_fp8_f32 v51, v56, v58 op_sel:[0,0,1]
	v_cvt_pk_fp8_f32 v43, v53, v55
	v_lshlrev_b32_e32 v2, 11, v2
	v_lshl_add_u64 v[46:47], v[60:61], 0, v[2:3]
	global_store_dwordx2 v[46:47], v[50:51], off nt
	v_cvt_pk_fp8_f32 v42, v45, v49 op_sel:[0,0,1]
	v_cvt_pk_fp8_f32 v43, v57, v59 op_sel:[0,0,1]
	ds_read2_b32 v[44:45], v31 offset0:49 offset1:57
	ds_read2_b32 v[46:47], v31 offset0:82 offset1:90
	ds_read2_b32 v[48:49], v31 offset0:16 offset1:24
	ds_read2_b32 v[50:51], v31 offset0:115 offset1:123
	ds_read2_b32 v[54:55], v31 offset0:148 offset1:156
	ds_read2_b32 v[56:57], v31 offset0:181 offset1:189
	v_or_b32_e32 v2, s2, v32
	v_lshlrev_b32_e32 v2, 11, v2
	v_mov_b32_e32 v52, v3
	ds_read2_b32 v[58:59], v31 offset0:214 offset1:222
	ds_read2_b32 v[62:63], v31 offset0:247 offset1:255
	v_mov_b32_e32 v53, v3
	v_lshl_add_u64 v[64:65], v[60:61], 0, v[2:3]
	s_waitcnt lgkmcnt(5)
	v_cvt_pk_fp8_f32 v52, v48, v44
	s_waitcnt lgkmcnt(2)
	v_cvt_pk_fp8_f32 v53, v54, v56
	global_store_dwordx2 v[64:65], v[42:43], off nt
	v_mov_b32_e32 v42, v3
	v_mov_b32_e32 v43, v3
	v_cvt_pk_fp8_f32 v42, v49, v45
	v_cvt_pk_fp8_f32 v43, v55, v57
	v_cvt_pk_fp8_f32 v52, v46, v50 op_sel:[0,0,1]
	s_waitcnt lgkmcnt(0)
	v_cvt_pk_fp8_f32 v53, v58, v62 op_sel:[0,0,1]
	v_or_b32_e32 v2, s2, v33
	v_lshlrev_b32_e32 v2, 11, v2
	v_cvt_pk_fp8_f32 v42, v47, v51 op_sel:[0,0,1]
	v_cvt_pk_fp8_f32 v43, v59, v63 op_sel:[0,0,1]
	v_lshl_add_u64 v[44:45], v[60:61], 0, v[2:3]
	v_or_b32_e32 v2, s2, v34
	v_lshlrev_b32_e32 v2, 11, v2
	global_store_dwordx2 v[44:45], v[52:53], off nt
	v_lshl_add_u64 v[44:45], v[60:61], 0, v[2:3]
	global_store_dwordx2 v[44:45], v[42:43], off nt
	s_waitcnt lgkmcnt(0)

.LBB0_1510:
	s_andn2_b64 vcc, exec, s[4:5]
	s_cbranch_vccnz .LBB0_1512
	s_add_i32 s2, s14, 0xb5c0
	s_lshr_b32 s4, s2, 1
	s_lshl_b32 s2, s2, 5
	s_and_b32 s4, s4, 0x7fc0
	s_and_b32 s6, s2, 0xfe0
	v_or_b32_e32 v2, s4, v28
	s_lshl_b32 s2, s6, 2
	v_lshl_add_u64 v[42:43], v[18:19], 0, s[2:3]
	v_lshlrev_b32_e32 v2, 14, v2
	v_lshl_add_u64 v[42:43], v[42:43], 0, v[2:3]
	v_add_co_u32_e32 v44, vcc, 0x8000, v42
	s_mov_b32 s5, s3
	s_nop 0
	v_addc_co_u32_e32 v45, vcc, 0, v43, vcc
	v_add_co_u32_e32 v46, vcc, 0x10000, v42
	s_nop 1
	v_addc_co_u32_e32 v47, vcc, 0, v43, vcc
	v_add_co_u32_e32 v48, vcc, 0x18000, v42
	s_nop 1
	v_addc_co_u32_e32 v49, vcc, 0, v43, vcc
	v_add_co_u32_e32 v50, vcc, 0x20000, v42
	s_nop 1
	v_addc_co_u32_e32 v51, vcc, 0, v43, vcc
	v_add_co_u32_e32 v52, vcc, 0x28000, v42
	s_nop 1
	v_addc_co_u32_e32 v53, vcc, 0, v43, vcc
	v_add_co_u32_e32 v54, vcc, 0x30000, v42
	s_nop 1
	v_addc_co_u32_e32 v55, vcc, 0, v43, vcc
	v_add_co_u32_e32 v56, vcc, 0x38000, v42
	s_nop 1
	v_addc_co_u32_e32 v57, vcc, 0, v43, vcc
	global_load_dword v2, v[42:43], off nt
	global_load_dword v27, v[44:45], off nt
	global_load_dword v60, v[46:47], off nt
	global_load_dword v61, v[48:49], off nt
	global_load_dword v62, v[50:51], off nt
	global_load_dword v63, v[52:53], off nt
	global_load_dword v64, v[54:55], off nt
	global_load_dword v65, v[56:57], off nt
	v_add_co_u32_e32 v44, vcc, 0x40000, v42
	s_waitcnt vmcnt(7)
	v_mul_f32_e32 v2, 0x42000000, v2
	v_addc_co_u32_e32 v45, vcc, 0, v43, vcc
	v_add_co_u32_e32 v46, vcc, 0x48000, v42
	s_waitcnt vmcnt(6)
	v_mul_f32_e32 v27, 0x42000000, v27
	v_addc_co_u32_e32 v47, vcc, 0, v43, vcc
	v_add_co_u32_e32 v48, vcc, 0x50000, v42
	s_nop 1
	v_addc_co_u32_e32 v49, vcc, 0, v43, vcc
	v_add_co_u32_e32 v50, vcc, 0x58000, v42
	s_nop 1
	v_addc_co_u32_e32 v51, vcc, 0, v43, vcc
	v_add_co_u32_e32 v52, vcc, 0x60000, v42
	s_nop 1
	v_addc_co_u32_e32 v53, vcc, 0, v43, vcc
	v_add_co_u32_e32 v54, vcc, 0x68000, v42
	s_nop 1
	v_addc_co_u32_e32 v55, vcc, 0, v43, vcc
	v_add_co_u32_e32 v56, vcc, 0x70000, v42
	s_nop 1
	v_addc_co_u32_e32 v57, vcc, 0, v43, vcc
	v_add_co_u32_e32 v58, vcc, 0x78000, v42
	s_nop 1
	v_addc_co_u32_e32 v59, vcc, 0, v43, vcc
	global_load_dword v66, v[44:45], off nt
	global_load_dword v67, v[46:47], off nt
	global_load_dword v68, v[48:49], off nt
	global_load_dword v69, v[50:51], off nt
	global_load_dword v70, v[52:53], off nt
	global_load_dword v71, v[54:55], off nt
	global_load_dword v72, v[56:57], off nt
	global_load_dword v73, v[58:59], off nt
	v_add_co_u32_e32 v44, vcc, 0x80000, v42
	s_nop 1
	v_addc_co_u32_e32 v45, vcc, 0, v43, vcc
	v_add_co_u32_e32 v46, vcc, 0x88000, v42
	s_nop 1
	v_addc_co_u32_e32 v47, vcc, 0, v43, vcc
	v_add_co_u32_e32 v48, vcc, 0x90000, v42
	s_nop 1
	v_addc_co_u32_e32 v49, vcc, 0, v43, vcc
	v_add_co_u32_e32 v50, vcc, 0x98000, v42
	s_nop 1
	v_addc_co_u32_e32 v51, vcc, 0, v43, vcc
	v_add_co_u32_e32 v52, vcc, 0xa0000, v42
	s_nop 1
	v_addc_co_u32_e32 v53, vcc, 0, v43, vcc
	v_add_co_u32_e32 v54, vcc, 0xa8000, v42
	s_nop 1
	v_addc_co_u32_e32 v55, vcc, 0, v43, vcc
	v_add_co_u32_e32 v56, vcc, s59, v42
	s_nop 1
	v_addc_co_u32_e32 v57, vcc, 0, v43, vcc
	v_add_co_u32_e32 v58, vcc, 0xb8000, v42
	s_nop 1
	v_addc_co_u32_e32 v59, vcc, 0, v43, vcc
	global_load_dword v74, v[44:45], off nt
	global_load_dword v75, v[46:47], off nt
	global_load_dword v76, v[48:49], off nt
	global_load_dword v77, v[50:51], off nt
	global_load_dword v78, v[52:53], off nt
	global_load_dword v79, v[54:55], off nt
	s_nop 0
	global_load_dword v56, v[56:57], off nt
	s_nop 0
	global_load_dword v57, v[58:59], off nt
	v_add_co_u32_e32 v44, vcc, 0xc0000, v42
	s_nop 1
	v_addc_co_u32_e32 v45, vcc, 0, v43, vcc
	v_add_co_u32_e32 v46, vcc, 0xc8000, v42
	s_nop 1
	v_addc_co_u32_e32 v47, vcc, 0, v43, vcc
	v_add_co_u32_e32 v48, vcc, 0xd0000, v42
	s_nop 1
	v_addc_co_u32_e32 v49, vcc, 0, v43, vcc
	v_add_co_u32_e32 v50, vcc, 0xd8000, v42
	s_nop 1
	v_addc_co_u32_e32 v51, vcc, 0, v43, vcc
	v_add_co_u32_e32 v52, vcc, 0xe0000, v42
	s_nop 1
	v_addc_co_u32_e32 v53, vcc, 0, v43, vcc
	v_add_co_u32_e32 v54, vcc, 0xe8000, v42
	s_nop 1
	v_addc_co_u32_e32 v55, vcc, 0, v43, vcc
	global_load_dword v58, v[44:45], off nt
	s_nop 0
	global_load_dword v46, v[46:47], off nt
	s_nop 0
	global_load_dword v47, v[48:49], off nt
	s_nop 0
	global_load_dword v48, v[50:51], off nt
	global_load_dword v49, v[52:53], off nt
	s_nop 0
	global_load_dword v50, v[54:55], off nt
	v_add_co_u32_e32 v44, vcc, 0xf0000, v42
	v_mov_b32_e32 v51, v3
	s_nop 0
	v_addc_co_u32_e32 v45, vcc, 0, v43, vcc
	v_add_co_u32_e32 v42, vcc, 0xf8000, v42
	s_nop 1
	v_addc_co_u32_e32 v43, vcc, 0, v43, vcc
	global_load_dword v44, v[44:45], off nt
	s_nop 0
	global_load_dword v42, v[42:43], off nt
	ds_write2_b32 v29, v2, v27 offset1:66
	s_waitcnt vmcnt(29)
	v_mul_f32_e32 v2, 0x42000000, v60
	s_waitcnt vmcnt(28)
	v_mul_f32_e32 v27, 0x42000000, v61
	ds_write2_b32 v29, v2, v27 offset0:132 offset1:198
	s_waitcnt vmcnt(27)
	v_mul_f32_e32 v2, 0x42000000, v62
	s_waitcnt vmcnt(26)
	v_mul_f32_e32 v27, 0x42000000, v63
	ds_write2_b32 v35, v2, v27 offset0:8 offset1:74
	s_waitcnt vmcnt(25)
	v_mul_f32_e32 v2, 0x42000000, v64
	s_waitcnt vmcnt(24)
	v_mul_f32_e32 v27, 0x42000000, v65
	ds_write2_b32 v35, v2, v27 offset0:140 offset1:206
	s_waitcnt vmcnt(23)
	v_mul_f32_e32 v2, 0x42000000, v66
	s_waitcnt vmcnt(22)
	v_mul_f32_e32 v27, 0x42000000, v67
	ds_write2_b32 v36, v2, v27 offset0:16 offset1:82
	s_waitcnt vmcnt(21)
	v_mul_f32_e32 v2, 0x42000000, v68
	s_waitcnt vmcnt(20)
	v_mul_f32_e32 v27, 0x42000000, v69
	ds_write2_b32 v36, v2, v27 offset0:148 offset1:214
	s_waitcnt vmcnt(19)
	v_mul_f32_e32 v2, 0x42000000, v70
	s_waitcnt vmcnt(18)
	v_mul_f32_e32 v27, 0x42000000, v71
	ds_write2_b32 v37, v2, v27 offset0:24 offset1:90
	s_waitcnt vmcnt(17)
	v_mul_f32_e32 v2, 0x42000000, v72
	s_waitcnt vmcnt(16)
	v_mul_f32_e32 v27, 0x42000000, v73
	ds_write2_b32 v37, v2, v27 offset0:156 offset1:222
	v_lshl_add_u64 v[60:61], v[20:21], 0, s[4:5]
	s_waitcnt vmcnt(15)
	v_mul_f32_e32 v2, 0x42000000, v74
	s_waitcnt vmcnt(14)
	v_mul_f32_e32 v27, 0x42000000, v75
	ds_write2_b32 v38, v2, v27 offset0:32 offset1:98
	s_waitcnt vmcnt(13)
	v_mul_f32_e32 v2, 0x42000000, v76
	s_waitcnt vmcnt(12)
	v_mul_f32_e32 v27, 0x42000000, v77
	ds_write2_b32 v38, v2, v27 offset0:164 offset1:230
	s_waitcnt vmcnt(11)
	v_mul_f32_e32 v2, 0x42000000, v78
	s_waitcnt vmcnt(10)
	v_mul_f32_e32 v27, 0x42000000, v79
	ds_write2_b32 v39, v2, v27 offset0:40 offset1:106
	s_waitcnt vmcnt(9)
	v_mul_f32_e32 v2, 0x42000000, v56
	s_waitcnt vmcnt(8)
	v_mul_f32_e32 v27, 0x42000000, v57
	ds_write2_b32 v39, v2, v27 offset0:172 offset1:238
	s_waitcnt vmcnt(7)
	v_mul_f32_e32 v2, 0x42000000, v58
	s_waitcnt vmcnt(6)
	v_mul_f32_e32 v27, 0x42000000, v46
	ds_write2_b32 v40, v2, v27 offset0:48 offset1:114
	s_waitcnt vmcnt(5)
	v_mul_f32_e32 v2, 0x42000000, v47
	s_waitcnt vmcnt(4)
	v_mul_f32_e32 v27, 0x42000000, v48
	ds_write2_b32 v40, v2, v27 offset0:180 offset1:246
	s_waitcnt vmcnt(3)
	v_mul_f32_e32 v2, 0x42000000, v49
	s_waitcnt vmcnt(2)
	v_mul_f32_e32 v27, 0x42000000, v50
	ds_write2_b32 v41, v2, v27 offset0:56 offset1:122
	v_mov_b32_e32 v50, v3
	s_waitcnt vmcnt(1)
	v_mul_f32_e32 v2, 0x42000000, v44
	s_waitcnt vmcnt(0)
	v_mul_f32_e32 v27, 0x42000000, v42
	ds_write2_b32 v41, v2, v27 offset0:188 offset1:254
	s_waitcnt lgkmcnt(0)
	ds_read2_b32 v[42:43], v31 offset0:33 offset1:41
	ds_read2_b32 v[44:45], v31 offset0:66 offset1:74
	ds_read2_b32 v[46:47], v31 offset1:8
	ds_read2_b32 v[48:49], v31 offset0:99 offset1:107
	ds_read2_b32 v[52:53], v31 offset0:132 offset1:140
	ds_read2_b32 v[54:55], v31 offset0:165 offset1:173
	ds_read2_b32 v[56:57], v31 offset0:198 offset1:206
	ds_read2_b32 v[58:59], v31 offset0:231 offset1:239
	v_or_b32_e32 v2, s6, v30
	s_waitcnt lgkmcnt(5)
	v_cvt_pk_fp8_f32 v50, v46, v42
	v_mov_b32_e32 v42, v3
	s_waitcnt lgkmcnt(2)
	v_cvt_pk_fp8_f32 v51, v52, v54
	v_cvt_pk_fp8_f32 v42, v47, v43
	v_cvt_pk_fp8_f32 v50, v44, v48 op_sel:[0,0,1]
	v_mov_b32_e32 v43, v3
	s_waitcnt lgkmcnt(0)
	v_cvt_pk_fp8_f32 v51, v56, v58 op_sel:[0,0,1]
	v_cvt_pk_fp8_f32 v43, v53, v55
	v_lshlrev_b32_e32 v2, 9, v2
	v_lshl_add_u64 v[46:47], v[60:61], 0, v[2:3]
	global_store_dwordx2 v[46:47], v[50:51], off nt
	v_cvt_pk_fp8_f32 v42, v45, v49 op_sel:[0,0,1]
	v_cvt_pk_fp8_f32 v43, v57, v59 op_sel:[0,0,1]
	ds_read2_b32 v[44:45], v31 offset0:49 offset1:57
	ds_read2_b32 v[46:47], v31 offset0:82 offset1:90
	ds_read2_b32 v[48:49], v31 offset0:16 offset1:24
	ds_read2_b32 v[50:51], v31 offset0:115 offset1:123
	ds_read2_b32 v[54:55], v31 offset0:148 offset1:156
	ds_read2_b32 v[56:57], v31 offset0:181 offset1:189
	v_or_b32_e32 v2, s6, v32
	v_lshlrev_b32_e32 v2, 9, v2
	v_mov_b32_e32 v52, v3
	ds_read2_b32 v[58:59], v31 offset0:214 offset1:222
	ds_read2_b32 v[62:63], v31 offset0:247 offset1:255
	v_mov_b32_e32 v53, v3
	v_lshl_add_u64 v[64:65], v[60:61], 0, v[2:3]
	s_waitcnt lgkmcnt(5)
	v_cvt_pk_fp8_f32 v52, v48, v44
	s_waitcnt lgkmcnt(2)
	v_cvt_pk_fp8_f32 v53, v54, v56
	global_store_dwordx2 v[64:65], v[42:43], off nt
	v_mov_b32_e32 v42, v3
	v_mov_b32_e32 v43, v3
	v_cvt_pk_fp8_f32 v42, v49, v45
	v_cvt_pk_fp8_f32 v43, v55, v57
	v_cvt_pk_fp8_f32 v52, v46, v50 op_sel:[0,0,1]
	s_waitcnt lgkmcnt(0)
	v_cvt_pk_fp8_f32 v53, v58, v62 op_sel:[0,0,1]
	v_or_b32_e32 v2, s6, v33
	v_lshlrev_b32_e32 v2, 9, v2
	v_cvt_pk_fp8_f32 v42, v47, v51 op_sel:[0,0,1]
	v_cvt_pk_fp8_f32 v43, v59, v63 op_sel:[0,0,1]
	v_lshl_add_u64 v[44:45], v[60:61], 0, v[2:3]
	v_or_b32_e32 v2, s6, v34
	v_lshlrev_b32_e32 v2, 9, v2
	global_store_dwordx2 v[44:45], v[52:53], off nt
	v_lshl_add_u64 v[44:45], v[60:61], 0, v[2:3]
	global_store_dwordx2 v[44:45], v[42:43], off nt
	s_waitcnt lgkmcnt(0)

.LBB0_1513:
	s_andn2_b64 vcc, exec, s[4:5]
	s_cbranch_vccnz .LBB0_1494
	s_mul_hi_i32 s2, s14, 0x6e5478ad
	s_lshr_b32 s4, s2, 31
	s_ashr_i32 s2, s2, 8
	s_add_i32 s2, s2, s4
	s_mul_i32 s5, s2, 0xffffb5c0
	s_lshl_b32 s4, s2, 6
	s_add_i32 s6, s10, s5
	v_or_b32_e32 v2, s4, v28
	s_ashr_i32 s7, s6, 31
	v_lshl_add_u64 v[42:43], s[6:7], 2, v[22:23]
	v_or_b32_e32 v27, 2, v2
	v_mad_i64_i32 v[46:47], s[84:85], v27, s83, v[42:43]
	v_or_b32_e32 v27, 4, v2
	v_mad_i64_i32 v[48:49], s[84:85], v27, s83, v[42:43]
	v_or_b32_e32 v27, 6, v2
	v_mad_i64_i32 v[50:51], s[84:85], v27, s83, v[42:43]
	v_or_b32_e32 v27, 8, v2
	v_mad_i64_i32 v[52:53], s[84:85], v27, s83, v[42:43]
	v_or_b32_e32 v27, 10, v2
	v_mad_i64_i32 v[54:55], s[84:85], v27, s83, v[42:43]
	v_or_b32_e32 v27, 12, v2
	v_mad_i64_i32 v[44:45], s[84:85], v2, s83, v[42:43]
	v_mad_i64_i32 v[56:57], s[84:85], v27, s83, v[42:43]
	v_or_b32_e32 v27, 14, v2
	v_mad_i64_i32 v[58:59], s[84:85], v27, s83, v[42:43]
	global_load_dword v27, v[44:45], off nt
	global_load_dword v60, v[46:47], off nt
	global_load_dword v61, v[48:49], off nt
	global_load_dword v62, v[50:51], off nt
	global_load_dword v63, v[52:53], off nt
	global_load_dword v64, v[54:55], off nt
	global_load_dword v65, v[56:57], off nt
	global_load_dword v66, v[58:59], off nt
	v_or_b32_e32 v44, 16, v2
	v_mad_i64_i32 v[44:45], s[84:85], v44, s83, v[42:43]
	v_or_b32_e32 v46, 18, v2
	v_or_b32_e32 v48, 20, v2
	v_or_b32_e32 v50, 22, v2
	v_or_b32_e32 v52, 24, v2
	v_or_b32_e32 v54, 26, v2
	v_or_b32_e32 v56, 28, v2
	v_or_b32_e32 v58, 30, v2
	v_mad_i64_i32 v[46:47], s[84:85], v46, s83, v[42:43]
	v_mad_i64_i32 v[48:49], s[84:85], v48, s83, v[42:43]
	v_mad_i64_i32 v[50:51], s[84:85], v50, s83, v[42:43]
	v_mad_i64_i32 v[52:53], s[84:85], v52, s83, v[42:43]
	v_mad_i64_i32 v[54:55], s[84:85], v54, s83, v[42:43]
	v_mad_i64_i32 v[56:57], s[84:85], v56, s83, v[42:43]
	v_mad_i64_i32 v[58:59], s[84:85], v58, s83, v[42:43]
	global_load_dword v67, v[44:45], off nt
	global_load_dword v68, v[46:47], off nt
	global_load_dword v69, v[48:49], off nt
	global_load_dword v70, v[50:51], off nt
	global_load_dword v71, v[52:53], off nt
	global_load_dword v72, v[54:55], off nt
	global_load_dword v73, v[56:57], off nt
	global_load_dword v74, v[58:59], off nt
	v_or_b32_e32 v44, 32, v2
	v_or_b32_e32 v46, 34, v2
	v_or_b32_e32 v48, 36, v2
	v_or_b32_e32 v50, 38, v2
	v_or_b32_e32 v56, 44, v2
	v_mad_i64_i32 v[44:45], s[84:85], v44, s83, v[42:43]
	v_mad_i64_i32 v[46:47], s[84:85], v46, s83, v[42:43]
	v_mad_i64_i32 v[48:49], s[84:85], v48, s83, v[42:43]
	v_mad_i64_i32 v[50:51], s[84:85], v50, s83, v[42:43]
	v_or_b32_e32 v52, 40, v2
	v_or_b32_e32 v54, 42, v2
	v_mad_i64_i32 v[56:57], s[84:85], v56, s83, v[42:43]
	v_or_b32_e32 v58, 46, v2
	v_mad_i64_i32 v[52:53], s[84:85], v52, s83, v[42:43]
	v_mad_i64_i32 v[54:55], s[84:85], v54, s83, v[42:43]
	v_mad_i64_i32 v[58:59], s[84:85], v58, s83, v[42:43]
	global_load_dword v75, v[44:45], off nt
	global_load_dword v76, v[46:47], off nt
	global_load_dword v77, v[48:49], off nt
	global_load_dword v78, v[50:51], off nt
	global_load_dword v79, v[52:53], off nt
	global_load_dword v80, v[54:55], off nt
	s_nop 0
	global_load_dword v56, v[56:57], off nt
	s_nop 0
	global_load_dword v57, v[58:59], off nt
	v_or_b32_e32 v44, 48, v2
	v_or_b32_e32 v46, 50, v2
	v_or_b32_e32 v48, 52, v2
	v_or_b32_e32 v50, 54, v2
	v_mad_i64_i32 v[44:45], s[84:85], v44, s83, v[42:43]
	v_mad_i64_i32 v[46:47], s[84:85], v46, s83, v[42:43]
	v_mad_i64_i32 v[48:49], s[84:85], v48, s83, v[42:43]
	v_mad_i64_i32 v[50:51], s[84:85], v50, s83, v[42:43]
	v_or_b32_e32 v52, 56, v2
	v_or_b32_e32 v54, 58, v2
	v_mad_i64_i32 v[52:53], s[84:85], v52, s83, v[42:43]
	v_mad_i64_i32 v[54:55], s[84:85], v54, s83, v[42:43]
	global_load_dword v58, v[44:45], off nt
	s_nop 0
	global_load_dword v46, v[46:47], off nt
	s_nop 0
	global_load_dword v47, v[48:49], off nt
	s_nop 0
	global_load_dword v48, v[50:51], off nt
	global_load_dword v49, v[52:53], off nt
	s_nop 0
	global_load_dword v50, v[54:55], off nt
	v_or_b32_e32 v44, 60, v2
	v_or_b32_e32 v2, 62, v2
	v_mad_i64_i32 v[44:45], s[84:85], v44, s83, v[42:43]
	v_mad_i64_i32 v[42:43], s[84:85], v2, s83, v[42:43]
	global_load_dword v2, v[44:45], off nt
	s_nop 0
	global_load_dword v42, v[42:43], off nt
	s_waitcnt vmcnt(31)
	v_mul_f32_e32 v27, 0x42800000, v27
	s_waitcnt vmcnt(30)
	v_mul_f32_e32 v43, 0x42800000, v60
	ds_write2_b32 v29, v27, v43 offset1:66
	s_waitcnt vmcnt(29)
	v_mul_f32_e32 v27, 0x42800000, v61
	s_waitcnt vmcnt(28)
	v_mul_f32_e32 v43, 0x42800000, v62
	ds_write2_b32 v29, v27, v43 offset0:132 offset1:198
	s_waitcnt vmcnt(27)
	v_mul_f32_e32 v27, 0x42800000, v63
	s_waitcnt vmcnt(26)
	v_mul_f32_e32 v43, 0x42800000, v64
	ds_write2_b32 v35, v27, v43 offset0:8 offset1:74
	s_waitcnt vmcnt(25)
	v_mul_f32_e32 v27, 0x42800000, v65
	s_waitcnt vmcnt(24)
	v_mul_f32_e32 v43, 0x42800000, v66
	ds_write2_b32 v35, v27, v43 offset0:140 offset1:206
	s_lshl_b32 s2, s2, 1
	s_sub_i32 s2, s14, s2
	v_mov_b32_e32 v51, 0
	s_and_b32 s5, s18, 4
	s_bfe_u32 s2, s2, 0x20001
	s_or_b32 s2, s5, s2
	s_lshl_b32 s2, s2, 5
	s_and_b32 s5, s6, 0xffffff00
	s_or_b32 s2, s2, s5
	s_waitcnt vmcnt(23)
	v_mul_f32_e32 v27, 0x42800000, v67
	s_waitcnt vmcnt(22)
	v_mul_f32_e32 v43, 0x42800000, v68
	ds_write2_b32 v36, v27, v43 offset0:16 offset1:82
	s_waitcnt vmcnt(21)
	v_mul_f32_e32 v27, 0x42800000, v69
	s_waitcnt vmcnt(20)
	v_mul_f32_e32 v43, 0x42800000, v70
	ds_write2_b32 v36, v27, v43 offset0:148 offset1:214
	s_waitcnt vmcnt(19)
	v_mul_f32_e32 v27, 0x42800000, v71
	s_waitcnt vmcnt(18)
	v_mul_f32_e32 v43, 0x42800000, v72
	ds_write2_b32 v37, v27, v43 offset0:24 offset1:90
	s_waitcnt vmcnt(17)
	v_mul_f32_e32 v27, 0x42800000, v73
	s_waitcnt vmcnt(16)
	v_mul_f32_e32 v43, 0x42800000, v74
	ds_write2_b32 v37, v27, v43 offset0:156 offset1:222
	v_or_b32_e32 v62, s2, v30
	s_ashr_i32 s5, s4, 31
	v_ashrrev_i32_e32 v63, 31, v62
	v_lshl_add_u64 v[60:61], v[24:25], 0, s[4:5]
	v_lshlrev_b64 v[62:63], 11, v[62:63]
	s_waitcnt vmcnt(15)
	v_mul_f32_e32 v27, 0x42800000, v75
	s_waitcnt vmcnt(14)
	v_mul_f32_e32 v43, 0x42800000, v76
	ds_write2_b32 v38, v27, v43 offset0:32 offset1:98
	s_waitcnt vmcnt(13)
	v_mul_f32_e32 v27, 0x42800000, v77
	s_waitcnt vmcnt(12)
	v_mul_f32_e32 v43, 0x42800000, v78
	ds_write2_b32 v38, v27, v43 offset0:164 offset1:230
	s_waitcnt vmcnt(11)
	v_mul_f32_e32 v27, 0x42800000, v79
	s_waitcnt vmcnt(10)
	v_mul_f32_e32 v43, 0x42800000, v80
	ds_write2_b32 v39, v27, v43 offset0:40 offset1:106
	s_waitcnt vmcnt(9)
	v_mul_f32_e32 v27, 0x42800000, v56
	s_waitcnt vmcnt(8)
	v_mul_f32_e32 v43, 0x42800000, v57
	ds_write2_b32 v39, v27, v43 offset0:172 offset1:238
	s_waitcnt vmcnt(7)
	v_mul_f32_e32 v27, 0x42800000, v58
	s_waitcnt vmcnt(6)
	v_mul_f32_e32 v43, 0x42800000, v46
	ds_write2_b32 v40, v27, v43 offset0:48 offset1:114
	s_waitcnt vmcnt(5)
	v_mul_f32_e32 v27, 0x42800000, v47
	s_waitcnt vmcnt(4)
	v_mul_f32_e32 v43, 0x42800000, v48
	ds_write2_b32 v40, v27, v43 offset0:180 offset1:246
	s_waitcnt vmcnt(3)
	v_mul_f32_e32 v27, 0x42800000, v49
	s_waitcnt vmcnt(2)
	v_mul_f32_e32 v43, 0x42800000, v50
	ds_write2_b32 v41, v27, v43 offset0:56 offset1:122
	v_mov_b32_e32 v50, 0
	s_waitcnt vmcnt(1)
	v_mul_f32_e32 v2, 0x42800000, v2
	s_waitcnt vmcnt(0)
	v_mul_f32_e32 v27, 0x42800000, v42
	ds_write2_b32 v41, v2, v27 offset0:188 offset1:254
	s_waitcnt lgkmcnt(0)
	ds_read2_b32 v[42:43], v31 offset0:33 offset1:41
	ds_read2_b32 v[44:45], v31 offset0:66 offset1:74
	ds_read2_b32 v[46:47], v31 offset1:8
	ds_read2_b32 v[48:49], v31 offset0:99 offset1:107
	ds_read2_b32 v[52:53], v31 offset0:132 offset1:140
	ds_read2_b32 v[54:55], v31 offset0:165 offset1:173
	ds_read2_b32 v[56:57], v31 offset0:198 offset1:206
	ds_read2_b32 v[58:59], v31 offset0:231 offset1:239
	s_waitcnt lgkmcnt(5)
	v_cvt_pk_fp8_f32 v50, v46, v42
	v_mov_b32_e32 v42, 0
	s_waitcnt lgkmcnt(2)
	v_cvt_pk_fp8_f32 v51, v52, v54
	v_cvt_pk_fp8_f32 v42, v47, v43
	v_cvt_pk_fp8_f32 v50, v44, v48 op_sel:[0,0,1]
	v_mov_b32_e32 v43, 0
	s_waitcnt lgkmcnt(0)
	v_cvt_pk_fp8_f32 v51, v56, v58 op_sel:[0,0,1]
	v_cvt_pk_fp8_f32 v43, v53, v55
	v_lshl_add_u64 v[46:47], v[60:61], 0, v[62:63]
	v_cvt_pk_fp8_f32 v42, v45, v49 op_sel:[0,0,1]
	global_store_dwordx2 v[46:47], v[50:51], off nt
	v_cvt_pk_fp8_f32 v43, v57, v59 op_sel:[0,0,1]
	ds_read2_b32 v[46:47], v31 offset0:49 offset1:57
	ds_read2_b32 v[48:49], v31 offset0:82 offset1:90
	ds_read2_b32 v[50:51], v31 offset0:16 offset1:24
	ds_read2_b32 v[52:53], v31 offset0:115 offset1:123
	ds_read2_b32 v[56:57], v31 offset0:148 offset1:156
	ds_read2_b32 v[58:59], v31 offset0:181 offset1:189
	v_or_b32_e32 v44, s2, v32
	v_mov_b32_e32 v54, 0
	ds_read2_b32 v[62:63], v31 offset0:214 offset1:222
	ds_read2_b32 v[64:65], v31 offset0:247 offset1:255
	v_mov_b32_e32 v55, 0
	v_ashrrev_i32_e32 v45, 31, v44
	s_waitcnt lgkmcnt(5)
	v_cvt_pk_fp8_f32 v54, v50, v46
	s_waitcnt lgkmcnt(2)
	v_cvt_pk_fp8_f32 v55, v56, v58
	v_lshlrev_b64 v[44:45], 11, v[44:45]
	v_lshl_add_u64 v[44:45], v[60:61], 0, v[44:45]
	global_store_dwordx2 v[44:45], v[42:43], off nt
	v_mov_b32_e32 v44, 0
	v_mov_b32_e32 v45, 0
	v_cvt_pk_fp8_f32 v54, v48, v52 op_sel:[0,0,1]
	s_waitcnt lgkmcnt(0)
	v_cvt_pk_fp8_f32 v55, v62, v64 op_sel:[0,0,1]
	v_or_b32_e32 v42, s2, v33
	v_cvt_pk_fp8_f32 v44, v51, v47
	v_cvt_pk_fp8_f32 v45, v57, v59
	v_ashrrev_i32_e32 v43, 31, v42
	v_lshlrev_b64 v[42:43], 11, v[42:43]
	v_lshl_add_u64 v[42:43], v[60:61], 0, v[42:43]
	global_store_dwordx2 v[42:43], v[54:55], off nt
	v_cvt_pk_fp8_f32 v44, v49, v53 op_sel:[0,0,1]
	v_cvt_pk_fp8_f32 v45, v63, v65 op_sel:[0,0,1]
	v_or_b32_e32 v42, s2, v34
	v_ashrrev_i32_e32 v43, 31, v42
	v_lshlrev_b64 v[42:43], 11, v[42:43]
	v_lshl_add_u64 v[42:43], v[60:61], 0, v[42:43]
	global_store_dwordx2 v[42:43], v[44:45], off nt
	s_waitcnt lgkmcnt(0)
	s_branch .LBB0_1494
.LBB0_1515:
	s_cmp_eq_u32 s101, 3
	s_cbranch_scc1 .Lret_c8
	s_cmp_eq_u32 s101, 4
	s_cbranch_scc1 .Lret_c10
	s_cmp_eq_u32 s101, 5
	s_cbranch_scc1 .Lret_c12
	v_lshl_add_u32 v1, s13, 9, v1
	s_movk_i32 s2, 0x6000
	v_cmp_gt_i32_e32 vcc, s2, v1
	s_and_saveexec_b64 s[2:3], vcc
	s_cbranch_execz .LBB0_1518
	s_add_u32 s0, s0, 0x3500000
	v_mov_b32_e32 v2, 0
	s_addc_u32 s1, s1, 0
	s_lshl_b32 s6, s12, 9
	s_mov_b64 s[4:5], 0
	v_mov_b32_e32 v3, v2
	v_mov_b32_e32 v4, v2
	v_mov_b32_e32 v5, v2
	s_movk_i32 s7, 0x5fff

	.amdhsa_kernel _Z10fwd_kernel4Args
		.amdhsa_group_segment_fixed_size 0
		.amdhsa_private_segment_fixed_size 0
		.amdhsa_kernarg_size 448
		.amdhsa_user_sgpr_count 2
		.amdhsa_user_sgpr_dispatch_ptr 0
		.amdhsa_user_sgpr_queue_ptr 0
		.amdhsa_user_sgpr_kernarg_segment_ptr 1
		.amdhsa_user_sgpr_dispatch_id 0
		.amdhsa_user_sgpr_kernarg_preload_length 0
		.amdhsa_user_sgpr_kernarg_preload_offset 0
		.amdhsa_user_sgpr_private_segment_size 0
		.amdhsa_uses_dynamic_stack 0
		.amdhsa_enable_private_segment 0
		.amdhsa_system_sgpr_workgroup_id_x 1
		.amdhsa_system_sgpr_workgroup_id_y 0
		.amdhsa_system_sgpr_workgroup_id_z 0
		.amdhsa_system_sgpr_workgroup_info 0
		.amdhsa_system_vgpr_workitem_id 0
		.amdhsa_next_free_vgpr 253
		.amdhsa_next_free_sgpr 102
		.amdhsa_accum_offset 256
		.amdhsa_reserve_vcc 1
		.amdhsa_float_round_mode_32 0
		.amdhsa_float_round_mode_16_64 0
		.amdhsa_float_denorm_mode_32 3
		.amdhsa_float_denorm_mode_16_64 3
		.amdhsa_dx10_clamp 1
		.amdhsa_ieee_mode 1
		.amdhsa_fp16_overflow 0
		.amdhsa_tg_split 0
		.amdhsa_exception_fp_ieee_invalid_op 0
		.amdhsa_exception_fp_denorm_src 0
		.amdhsa_exception_fp_ieee_div_zero 0
		.amdhsa_exception_fp_ieee_overflow 0
		.amdhsa_exception_fp_ieee_underflow 0
		.amdhsa_exception_fp_ieee_inexact 0
		.amdhsa_exception_int_div_zero 0
	.end_amdhsa_kernel

amdhsa.kernels:
  - .agpr_count:     0
    .args:
      - .offset:         0
        .size:           192
        .value_kind:     by_value
      - .offset:         192
        .size:           4
        .value_kind:     hidden_block_count_x
      - .offset:         196
        .size:           4
        .value_kind:     hidden_block_count_y
      - .offset:         200
        .size:           4
        .value_kind:     hidden_block_count_z
      - .offset:         204
        .size:           2
        .value_kind:     hidden_group_size_x
      - .offset:         206
        .size:           2
        .value_kind:     hidden_group_size_y
      - .offset:         208
        .size:           2
        .value_kind:     hidden_group_size_z
      - .offset:         210
        .size:           2
        .value_kind:     hidden_remainder_x
      - .offset:         212
        .size:           2
        .value_kind:     hidden_remainder_y
      - .offset:         214
        .size:           2
        .value_kind:     hidden_remainder_z
      - .offset:         232
        .size:           8
        .value_kind:     hidden_global_offset_x
      - .offset:         240
        .size:           8
        .value_kind:     hidden_global_offset_y
      - .offset:         248
        .size:           8
        .value_kind:     hidden_global_offset_z
      - .offset:         256
        .size:           2
        .value_kind:     hidden_grid_dims
      - .offset:         312
        .size:           4
        .value_kind:     hidden_dynamic_lds_size
    .group_segment_fixed_size: 0
    .kernarg_segment_align: 8
    .kernarg_segment_size: 448
    .language:       OpenCL C
    .language_version:
      - 2
      - 0
    .max_flat_workgroup_size: 512
    .name:           _Z10fwd_kernel4Args
    .private_segment_fixed_size: 0
    .sgpr_count:     108
    .sgpr_spill_count: 54
    .symbol:         _Z10fwd_kernel4Args.kd
    .uniform_work_group_size: 1
    .uses_dynamic_stack: false
    .vgpr_count:     253
    .vgpr_spill_count: 0
    .wavefront_size: 64
